# GEMM loops: redundant lgkmcnt(0) after each phase barrier removed; s_setprio 1 moved before and s_setprio 0 after the phase barriers (on top of v9b)
# speedup vs baseline: 1.0061x; 1.0013x over previous
; #define PG8_STAGE(bufoff, gbase, voff) do { _Pragma("unroll") for (int _i = 0; _i < 2; ++_i) \
;         __builtin_amdgcn_global_load_lds((const unsigned*)((const char*)(gbase) + (voff)[_i]), (LAS unsigned*)(lds + (bufoff) + ldsw + _i * 8192), 16, 0, 0); } while (0)
; #define PG8_LDA(dst, b, h) do { _Pragma("unroll") for (int m = 0; m < 4; ++m) _Pragma("unroll") for (int k = 0; k < 2; ++k) dst[m][k] = *(const LAS bf16x8*)(lds + PG8_SA(b, h) + aoff + m * 2048 + k * 1024); } while (0)
; #define PG8_LDB(dst, b, h) do { _Pragma("unroll") for (int n = 0; n < 2; ++n) _Pragma("unroll") for (int k = 0; k < 2; ++k) dst[n][k] = *(const LAS bf16x8*)(lds + PG8_SB(b, h) + boff + n * 2048 + k * 1024); } while (0)
; #define PG8_MMA(ai, bj, At, Bt) do { __builtin_amdgcn_s_setprio(1); _Pragma("unroll") for (int m = 0; m < 4; ++m) _Pragma("unroll") for (int n = 0; n < 2; ++n) _Pragma("unroll") for (int k = 0; k < 2; ++k) \
;         acc[ai][bj][m][n] = __builtin_amdgcn_mfma_f32_16x16x32_bf16(Bt[n][k], At[m][k], acc[ai][bj][m][n], 0, 0, 0); __builtin_amdgcn_s_setprio(0); } while (0)
; #define PG8_WAIT_V(n) asm volatile("s_waitcnt vmcnt(" #n ")" ::: "memory")
; #define PG8_WAIT_L(n) asm volatile("s_waitcnt lgkmcnt(" #n ")" ::: "memory")
; #define PG8_BAR __builtin_amdgcn_s_barrier()
; #define PG8_SCHED __builtin_amdgcn_sched_barrier(0)
; template <class Epi, bool ALIGN_EPI>
; __device__ __forceinline__ void gemm_phase(LAS unsigned char* lds, const Gemm g, const StaticOrder& S, const Epi& E) {
;     ...
;             PG8_LDB(B0, 0, 0); PG8_LDB(B1, 0, 1); PG8_SCHED; PG8_LDA(At, 0, 0); PG8_STAGE(PG8_SA(1, 1), a1 + hstepA, voffA);
;             PG8_WAIT_V(8); PG8_WAIT_L(0); PG8_BAR; PG8_MMA(0, 0, At, B0); PG8_MMA(0, 1, At, B1); PG8_BAR; PG8_SCHED;
;             PG8_LDA(At, 0, 1); PG8_STAGE(PG8_SB(0, 0), b2, voffB); PG8_STAGE(PG8_SB(0, 1), b2 + hstepB, voffB); PG8_STAGE(PG8_SA(0, 0), a2, voffA);
;             PG8_WAIT_V(8); PG8_WAIT_L(0); PG8_BAR; PG8_MMA(1, 0, At, B0); PG8_MMA(1, 1, At, B1); PG8_BAR; PG8_SCHED;
.LBB0_121:
	ds_read_b128 v[144:147], v152
	ds_read_b128 v[156:159], v152 offset:1024
	ds_read_b128 v[160:163], v152 offset:2048
	ds_read_b128 v[168:171], v152 offset:3072
	ds_read_b128 v[172:175], v153
	ds_read_b128 v[176:179], v153 offset:1024
	ds_read_b128 v[180:183], v153 offset:2048
	ds_read_b128 v[184:187], v153 offset:3072
	s_add_u32 s26, s24, 0xfff80080
	s_addc_u32 s27, s25, -1
	s_cmp_eq_u32 s55, 28
	s_cselect_b32 s29, s17, s27
	s_cselect_b32 s28, s51, s26
	s_cselect_b32 s27, s15, s54
	s_cselect_b32 s26, s52, s53
	v_lshl_add_u64 v[164:165], s[24:25], 0, v[138:139]
	s_add_i32 m0, s23, 0xc000
	ds_read_b128 v[188:191], v154
	ds_read_b128 v[192:195], v154 offset:1024
	ds_read_b128 v[196:199], v154 offset:2048
	ds_read_b128 v[200:203], v154 offset:3072
	ds_read_b128 v[204:207], v154 offset:4096
	ds_read_b128 v[208:211], v154 offset:5120
	ds_read_b128 v[212:215], v154 offset:6144
	ds_read_b128 v[216:219], v154 offset:7168
	global_load_lds_dwordx4 v[164:165], off
	v_lshl_add_u64 v[164:165], s[24:25], 0, v[136:137]
	s_add_i32 m0, s23, 0xe000
	s_nop 0
	global_load_lds_dwordx4 v[164:165], off
	s_waitcnt vmcnt(8)
	s_waitcnt lgkmcnt(0)
	s_setprio 1
	s_barrier
	v_mfma_f32_16x16x32_bf16 v[124:127], v[144:147], v[188:191], v[124:127]
	v_mfma_f32_16x16x32_bf16 v[120:123], v[160:163], v[188:191], v[120:123]
	v_mfma_f32_16x16x32_bf16 v[108:111], v[144:147], v[196:199], v[108:111]
	v_mfma_f32_16x16x32_bf16 v[104:107], v[160:163], v[196:199], v[104:107]
	v_mfma_f32_16x16x32_bf16 v[92:95], v[144:147], v[204:207], v[92:95]
	v_mfma_f32_16x16x32_bf16 v[88:91], v[160:163], v[204:207], v[88:91]
	v_mfma_f32_16x16x32_bf16 v[76:79], v[144:147], v[212:215], v[76:79]
	v_mfma_f32_16x16x32_bf16 v[72:75], v[160:163], v[212:215], v[72:75]
	v_mfma_f32_16x16x32_bf16 v[124:127], v[156:159], v[192:195], v[124:127]
	v_mfma_f32_16x16x32_bf16 v[120:123], v[168:171], v[192:195], v[120:123]
	v_mfma_f32_16x16x32_bf16 v[108:111], v[156:159], v[200:203], v[108:111]
	v_mfma_f32_16x16x32_bf16 v[104:107], v[168:171], v[200:203], v[104:107]
	v_mfma_f32_16x16x32_bf16 v[92:95], v[156:159], v[208:211], v[92:95]
	v_mfma_f32_16x16x32_bf16 v[88:91], v[168:171], v[208:211], v[88:91]
	v_mfma_f32_16x16x32_bf16 v[76:79], v[156:159], v[216:219], v[76:79]
	v_mfma_f32_16x16x32_bf16 v[72:75], v[168:171], v[216:219], v[72:75]
	s_setprio 0
	s_setprio 1
	v_mfma_f32_16x16x32_bf16 v[116:119], v[172:175], v[188:191], v[116:119]
	v_mfma_f32_16x16x32_bf16 v[112:115], v[180:183], v[188:191], v[112:115]
	v_mfma_f32_16x16x32_bf16 v[100:103], v[172:175], v[196:199], v[100:103]
	v_mfma_f32_16x16x32_bf16 v[96:99], v[180:183], v[196:199], v[96:99]
	v_mfma_f32_16x16x32_bf16 v[84:87], v[172:175], v[204:207], v[84:87]
	v_mfma_f32_16x16x32_bf16 v[80:83], v[180:183], v[204:207], v[80:83]
	v_mfma_f32_16x16x32_bf16 v[68:71], v[172:175], v[212:215], v[68:71]
	v_mfma_f32_16x16x32_bf16 v[64:67], v[180:183], v[212:215], v[64:67]
	v_mfma_f32_16x16x32_bf16 v[116:119], v[176:179], v[192:195], v[116:119]
	v_mfma_f32_16x16x32_bf16 v[112:115], v[184:187], v[192:195], v[112:115]
	v_mfma_f32_16x16x32_bf16 v[100:103], v[176:179], v[200:203], v[100:103]
	v_mfma_f32_16x16x32_bf16 v[96:99], v[184:187], v[200:203], v[96:99]
	v_mfma_f32_16x16x32_bf16 v[84:87], v[176:179], v[208:211], v[84:87]
	v_mfma_f32_16x16x32_bf16 v[80:83], v[184:187], v[208:211], v[80:83]
	v_mfma_f32_16x16x32_bf16 v[68:71], v[176:179], v[216:219], v[68:71]
	v_mfma_f32_16x16x32_bf16 v[64:67], v[184:187], v[216:219], v[64:67]
	s_barrier
	s_setprio 0
	s_add_i32 s56, s46, s35
	v_lshl_add_u64 v[164:165], s[26:27], 0, v[132:133]
	s_mov_b32 m0, s56
	ds_read_b128 v[188:191], v154 offset:16384
	ds_read_b128 v[192:195], v154 offset:17408
	ds_read_b128 v[196:199], v154 offset:18432
	ds_read_b128 v[200:203], v154 offset:19456
	ds_read_b128 v[204:207], v154 offset:20480
	ds_read_b128 v[208:211], v154 offset:21504
	ds_read_b128 v[212:215], v154 offset:22528
	ds_read_b128 v[216:219], v154 offset:23552
	global_load_lds_dwordx4 v[164:165], off
	s_add_i32 m0, s56, 0x2000
	s_add_u32 s56, s26, 0x80000
	v_lshl_add_u64 v[220:221], s[26:27], 0, v[128:129]
	s_addc_u32 s57, s27, 0
	s_add_i32 s58, s47, s35
	global_load_lds_dwordx4 v[220:221], off
	v_lshl_add_u64 v[222:223], s[56:57], 0, v[132:133]
	s_mov_b32 m0, s58
	v_lshl_add_u64 v[224:225], s[28:29], 0, v[130:131]
	global_load_lds_dwordx4 v[222:223], off
	v_lshl_add_u64 v[222:223], s[56:57], 0, v[128:129]
	s_add_i32 m0, s58, 0x2000
	s_nop 0
	global_load_lds_dwordx4 v[222:223], off
	v_lshl_add_u64 v[222:223], s[28:29], 0, v[134:135]
	s_mov_b32 m0, s23
	s_nop 0
	global_load_lds_dwordx4 v[222:223], off
	s_mov_b32 m0, s38
	s_nop 0
	global_load_lds_dwordx4 v[224:225], off
	s_waitcnt vmcnt(8)
	s_waitcnt lgkmcnt(0)
	s_setprio 1
	s_barrier
; #define PG8_STAGE(bufoff, gbase, voff) do { _Pragma("unroll") for (int _i = 0; _i < 2; ++_i) \
;         __builtin_amdgcn_global_load_lds((const unsigned*)((const char*)(gbase) + (voff)[_i]), (LAS unsigned*)(lds + (bufoff) + ldsw + _i * 8192), 16, 0, 0); } while (0)
; #define PG8_LDA(dst, b, h) do { _Pragma("unroll") for (int m = 0; m < 4; ++m) _Pragma("unroll") for (int k = 0; k < 2; ++k) dst[m][k] = *(const LAS bf16x8*)(lds + PG8_SA(b, h) + aoff + m * 2048 + k * 1024); } while (0)
; #define PG8_LDB(dst, b, h) do { _Pragma("unroll") for (int n = 0; n < 2; ++n) _Pragma("unroll") for (int k = 0; k < 2; ++k) dst[n][k] = *(const LAS bf16x8*)(lds + PG8_SB(b, h) + boff + n * 2048 + k * 1024); } while (0)
; #define PG8_MMA(ai, bj, At, Bt) do { __builtin_amdgcn_s_setprio(1); _Pragma("unroll") for (int m = 0; m < 4; ++m) _Pragma("unroll") for (int n = 0; n < 2; ++n) _Pragma("unroll") for (int k = 0; k < 2; ++k) \
;         acc[ai][bj][m][n] = __builtin_amdgcn_mfma_f32_16x16x32_bf16(Bt[n][k], At[m][k], acc[ai][bj][m][n], 0, 0, 0); __builtin_amdgcn_s_setprio(0); } while (0)
; #define PG8_WAIT_V(n) asm volatile("s_waitcnt vmcnt(" #n ")" ::: "memory")
; #define PG8_WAIT_L(n) asm volatile("s_waitcnt lgkmcnt(" #n ")" ::: "memory")
; #define PG8_BAR __builtin_amdgcn_s_barrier()
; #define PG8_SCHED __builtin_amdgcn_sched_barrier(0)
; template <class Epi, bool ALIGN_EPI>
; __device__ __forceinline__ void gemm_phase(LAS unsigned char* lds, const Gemm g, const StaticOrder& S, const Epi& E) {
;     ...
;             PG8_LDA(At, 0, 1); PG8_STAGE(PG8_SB(0, 0), b2, voffB); PG8_STAGE(PG8_SB(0, 1), b2 + hstepB, voffB); PG8_STAGE(PG8_SA(0, 0), a2, voffA);
;             PG8_WAIT_V(8); PG8_WAIT_L(0); PG8_BAR; PG8_MMA(1, 0, At, B0); PG8_MMA(1, 1, At, B1); PG8_BAR; PG8_SCHED;
;             PG8_LDB(B0, 1, 0); PG8_LDB(B1, 1, 1); PG8_SCHED; PG8_LDA(At, 1, 0); PG8_STAGE(PG8_SA(0, 1), a2 + hstepA, voffA);
;             PG8_WAIT_V(8); PG8_WAIT_L(0); PG8_BAR; PG8_MMA(0, 0, At, B0); PG8_MMA(0, 1, At, B1); PG8_BAR; PG8_SCHED;
;             PG8_LDA(At, 1, 1); PG8_STAGE(PG8_SB(1, 0), b3, voffB); PG8_STAGE(PG8_SB(1, 1), b3 + hstepB, voffB); PG8_STAGE(PG8_SA(1, 0), a3, voffA);
;             PG8_WAIT_V(8); PG8_WAIT_L(0); PG8_BAR; PG8_MMA(1, 0, At, B0); PG8_MMA(1, 1, At, B1); PG8_BAR; PG8_SCHED;
	v_mfma_f32_16x16x32_bf16 v[60:63], v[144:147], v[188:191], v[60:63]
	v_mfma_f32_16x16x32_bf16 v[56:59], v[160:163], v[188:191], v[56:59]
	v_mfma_f32_16x16x32_bf16 v[44:47], v[144:147], v[196:199], v[44:47]
	v_mfma_f32_16x16x32_bf16 v[40:43], v[160:163], v[196:199], v[40:43]
	v_mfma_f32_16x16x32_bf16 v[28:31], v[144:147], v[204:207], v[28:31]
	v_mfma_f32_16x16x32_bf16 v[24:27], v[160:163], v[204:207], v[24:27]
	v_mfma_f32_16x16x32_bf16 v[12:15], v[144:147], v[212:215], v[12:15]
	v_mfma_f32_16x16x32_bf16 v[8:11], v[160:163], v[212:215], v[8:11]
	v_mfma_f32_16x16x32_bf16 v[60:63], v[156:159], v[192:195], v[60:63]
	v_mfma_f32_16x16x32_bf16 v[56:59], v[168:171], v[192:195], v[56:59]
	v_mfma_f32_16x16x32_bf16 v[44:47], v[156:159], v[200:203], v[44:47]
	v_mfma_f32_16x16x32_bf16 v[40:43], v[168:171], v[200:203], v[40:43]
	v_mfma_f32_16x16x32_bf16 v[28:31], v[156:159], v[208:211], v[28:31]
	v_mfma_f32_16x16x32_bf16 v[24:27], v[168:171], v[208:211], v[24:27]
	v_mfma_f32_16x16x32_bf16 v[12:15], v[156:159], v[216:219], v[12:15]
	v_mfma_f32_16x16x32_bf16 v[8:11], v[168:171], v[216:219], v[8:11]
	s_setprio 0
	s_setprio 1
	v_mfma_f32_16x16x32_bf16 v[52:55], v[172:175], v[188:191], v[52:55]
	v_mfma_f32_16x16x32_bf16 v[48:51], v[180:183], v[188:191], v[48:51]
	v_mfma_f32_16x16x32_bf16 v[36:39], v[172:175], v[196:199], v[36:39]
	v_mfma_f32_16x16x32_bf16 v[32:35], v[180:183], v[196:199], v[32:35]
	v_mfma_f32_16x16x32_bf16 v[20:23], v[172:175], v[204:207], v[20:23]
	v_mfma_f32_16x16x32_bf16 v[16:19], v[180:183], v[204:207], v[16:19]
	v_mfma_f32_16x16x32_bf16 v[4:7], v[172:175], v[212:215], v[4:7]
	v_mfma_f32_16x16x32_bf16 v[0:3], v[180:183], v[212:215], v[0:3]
	v_mfma_f32_16x16x32_bf16 v[52:55], v[176:179], v[192:195], v[52:55]
	v_mfma_f32_16x16x32_bf16 v[48:51], v[184:187], v[192:195], v[48:51]
	v_mfma_f32_16x16x32_bf16 v[36:39], v[176:179], v[200:203], v[36:39]
	v_mfma_f32_16x16x32_bf16 v[32:35], v[184:187], v[200:203], v[32:35]
	v_mfma_f32_16x16x32_bf16 v[20:23], v[176:179], v[208:211], v[20:23]
	v_mfma_f32_16x16x32_bf16 v[16:19], v[184:187], v[208:211], v[16:19]
	v_mfma_f32_16x16x32_bf16 v[4:7], v[176:179], v[216:219], v[4:7]
	v_mfma_f32_16x16x32_bf16 v[0:3], v[184:187], v[216:219], v[0:3]
	s_barrier
	s_setprio 0
	s_add_i32 s56, 0, 0x18000
	v_add_u32_e32 v155, s56, v150
	s_add_i32 s57, 0, 0x1c000
	ds_read_b128 v[144:147], v155
	ds_read_b128 v[156:159], v155 offset:1024
	ds_read_b128 v[160:163], v155 offset:2048
	ds_read_b128 v[168:171], v155 offset:3072
	v_add_u32_e32 v155, s57, v150
	ds_read_b128 v[172:175], v155
	ds_read_b128 v[176:179], v155 offset:1024
	ds_read_b128 v[180:183], v155 offset:2048
	ds_read_b128 v[184:187], v155 offset:3072
	s_add_u32 s28, s28, 0x80000
	s_addc_u32 s29, s29, 0
	s_mov_b32 m0, s39
	v_lshl_add_u64 v[226:227], s[28:29], 0, v[134:135]
	ds_read_b128 v[188:191], v154 offset:32768
	ds_read_b128 v[192:195], v154 offset:33792
	ds_read_b128 v[196:199], v154 offset:34816
	ds_read_b128 v[200:203], v154 offset:35840
	ds_read_b128 v[204:207], v154 offset:36864
	ds_read_b128 v[208:211], v154 offset:37888
	ds_read_b128 v[212:215], v154 offset:38912
	ds_read_b128 v[216:219], v154 offset:39936
	global_load_lds_dwordx4 v[226:227], off
	v_lshl_add_u64 v[226:227], s[28:29], 0, v[130:131]
	s_mov_b32 m0, s40
	s_nop 0
	global_load_lds_dwordx4 v[226:227], off
	s_waitcnt vmcnt(8)
	s_waitcnt lgkmcnt(0)
	s_setprio 1
	s_barrier
	v_mfma_f32_16x16x32_bf16 v[124:127], v[144:147], v[188:191], v[124:127]
	v_mfma_f32_16x16x32_bf16 v[120:123], v[160:163], v[188:191], v[120:123]
	v_mfma_f32_16x16x32_bf16 v[108:111], v[144:147], v[196:199], v[108:111]
	v_mfma_f32_16x16x32_bf16 v[104:107], v[160:163], v[196:199], v[104:107]
	v_mfma_f32_16x16x32_bf16 v[92:95], v[144:147], v[204:207], v[92:95]
	v_mfma_f32_16x16x32_bf16 v[88:91], v[160:163], v[204:207], v[88:91]
	v_mfma_f32_16x16x32_bf16 v[76:79], v[144:147], v[212:215], v[76:79]
	v_mfma_f32_16x16x32_bf16 v[72:75], v[160:163], v[212:215], v[72:75]
	v_mfma_f32_16x16x32_bf16 v[124:127], v[156:159], v[192:195], v[124:127]
	v_mfma_f32_16x16x32_bf16 v[120:123], v[168:171], v[192:195], v[120:123]
	v_mfma_f32_16x16x32_bf16 v[108:111], v[156:159], v[200:203], v[108:111]
	v_mfma_f32_16x16x32_bf16 v[104:107], v[168:171], v[200:203], v[104:107]
	v_mfma_f32_16x16x32_bf16 v[92:95], v[156:159], v[208:211], v[92:95]
	v_mfma_f32_16x16x32_bf16 v[88:91], v[168:171], v[208:211], v[88:91]
	v_mfma_f32_16x16x32_bf16 v[76:79], v[156:159], v[216:219], v[76:79]
	v_mfma_f32_16x16x32_bf16 v[72:75], v[168:171], v[216:219], v[72:75]
	s_setprio 0
	s_setprio 1
	v_mfma_f32_16x16x32_bf16 v[116:119], v[172:175], v[188:191], v[116:119]
	v_mfma_f32_16x16x32_bf16 v[112:115], v[180:183], v[188:191], v[112:115]
	v_mfma_f32_16x16x32_bf16 v[100:103], v[172:175], v[196:199], v[100:103]
	v_mfma_f32_16x16x32_bf16 v[96:99], v[180:183], v[196:199], v[96:99]
	v_mfma_f32_16x16x32_bf16 v[84:87], v[172:175], v[204:207], v[84:87]
	v_mfma_f32_16x16x32_bf16 v[80:83], v[180:183], v[204:207], v[80:83]
	v_mfma_f32_16x16x32_bf16 v[68:71], v[172:175], v[212:215], v[68:71]
	v_mfma_f32_16x16x32_bf16 v[64:67], v[180:183], v[212:215], v[64:67]
	v_mfma_f32_16x16x32_bf16 v[116:119], v[176:179], v[192:195], v[116:119]
	v_mfma_f32_16x16x32_bf16 v[112:115], v[184:187], v[192:195], v[112:115]
	v_mfma_f32_16x16x32_bf16 v[100:103], v[176:179], v[200:203], v[100:103]
	v_mfma_f32_16x16x32_bf16 v[96:99], v[184:187], v[200:203], v[96:99]
	v_mfma_f32_16x16x32_bf16 v[84:87], v[176:179], v[208:211], v[84:87]
	v_mfma_f32_16x16x32_bf16 v[80:83], v[184:187], v[208:211], v[80:83]
	v_mfma_f32_16x16x32_bf16 v[68:71], v[176:179], v[216:219], v[68:71]
	v_mfma_f32_16x16x32_bf16 v[64:67], v[184:187], v[216:219], v[64:67]
	s_barrier
; #define PG8_STAGE(bufoff, gbase, voff) do { _Pragma("unroll") for (int _i = 0; _i < 2; ++_i) \
;         __builtin_amdgcn_global_load_lds((const unsigned*)((const char*)(gbase) + (voff)[_i]), (LAS unsigned*)(lds + (bufoff) + ldsw + _i * 8192), 16, 0, 0); } while (0)
; #define PG8_LDA(dst, b, h) do { _Pragma("unroll") for (int m = 0; m < 4; ++m) _Pragma("unroll") for (int k = 0; k < 2; ++k) dst[m][k] = *(const LAS bf16x8*)(lds + PG8_SA(b, h) + aoff + m * 2048 + k * 1024); } while (0)
; #define PG8_MMA(ai, bj, At, Bt) do { __builtin_amdgcn_s_setprio(1); _Pragma("unroll") for (int m = 0; m < 4; ++m) _Pragma("unroll") for (int n = 0; n < 2; ++n) _Pragma("unroll") for (int k = 0; k < 2; ++k) \
;         acc[ai][bj][m][n] = __builtin_amdgcn_mfma_f32_16x16x32_bf16(Bt[n][k], At[m][k], acc[ai][bj][m][n], 0, 0, 0); __builtin_amdgcn_s_setprio(0); } while (0)
; #define PG8_WAIT_V(n) asm volatile("s_waitcnt vmcnt(" #n ")" ::: "memory")
; #define PG8_WAIT_L(n) asm volatile("s_waitcnt lgkmcnt(" #n ")" ::: "memory")
; #define PG8_BAR __builtin_amdgcn_s_barrier()
; #define PG8_SCHED __builtin_amdgcn_sched_barrier(0)
; template <class Epi, bool ALIGN_EPI>
; __device__ __forceinline__ void gemm_phase(LAS unsigned char* lds, const Gemm g, const StaticOrder& S, const Epi& E) {
;     ...
;             PG8_LDA(At, 1, 1); PG8_STAGE(PG8_SB(1, 0), b3, voffB); PG8_STAGE(PG8_SB(1, 1), b3 + hstepB, voffB); PG8_STAGE(PG8_SA(1, 0), a3, voffA);
;             PG8_WAIT_V(8); PG8_WAIT_L(0); PG8_BAR; PG8_MMA(1, 0, At, B0); PG8_MMA(1, 1, At, B1); PG8_BAR; PG8_SCHED;
;         }
;         if constexpr (ALIGN_EPI) { if (wr == 0) PG8_BAR; }
	s_setprio 0
	s_add_i32 s28, s56, s35
	v_lshl_add_u64 v[164:165], v[164:165], 0, s[10:11]
	s_mov_b32 m0, s28
	ds_read_b128 v[188:191], v154 offset:49152
	ds_read_b128 v[192:195], v154 offset:50176
	ds_read_b128 v[196:199], v154 offset:51200
	ds_read_b128 v[200:203], v154 offset:52224
	ds_read_b128 v[204:207], v154 offset:53248
	ds_read_b128 v[208:211], v154 offset:54272
	ds_read_b128 v[212:215], v154 offset:55296
	ds_read_b128 v[216:219], v154 offset:56320
	global_load_lds_dwordx4 v[164:165], off
	s_add_i32 m0, s28, 0x2000
	s_add_u32 s26, s26, 0x80080
	v_lshl_add_u64 v[164:165], v[220:221], 0, s[10:11]
	s_addc_u32 s27, s27, 0
	s_add_i32 s28, s57, s35
	global_load_lds_dwordx4 v[164:165], off
	v_lshl_add_u64 v[164:165], s[26:27], 0, v[132:133]
	s_mov_b32 m0, s28
	s_nop 0
	global_load_lds_dwordx4 v[164:165], off
	v_lshl_add_u64 v[164:165], s[26:27], 0, v[128:129]
	s_add_i32 m0, s28, 0x2000
	s_nop 0
	global_load_lds_dwordx4 v[164:165], off
	v_lshl_add_u64 v[164:165], v[222:223], 0, s[10:11]
	s_mov_b32 m0, s41
	s_nop 0
	global_load_lds_dwordx4 v[164:165], off
	v_lshl_add_u64 v[164:165], v[224:225], 0, s[10:11]
	s_mov_b32 m0, s42
	s_nop 0
	global_load_lds_dwordx4 v[164:165], off
	s_waitcnt vmcnt(8)
	s_waitcnt lgkmcnt(0)
	s_setprio 1
	s_barrier
	v_mfma_f32_16x16x32_bf16 v[60:63], v[144:147], v[188:191], v[60:63]
	v_mfma_f32_16x16x32_bf16 v[56:59], v[160:163], v[188:191], v[56:59]
	v_mfma_f32_16x16x32_bf16 v[44:47], v[144:147], v[196:199], v[44:47]
	v_mfma_f32_16x16x32_bf16 v[40:43], v[160:163], v[196:199], v[40:43]
	v_mfma_f32_16x16x32_bf16 v[28:31], v[144:147], v[204:207], v[28:31]
	v_mfma_f32_16x16x32_bf16 v[24:27], v[160:163], v[204:207], v[24:27]
	v_mfma_f32_16x16x32_bf16 v[12:15], v[144:147], v[212:215], v[12:15]
	v_mfma_f32_16x16x32_bf16 v[8:11], v[160:163], v[212:215], v[8:11]
	v_mfma_f32_16x16x32_bf16 v[60:63], v[156:159], v[192:195], v[60:63]
	v_mfma_f32_16x16x32_bf16 v[56:59], v[168:171], v[192:195], v[56:59]
	v_mfma_f32_16x16x32_bf16 v[44:47], v[156:159], v[200:203], v[44:47]
	v_mfma_f32_16x16x32_bf16 v[40:43], v[168:171], v[200:203], v[40:43]
	v_mfma_f32_16x16x32_bf16 v[28:31], v[156:159], v[208:211], v[28:31]
	v_mfma_f32_16x16x32_bf16 v[24:27], v[168:171], v[208:211], v[24:27]
	v_mfma_f32_16x16x32_bf16 v[12:15], v[156:159], v[216:219], v[12:15]
	v_mfma_f32_16x16x32_bf16 v[8:11], v[168:171], v[216:219], v[8:11]
	s_setprio 0
	s_setprio 1
	v_mfma_f32_16x16x32_bf16 v[52:55], v[172:175], v[188:191], v[52:55]
	v_mfma_f32_16x16x32_bf16 v[48:51], v[180:183], v[188:191], v[48:51]
	v_mfma_f32_16x16x32_bf16 v[36:39], v[172:175], v[196:199], v[36:39]
	v_mfma_f32_16x16x32_bf16 v[32:35], v[180:183], v[196:199], v[32:35]
	v_mfma_f32_16x16x32_bf16 v[20:23], v[172:175], v[204:207], v[20:23]
	v_mfma_f32_16x16x32_bf16 v[16:19], v[180:183], v[204:207], v[16:19]
	v_mfma_f32_16x16x32_bf16 v[4:7], v[172:175], v[212:215], v[4:7]
	v_mfma_f32_16x16x32_bf16 v[0:3], v[180:183], v[212:215], v[0:3]
	v_mfma_f32_16x16x32_bf16 v[52:55], v[176:179], v[192:195], v[52:55]
	v_mfma_f32_16x16x32_bf16 v[48:51], v[184:187], v[192:195], v[48:51]
	v_mfma_f32_16x16x32_bf16 v[36:39], v[176:179], v[200:203], v[36:39]
	v_mfma_f32_16x16x32_bf16 v[32:35], v[184:187], v[200:203], v[32:35]
	v_mfma_f32_16x16x32_bf16 v[20:23], v[176:179], v[208:211], v[20:23]
	v_mfma_f32_16x16x32_bf16 v[16:19], v[184:187], v[208:211], v[16:19]
	v_mfma_f32_16x16x32_bf16 v[4:7], v[176:179], v[216:219], v[4:7]
	v_mfma_f32_16x16x32_bf16 v[0:3], v[184:187], v[216:219], v[0:3]
	s_barrier
	s_setprio 0
	s_add_i32 s55, s55, 2
	s_add_u32 s53, s53, 0x100
	s_addc_u32 s54, s54, 0
	s_add_u32 s24, s24, 0x100
	s_addc_u32 s25, s25, 0
	s_cmp_gt_u32 s55, 29
	s_cbranch_scc0 .LBB0_121
	s_and_b64 vcc, exec, s[12:13]
	s_cbranch_vccz .LBB0_124
	s_barrier

; #define PG8_STAGE(bufoff, gbase, voff) do { _Pragma("unroll") for (int _i = 0; _i < 2; ++_i) \
;         __builtin_amdgcn_global_load_lds((const unsigned*)((const char*)(gbase) + (voff)[_i]), (LAS unsigned*)(lds + (bufoff) + ldsw + _i * 8192), 16, 0, 0); } while (0)
; #define PG8_LDA(dst, b, h) do { _Pragma("unroll") for (int m = 0; m < 4; ++m) _Pragma("unroll") for (int k = 0; k < 2; ++k) dst[m][k] = *(const LAS bf16x8*)(lds + PG8_SA(b, h) + aoff + m * 2048 + k * 1024); } while (0)
; #define PG8_LDB(dst, b, h) do { _Pragma("unroll") for (int n = 0; n < 2; ++n) _Pragma("unroll") for (int k = 0; k < 2; ++k) dst[n][k] = *(const LAS bf16x8*)(lds + PG8_SB(b, h) + boff + n * 2048 + k * 1024); } while (0)
; #define PG8_MMA(ai, bj, At, Bt) do { __builtin_amdgcn_s_setprio(1); _Pragma("unroll") for (int m = 0; m < 4; ++m) _Pragma("unroll") for (int n = 0; n < 2; ++n) _Pragma("unroll") for (int k = 0; k < 2; ++k) \
;         acc[ai][bj][m][n] = __builtin_amdgcn_mfma_f32_16x16x32_bf16(Bt[n][k], At[m][k], acc[ai][bj][m][n], 0, 0, 0); __builtin_amdgcn_s_setprio(0); } while (0)
; #define PG8_WAIT_V(n) asm volatile("s_waitcnt vmcnt(" #n ")" ::: "memory")
; #define PG8_WAIT_L(n) asm volatile("s_waitcnt lgkmcnt(" #n ")" ::: "memory")
; #define PG8_BAR __builtin_amdgcn_s_barrier()
; #define PG8_SCHED __builtin_amdgcn_sched_barrier(0)
; template <class Epi, bool ALIGN_EPI>
; __device__ __forceinline__ void gemm_phase(LAS unsigned char* lds, const Gemm g, const StaticOrder& S, const Epi& E) {
;     ...
;             PG8_LDB(B0, 0, 0); PG8_LDB(B1, 0, 1); PG8_SCHED; PG8_LDA(At, 0, 0); PG8_STAGE(PG8_SA(1, 1), a1 + hstepA, voffA);
;             PG8_WAIT_V(8); PG8_WAIT_L(0); PG8_BAR; PG8_MMA(0, 0, At, B0); PG8_MMA(0, 1, At, B1); PG8_BAR; PG8_SCHED;
;             PG8_LDA(At, 0, 1); PG8_STAGE(PG8_SB(0, 0), b2, voffB); PG8_STAGE(PG8_SB(0, 1), b2 + hstepB, voffB); PG8_STAGE(PG8_SA(0, 0), a2, voffA);
;             PG8_WAIT_V(8); PG8_WAIT_L(0); PG8_BAR; PG8_MMA(1, 0, At, B0); PG8_MMA(1, 1, At, B1); PG8_BAR; PG8_SCHED;
.LBB0_309:
	ds_read_b128 v[64:67], v171
	ds_read_b128 v[72:75], v171 offset:1024
	ds_read_b128 v[80:83], v171 offset:2048
	ds_read_b128 v[84:87], v171 offset:3072
	ds_read_b128 v[156:159], v172
	ds_read_b128 v[160:163], v172 offset:1024
	ds_read_b128 v[176:179], v172 offset:2048
	ds_read_b128 v[180:183], v172 offset:3072
	s_add_u32 s4, s30, 0x100
	s_addc_u32 s5, s31, 0
	s_cmpk_eq_i32 s65, 0x54
	s_cselect_b32 s37, s27, s5
	s_cselect_b32 s36, s26, s4
	s_cselect_b32 s35, s29, s64
	s_cselect_b32 s34, s28, s63
	v_lshl_add_u64 v[164:165], s[30:31], 0, v[150:151]
	s_add_i32 m0, s43, 0xc000
	ds_read_b128 v[184:187], v173
	ds_read_b128 v[188:191], v173 offset:1024
	ds_read_b128 v[192:195], v173 offset:2048
	ds_read_b128 v[196:199], v173 offset:3072
	ds_read_b128 v[200:203], v173 offset:4096
	ds_read_b128 v[204:207], v173 offset:5120
	ds_read_b128 v[208:211], v173 offset:6144
	ds_read_b128 v[212:215], v173 offset:7168
	global_load_lds_dwordx4 v[164:165], off
	v_lshl_add_u64 v[164:165], s[30:31], 0, v[148:149]
	s_add_i32 m0, s43, 0xe000
	s_nop 0
	global_load_lds_dwordx4 v[164:165], off
	s_waitcnt vmcnt(8)
	s_waitcnt lgkmcnt(0)
	s_setprio 1
	s_barrier
	v_mfma_f32_16x16x32_bf16 v[140:143], v[64:67], v[184:187], v[140:143]
	v_mfma_f32_16x16x32_bf16 v[136:139], v[80:83], v[184:187], v[136:139]
	v_mfma_f32_16x16x32_bf16 v[124:127], v[64:67], v[192:195], v[124:127]
	v_mfma_f32_16x16x32_bf16 v[120:123], v[80:83], v[192:195], v[120:123]
	v_mfma_f32_16x16x32_bf16 v[108:111], v[64:67], v[200:203], v[108:111]
	v_mfma_f32_16x16x32_bf16 v[104:107], v[80:83], v[200:203], v[104:107]
	v_mfma_f32_16x16x32_bf16 v[92:95], v[64:67], v[208:211], v[92:95]
	v_mfma_f32_16x16x32_bf16 v[88:91], v[80:83], v[208:211], v[88:91]
	v_mfma_f32_16x16x32_bf16 v[140:143], v[72:75], v[188:191], v[140:143]
	v_mfma_f32_16x16x32_bf16 v[136:139], v[84:87], v[188:191], v[136:139]
	v_mfma_f32_16x16x32_bf16 v[124:127], v[72:75], v[196:199], v[124:127]
	v_mfma_f32_16x16x32_bf16 v[120:123], v[84:87], v[196:199], v[120:123]
	v_mfma_f32_16x16x32_bf16 v[108:111], v[72:75], v[204:207], v[108:111]
	v_mfma_f32_16x16x32_bf16 v[104:107], v[84:87], v[204:207], v[104:107]
	v_mfma_f32_16x16x32_bf16 v[92:95], v[72:75], v[212:215], v[92:95]
	v_mfma_f32_16x16x32_bf16 v[88:91], v[84:87], v[212:215], v[88:91]
	s_setprio 0
	s_setprio 1
	v_mfma_f32_16x16x32_bf16 v[132:135], v[156:159], v[184:187], v[132:135]
	v_mfma_f32_16x16x32_bf16 v[128:131], v[176:179], v[184:187], v[128:131]
	v_mfma_f32_16x16x32_bf16 v[116:119], v[156:159], v[192:195], v[116:119]
	v_mfma_f32_16x16x32_bf16 v[112:115], v[176:179], v[192:195], v[112:115]
	v_mfma_f32_16x16x32_bf16 v[100:103], v[156:159], v[200:203], v[100:103]
	v_mfma_f32_16x16x32_bf16 v[96:99], v[176:179], v[200:203], v[96:99]
	v_mfma_f32_16x16x32_bf16 v[76:79], v[156:159], v[208:211], v[76:79]
	v_mfma_f32_16x16x32_bf16 v[68:71], v[176:179], v[208:211], v[68:71]
	v_mfma_f32_16x16x32_bf16 v[132:135], v[160:163], v[188:191], v[132:135]
	v_mfma_f32_16x16x32_bf16 v[128:131], v[180:183], v[188:191], v[128:131]
	v_mfma_f32_16x16x32_bf16 v[116:119], v[160:163], v[196:199], v[116:119]
	v_mfma_f32_16x16x32_bf16 v[112:115], v[180:183], v[196:199], v[112:115]
	v_mfma_f32_16x16x32_bf16 v[100:103], v[160:163], v[204:207], v[100:103]
	v_mfma_f32_16x16x32_bf16 v[96:99], v[180:183], v[204:207], v[96:99]
	v_mfma_f32_16x16x32_bf16 v[76:79], v[160:163], v[212:215], v[76:79]
	v_mfma_f32_16x16x32_bf16 v[68:71], v[180:183], v[212:215], v[68:71]
	s_barrier
	s_setprio 0
	s_add_i32 s30, s56, s42
	v_lshl_add_u64 v[164:165], s[34:35], 0, v[144:145]
	s_mov_b32 m0, s30
	ds_read_b128 v[184:187], v173 offset:16384
	ds_read_b128 v[188:191], v173 offset:17408
	ds_read_b128 v[192:195], v173 offset:18432
	ds_read_b128 v[196:199], v173 offset:19456
	ds_read_b128 v[200:203], v173 offset:20480
	ds_read_b128 v[204:207], v173 offset:21504
	ds_read_b128 v[208:211], v173 offset:22528
	ds_read_b128 v[212:215], v173 offset:23552
	global_load_lds_dwordx4 v[164:165], off
	s_add_i32 m0, s30, 0x2000
	s_add_u32 s30, s34, 0x160000
	v_lshl_add_u64 v[216:217], s[34:35], 0, v[146:147]
	s_addc_u32 s31, s35, 0
	s_add_i32 s66, s57, s42
	global_load_lds_dwordx4 v[216:217], off
	v_lshl_add_u64 v[218:219], s[30:31], 0, v[144:145]
	s_mov_b32 m0, s66
	v_lshl_add_u64 v[220:221], s[36:37], 0, v[146:147]
	global_load_lds_dwordx4 v[218:219], off
	v_lshl_add_u64 v[218:219], s[30:31], 0, v[146:147]
	s_add_i32 m0, s66, 0x2000
	s_nop 0
	global_load_lds_dwordx4 v[218:219], off
	v_lshl_add_u64 v[218:219], s[36:37], 0, v[144:145]
	s_mov_b32 m0, s43
	s_nop 0
	global_load_lds_dwordx4 v[218:219], off
	s_mov_b32 m0, s44
	s_nop 0
	global_load_lds_dwordx4 v[220:221], off
	s_waitcnt vmcnt(8)
	s_waitcnt lgkmcnt(0)
	s_setprio 1
	s_barrier
; #define PG8_STAGE(bufoff, gbase, voff) do { _Pragma("unroll") for (int _i = 0; _i < 2; ++_i) \
;         __builtin_amdgcn_global_load_lds((const unsigned*)((const char*)(gbase) + (voff)[_i]), (LAS unsigned*)(lds + (bufoff) + ldsw + _i * 8192), 16, 0, 0); } while (0)
; #define PG8_LDA(dst, b, h) do { _Pragma("unroll") for (int m = 0; m < 4; ++m) _Pragma("unroll") for (int k = 0; k < 2; ++k) dst[m][k] = *(const LAS bf16x8*)(lds + PG8_SA(b, h) + aoff + m * 2048 + k * 1024); } while (0)
; #define PG8_LDB(dst, b, h) do { _Pragma("unroll") for (int n = 0; n < 2; ++n) _Pragma("unroll") for (int k = 0; k < 2; ++k) dst[n][k] = *(const LAS bf16x8*)(lds + PG8_SB(b, h) + boff + n * 2048 + k * 1024); } while (0)
; #define PG8_MMA(ai, bj, At, Bt) do { __builtin_amdgcn_s_setprio(1); _Pragma("unroll") for (int m = 0; m < 4; ++m) _Pragma("unroll") for (int n = 0; n < 2; ++n) _Pragma("unroll") for (int k = 0; k < 2; ++k) \
;         acc[ai][bj][m][n] = __builtin_amdgcn_mfma_f32_16x16x32_bf16(Bt[n][k], At[m][k], acc[ai][bj][m][n], 0, 0, 0); __builtin_amdgcn_s_setprio(0); } while (0)
; #define PG8_WAIT_V(n) asm volatile("s_waitcnt vmcnt(" #n ")" ::: "memory")
; #define PG8_WAIT_L(n) asm volatile("s_waitcnt lgkmcnt(" #n ")" ::: "memory")
; #define PG8_BAR __builtin_amdgcn_s_barrier()
; #define PG8_SCHED __builtin_amdgcn_sched_barrier(0)
; template <class Epi, bool ALIGN_EPI>
; __device__ __forceinline__ void gemm_phase(LAS unsigned char* lds, const Gemm g, const StaticOrder& S, const Epi& E) {
;     ...
;             PG8_LDA(At, 0, 1); PG8_STAGE(PG8_SB(0, 0), b2, voffB); PG8_STAGE(PG8_SB(0, 1), b2 + hstepB, voffB); PG8_STAGE(PG8_SA(0, 0), a2, voffA);
;             PG8_WAIT_V(8); PG8_WAIT_L(0); PG8_BAR; PG8_MMA(1, 0, At, B0); PG8_MMA(1, 1, At, B1); PG8_BAR; PG8_SCHED;
;             PG8_LDB(B0, 1, 0); PG8_LDB(B1, 1, 1); PG8_SCHED; PG8_LDA(At, 1, 0); PG8_STAGE(PG8_SA(0, 1), a2 + hstepA, voffA);
;             PG8_WAIT_V(8); PG8_WAIT_L(0); PG8_BAR; PG8_MMA(0, 0, At, B0); PG8_MMA(0, 1, At, B1); PG8_BAR; PG8_SCHED;
;             PG8_LDA(At, 1, 1); PG8_STAGE(PG8_SB(1, 0), b3, voffB); PG8_STAGE(PG8_SB(1, 1), b3 + hstepB, voffB); PG8_STAGE(PG8_SA(1, 0), a3, voffA);
;             PG8_WAIT_V(8); PG8_WAIT_L(0); PG8_BAR; PG8_MMA(1, 0, At, B0); PG8_MMA(1, 1, At, B1); PG8_BAR; PG8_SCHED;
	v_mfma_f32_16x16x32_bf16 v[60:63], v[64:67], v[184:187], v[60:63]
	v_mfma_f32_16x16x32_bf16 v[56:59], v[80:83], v[184:187], v[56:59]
	v_mfma_f32_16x16x32_bf16 v[44:47], v[64:67], v[192:195], v[44:47]
	v_mfma_f32_16x16x32_bf16 v[40:43], v[80:83], v[192:195], v[40:43]
	v_mfma_f32_16x16x32_bf16 v[28:31], v[64:67], v[200:203], v[28:31]
	v_mfma_f32_16x16x32_bf16 v[24:27], v[80:83], v[200:203], v[24:27]
	v_mfma_f32_16x16x32_bf16 v[12:15], v[64:67], v[208:211], v[12:15]
	v_mfma_f32_16x16x32_bf16 v[8:11], v[80:83], v[208:211], v[8:11]
	v_mfma_f32_16x16x32_bf16 v[60:63], v[72:75], v[188:191], v[60:63]
	v_mfma_f32_16x16x32_bf16 v[56:59], v[84:87], v[188:191], v[56:59]
	v_mfma_f32_16x16x32_bf16 v[44:47], v[72:75], v[196:199], v[44:47]
	v_mfma_f32_16x16x32_bf16 v[40:43], v[84:87], v[196:199], v[40:43]
	v_mfma_f32_16x16x32_bf16 v[28:31], v[72:75], v[204:207], v[28:31]
	v_mfma_f32_16x16x32_bf16 v[24:27], v[84:87], v[204:207], v[24:27]
	v_mfma_f32_16x16x32_bf16 v[12:15], v[72:75], v[212:215], v[12:15]
	v_mfma_f32_16x16x32_bf16 v[8:11], v[84:87], v[212:215], v[8:11]
	s_setprio 0
	s_setprio 1
	v_mfma_f32_16x16x32_bf16 v[52:55], v[156:159], v[184:187], v[52:55]
	v_mfma_f32_16x16x32_bf16 v[48:51], v[176:179], v[184:187], v[48:51]
	v_mfma_f32_16x16x32_bf16 v[36:39], v[156:159], v[192:195], v[36:39]
	v_mfma_f32_16x16x32_bf16 v[32:35], v[176:179], v[192:195], v[32:35]
	v_mfma_f32_16x16x32_bf16 v[20:23], v[156:159], v[200:203], v[20:23]
	v_mfma_f32_16x16x32_bf16 v[16:19], v[176:179], v[200:203], v[16:19]
	v_mfma_f32_16x16x32_bf16 v[4:7], v[156:159], v[208:211], v[4:7]
	v_mfma_f32_16x16x32_bf16 v[0:3], v[176:179], v[208:211], v[0:3]
	v_mfma_f32_16x16x32_bf16 v[52:55], v[160:163], v[188:191], v[52:55]
	v_mfma_f32_16x16x32_bf16 v[48:51], v[180:183], v[188:191], v[48:51]
	v_mfma_f32_16x16x32_bf16 v[36:39], v[160:163], v[196:199], v[36:39]
	v_mfma_f32_16x16x32_bf16 v[32:35], v[180:183], v[196:199], v[32:35]
	v_mfma_f32_16x16x32_bf16 v[20:23], v[160:163], v[204:207], v[20:23]
	v_mfma_f32_16x16x32_bf16 v[16:19], v[180:183], v[204:207], v[16:19]
	v_mfma_f32_16x16x32_bf16 v[4:7], v[160:163], v[212:215], v[4:7]
	v_mfma_f32_16x16x32_bf16 v[0:3], v[180:183], v[212:215], v[0:3]
	s_barrier
	s_setprio 0
	s_add_i32 s66, 0, 0x18000
	s_add_i32 s67, 0, 0x1c000
	v_add_u32_e32 v84, s66, v169
	v_add_u32_e32 v175, s67, v169
	ds_read_b128 v[64:67], v84
	ds_read_b128 v[72:75], v84 offset:1024
	ds_read_b128 v[80:83], v84 offset:2048
	ds_read_b128 v[84:87], v84 offset:3072
	ds_read_b128 v[156:159], v175
	ds_read_b128 v[160:163], v175 offset:1024
	ds_read_b128 v[176:179], v175 offset:2048
	ds_read_b128 v[180:183], v175 offset:3072
	s_add_u32 s30, s36, 0x160000
	s_addc_u32 s31, s37, 0
	s_mov_b32 m0, s45
	v_lshl_add_u64 v[222:223], s[30:31], 0, v[144:145]
	ds_read_b128 v[184:187], v173 offset:32768
	ds_read_b128 v[188:191], v173 offset:33792
	ds_read_b128 v[192:195], v173 offset:34816
	ds_read_b128 v[196:199], v173 offset:35840
	ds_read_b128 v[200:203], v173 offset:36864
	ds_read_b128 v[204:207], v173 offset:37888
	ds_read_b128 v[208:211], v173 offset:38912
	ds_read_b128 v[212:215], v173 offset:39936
	global_load_lds_dwordx4 v[222:223], off
	v_lshl_add_u64 v[222:223], s[30:31], 0, v[146:147]
	s_mov_b32 m0, s46
	s_nop 0
	global_load_lds_dwordx4 v[222:223], off
	s_waitcnt vmcnt(8)
	s_waitcnt lgkmcnt(0)
	s_setprio 1
	s_barrier
	v_mfma_f32_16x16x32_bf16 v[140:143], v[64:67], v[184:187], v[140:143]
	v_mfma_f32_16x16x32_bf16 v[136:139], v[80:83], v[184:187], v[136:139]
	v_mfma_f32_16x16x32_bf16 v[124:127], v[64:67], v[192:195], v[124:127]
	v_mfma_f32_16x16x32_bf16 v[120:123], v[80:83], v[192:195], v[120:123]
	v_mfma_f32_16x16x32_bf16 v[108:111], v[64:67], v[200:203], v[108:111]
	v_mfma_f32_16x16x32_bf16 v[104:107], v[80:83], v[200:203], v[104:107]
	v_mfma_f32_16x16x32_bf16 v[92:95], v[64:67], v[208:211], v[92:95]
	v_mfma_f32_16x16x32_bf16 v[88:91], v[80:83], v[208:211], v[88:91]
	v_mfma_f32_16x16x32_bf16 v[140:143], v[72:75], v[188:191], v[140:143]
	v_mfma_f32_16x16x32_bf16 v[136:139], v[84:87], v[188:191], v[136:139]
	v_mfma_f32_16x16x32_bf16 v[124:127], v[72:75], v[196:199], v[124:127]
	v_mfma_f32_16x16x32_bf16 v[120:123], v[84:87], v[196:199], v[120:123]
	v_mfma_f32_16x16x32_bf16 v[108:111], v[72:75], v[204:207], v[108:111]
	v_mfma_f32_16x16x32_bf16 v[104:107], v[84:87], v[204:207], v[104:107]
	v_mfma_f32_16x16x32_bf16 v[92:95], v[72:75], v[212:215], v[92:95]
	v_mfma_f32_16x16x32_bf16 v[88:91], v[84:87], v[212:215], v[88:91]
	s_setprio 0
	s_setprio 1
	v_mfma_f32_16x16x32_bf16 v[132:135], v[156:159], v[184:187], v[132:135]
	v_mfma_f32_16x16x32_bf16 v[128:131], v[176:179], v[184:187], v[128:131]
	v_mfma_f32_16x16x32_bf16 v[116:119], v[156:159], v[192:195], v[116:119]
	v_mfma_f32_16x16x32_bf16 v[112:115], v[176:179], v[192:195], v[112:115]
	v_mfma_f32_16x16x32_bf16 v[100:103], v[156:159], v[200:203], v[100:103]
	v_mfma_f32_16x16x32_bf16 v[96:99], v[176:179], v[200:203], v[96:99]
	v_mfma_f32_16x16x32_bf16 v[76:79], v[156:159], v[208:211], v[76:79]
	v_mfma_f32_16x16x32_bf16 v[68:71], v[176:179], v[208:211], v[68:71]
	v_mfma_f32_16x16x32_bf16 v[132:135], v[160:163], v[188:191], v[132:135]
	v_mfma_f32_16x16x32_bf16 v[128:131], v[180:183], v[188:191], v[128:131]
	v_mfma_f32_16x16x32_bf16 v[116:119], v[160:163], v[196:199], v[116:119]
	v_mfma_f32_16x16x32_bf16 v[112:115], v[180:183], v[196:199], v[112:115]
	v_mfma_f32_16x16x32_bf16 v[100:103], v[160:163], v[204:207], v[100:103]
	v_mfma_f32_16x16x32_bf16 v[96:99], v[180:183], v[204:207], v[96:99]
	v_mfma_f32_16x16x32_bf16 v[76:79], v[160:163], v[212:215], v[76:79]
	v_mfma_f32_16x16x32_bf16 v[68:71], v[180:183], v[212:215], v[68:71]
	s_barrier
; #define PG8_STAGE(bufoff, gbase, voff) do { _Pragma("unroll") for (int _i = 0; _i < 2; ++_i) \
;         __builtin_amdgcn_global_load_lds((const unsigned*)((const char*)(gbase) + (voff)[_i]), (LAS unsigned*)(lds + (bufoff) + ldsw + _i * 8192), 16, 0, 0); } while (0)
; #define PG8_LDA(dst, b, h) do { _Pragma("unroll") for (int m = 0; m < 4; ++m) _Pragma("unroll") for (int k = 0; k < 2; ++k) dst[m][k] = *(const LAS bf16x8*)(lds + PG8_SA(b, h) + aoff + m * 2048 + k * 1024); } while (0)
; #define PG8_MMA(ai, bj, At, Bt) do { __builtin_amdgcn_s_setprio(1); _Pragma("unroll") for (int m = 0; m < 4; ++m) _Pragma("unroll") for (int n = 0; n < 2; ++n) _Pragma("unroll") for (int k = 0; k < 2; ++k) \
;         acc[ai][bj][m][n] = __builtin_amdgcn_mfma_f32_16x16x32_bf16(Bt[n][k], At[m][k], acc[ai][bj][m][n], 0, 0, 0); __builtin_amdgcn_s_setprio(0); } while (0)
; #define PG8_WAIT_V(n) asm volatile("s_waitcnt vmcnt(" #n ")" ::: "memory")
; #define PG8_WAIT_L(n) asm volatile("s_waitcnt lgkmcnt(" #n ")" ::: "memory")
; #define PG8_BAR __builtin_amdgcn_s_barrier()
; #define PG8_SCHED __builtin_amdgcn_sched_barrier(0)
; template <class Epi, bool ALIGN_EPI>
; __device__ __forceinline__ void gemm_phase(LAS unsigned char* lds, const Gemm g, const StaticOrder& S, const Epi& E) {
;     ...
;             PG8_LDA(At, 1, 1); PG8_STAGE(PG8_SB(1, 0), b3, voffB); PG8_STAGE(PG8_SB(1, 1), b3 + hstepB, voffB); PG8_STAGE(PG8_SA(1, 0), a3, voffA);
;             PG8_WAIT_V(8); PG8_WAIT_L(0); PG8_BAR; PG8_MMA(1, 0, At, B0); PG8_MMA(1, 1, At, B1); PG8_BAR; PG8_SCHED;
;         }
;         if constexpr (ALIGN_EPI) { if (wr == 0) PG8_BAR; }
	s_setprio 0
	s_add_i32 s30, s66, s42
	v_lshl_add_u64 v[164:165], v[164:165], 0, s[20:21]
	s_mov_b32 m0, s30
	ds_read_b128 v[184:187], v173 offset:49152
	ds_read_b128 v[188:191], v173 offset:50176
	ds_read_b128 v[192:195], v173 offset:51200
	ds_read_b128 v[196:199], v173 offset:52224
	ds_read_b128 v[200:203], v173 offset:53248
	ds_read_b128 v[204:207], v173 offset:54272
	ds_read_b128 v[208:211], v173 offset:55296
	ds_read_b128 v[212:215], v173 offset:56320
	global_load_lds_dwordx4 v[164:165], off
	s_add_i32 m0, s30, 0x2000
	s_add_u32 s30, s34, 0x160080
	v_lshl_add_u64 v[164:165], v[216:217], 0, s[20:21]
	s_addc_u32 s31, s35, 0
	s_add_i32 s34, s67, s42
	global_load_lds_dwordx4 v[164:165], off
	v_lshl_add_u64 v[164:165], s[30:31], 0, v[144:145]
	s_mov_b32 m0, s34
	s_nop 0
	global_load_lds_dwordx4 v[164:165], off
	v_lshl_add_u64 v[164:165], s[30:31], 0, v[146:147]
	s_add_i32 m0, s34, 0x2000
	s_nop 0
	global_load_lds_dwordx4 v[164:165], off
	v_lshl_add_u64 v[164:165], v[218:219], 0, s[20:21]
	s_mov_b32 m0, s48
	s_nop 0
	global_load_lds_dwordx4 v[164:165], off
	v_lshl_add_u64 v[164:165], v[220:221], 0, s[20:21]
	s_mov_b32 m0, s49
	s_nop 0
	global_load_lds_dwordx4 v[164:165], off
	s_waitcnt vmcnt(8)
	s_waitcnt lgkmcnt(0)
	s_setprio 1
	s_barrier
	v_mfma_f32_16x16x32_bf16 v[60:63], v[64:67], v[184:187], v[60:63]
	v_mfma_f32_16x16x32_bf16 v[56:59], v[80:83], v[184:187], v[56:59]
	v_mfma_f32_16x16x32_bf16 v[44:47], v[64:67], v[192:195], v[44:47]
	v_mfma_f32_16x16x32_bf16 v[40:43], v[80:83], v[192:195], v[40:43]
	v_mfma_f32_16x16x32_bf16 v[28:31], v[64:67], v[200:203], v[28:31]
	v_mfma_f32_16x16x32_bf16 v[24:27], v[80:83], v[200:203], v[24:27]
	v_mfma_f32_16x16x32_bf16 v[12:15], v[64:67], v[208:211], v[12:15]
	v_mfma_f32_16x16x32_bf16 v[8:11], v[80:83], v[208:211], v[8:11]
	v_mfma_f32_16x16x32_bf16 v[60:63], v[72:75], v[188:191], v[60:63]
	v_mfma_f32_16x16x32_bf16 v[56:59], v[84:87], v[188:191], v[56:59]
	v_mfma_f32_16x16x32_bf16 v[44:47], v[72:75], v[196:199], v[44:47]
	v_mfma_f32_16x16x32_bf16 v[40:43], v[84:87], v[196:199], v[40:43]
	v_mfma_f32_16x16x32_bf16 v[28:31], v[72:75], v[204:207], v[28:31]
	v_mfma_f32_16x16x32_bf16 v[24:27], v[84:87], v[204:207], v[24:27]
	v_mfma_f32_16x16x32_bf16 v[12:15], v[72:75], v[212:215], v[12:15]
	v_mfma_f32_16x16x32_bf16 v[8:11], v[84:87], v[212:215], v[8:11]
	s_setprio 0
	s_setprio 1
	v_mfma_f32_16x16x32_bf16 v[52:55], v[156:159], v[184:187], v[52:55]
	v_mfma_f32_16x16x32_bf16 v[48:51], v[176:179], v[184:187], v[48:51]
	v_mfma_f32_16x16x32_bf16 v[36:39], v[156:159], v[192:195], v[36:39]
	v_mfma_f32_16x16x32_bf16 v[32:35], v[176:179], v[192:195], v[32:35]
	v_mfma_f32_16x16x32_bf16 v[20:23], v[156:159], v[200:203], v[20:23]
	v_mfma_f32_16x16x32_bf16 v[16:19], v[176:179], v[200:203], v[16:19]
	v_mfma_f32_16x16x32_bf16 v[4:7], v[156:159], v[208:211], v[4:7]
	v_mfma_f32_16x16x32_bf16 v[0:3], v[176:179], v[208:211], v[0:3]
	v_mfma_f32_16x16x32_bf16 v[52:55], v[160:163], v[188:191], v[52:55]
	v_mfma_f32_16x16x32_bf16 v[48:51], v[180:183], v[188:191], v[48:51]
	v_mfma_f32_16x16x32_bf16 v[36:39], v[160:163], v[196:199], v[36:39]
	v_mfma_f32_16x16x32_bf16 v[32:35], v[180:183], v[196:199], v[32:35]
	v_mfma_f32_16x16x32_bf16 v[20:23], v[160:163], v[204:207], v[20:23]
	v_mfma_f32_16x16x32_bf16 v[16:19], v[180:183], v[204:207], v[16:19]
	v_mfma_f32_16x16x32_bf16 v[4:7], v[160:163], v[212:215], v[4:7]
	v_mfma_f32_16x16x32_bf16 v[0:3], v[180:183], v[212:215], v[0:3]
	s_barrier
	s_setprio 0
	s_add_i32 s65, s65, 2
	s_add_u32 s63, s63, 0x100
	s_addc_u32 s64, s64, 0
	s_cmpk_gt_u32 s65, 0x55
	s_mov_b64 s[30:31], s[4:5]
	s_cbranch_scc0 .LBB0_309
	s_and_b64 vcc, exec, s[22:23]
	s_cbranch_vccz .LBB0_312
	s_barrier

; #define PG8_STAGE(bufoff, gbase, voff) do { _Pragma("unroll") for (int _i = 0; _i < 2; ++_i) \
;         __builtin_amdgcn_global_load_lds((const unsigned*)((const char*)(gbase) + (voff)[_i]), (LAS unsigned*)(lds + (bufoff) + ldsw + _i * 8192), 16, 0, 0); } while (0)
; #define PG8_LDA(dst, b, h) do { _Pragma("unroll") for (int m = 0; m < 4; ++m) _Pragma("unroll") for (int k = 0; k < 2; ++k) dst[m][k] = *(const LAS bf16x8*)(lds + PG8_SA(b, h) + aoff + m * 2048 + k * 1024); } while (0)
; #define PG8_LDB(dst, b, h) do { _Pragma("unroll") for (int n = 0; n < 2; ++n) _Pragma("unroll") for (int k = 0; k < 2; ++k) dst[n][k] = *(const LAS bf16x8*)(lds + PG8_SB(b, h) + boff + n * 2048 + k * 1024); } while (0)
; #define PG8_MMA(ai, bj, At, Bt) do { __builtin_amdgcn_s_setprio(1); _Pragma("unroll") for (int m = 0; m < 4; ++m) _Pragma("unroll") for (int n = 0; n < 2; ++n) _Pragma("unroll") for (int k = 0; k < 2; ++k) \
;         acc[ai][bj][m][n] = __builtin_amdgcn_mfma_f32_16x16x32_bf16(Bt[n][k], At[m][k], acc[ai][bj][m][n], 0, 0, 0); __builtin_amdgcn_s_setprio(0); } while (0)
; #define PG8_WAIT_V(n) asm volatile("s_waitcnt vmcnt(" #n ")" ::: "memory")
; #define PG8_WAIT_L(n) asm volatile("s_waitcnt lgkmcnt(" #n ")" ::: "memory")
; #define PG8_BAR __builtin_amdgcn_s_barrier()
; #define PG8_SCHED __builtin_amdgcn_sched_barrier(0)
; template <class Epi, bool ALIGN_EPI>
; __device__ __forceinline__ void gemm_phase(LAS unsigned char* lds, const Gemm g, const StaticOrder& S, const Epi& E) {
;     ...
;             PG8_LDB(B0, 0, 0); PG8_LDB(B1, 0, 1); PG8_SCHED; PG8_LDA(At, 0, 0); PG8_STAGE(PG8_SA(1, 1), a1 + hstepA, voffA);
;             PG8_WAIT_V(8); PG8_WAIT_L(0); PG8_BAR; PG8_MMA(0, 0, At, B0); PG8_MMA(0, 1, At, B1); PG8_BAR; PG8_SCHED;
;             PG8_LDA(At, 0, 1); PG8_STAGE(PG8_SB(0, 0), b2, voffB); PG8_STAGE(PG8_SB(0, 1), b2 + hstepB, voffB); PG8_STAGE(PG8_SA(0, 0), a2, voffA);
;             PG8_WAIT_V(8); PG8_WAIT_L(0); PG8_BAR; PG8_MMA(1, 0, At, B0); PG8_MMA(1, 1, At, B1); PG8_BAR; PG8_SCHED;
.LBB0_459:
	ds_read_b128 v[152:155], v165
	ds_read_b128 v[156:159], v165 offset:1024
	ds_read_b128 v[172:175], v165 offset:2048
	ds_read_b128 v[176:179], v165 offset:3072
	ds_read_b128 v[180:183], v168
	ds_read_b128 v[184:187], v168 offset:1024
	ds_read_b128 v[188:191], v168 offset:2048
	ds_read_b128 v[192:195], v168 offset:3072
	s_add_u32 s40, s8, 0xfff80080
	s_addc_u32 s41, s9, -1
	s_cmp_eq_u32 s45, 28
	s_cselect_b32 s43, s5, s41
	s_cselect_b32 s42, s7, s40
	s_cselect_b32 s41, s10, s44
	s_cselect_b32 s40, s31, s35
	v_lshl_add_u64 v[160:161], s[8:9], 0, v[146:147]
	s_add_i32 m0, s50, 0xc000
	ds_read_b128 v[196:199], v169
	ds_read_b128 v[200:203], v169 offset:1024
	ds_read_b128 v[204:207], v169 offset:2048
	ds_read_b128 v[208:211], v169 offset:3072
	ds_read_b128 v[212:215], v169 offset:4096
	ds_read_b128 v[216:219], v169 offset:5120
	ds_read_b128 v[220:223], v169 offset:6144
	ds_read_b128 v[224:227], v169 offset:7168
	global_load_lds_dwordx4 v[160:161], off
	v_lshl_add_u64 v[160:161], s[8:9], 0, v[144:145]
	s_add_i32 m0, s50, 0xe000
	s_nop 0
	global_load_lds_dwordx4 v[160:161], off
	s_waitcnt vmcnt(8)
	s_waitcnt lgkmcnt(0)
	s_setprio 1
	s_barrier
	v_mfma_f32_16x16x32_bf16 v[120:123], v[152:155], v[196:199], v[120:123]
	v_mfma_f32_16x16x32_bf16 v[112:115], v[172:175], v[196:199], v[112:115]
	v_mfma_f32_16x16x32_bf16 v[104:107], v[152:155], v[204:207], v[104:107]
	v_mfma_f32_16x16x32_bf16 v[96:99], v[172:175], v[204:207], v[96:99]
	v_mfma_f32_16x16x32_bf16 v[88:91], v[152:155], v[212:215], v[88:91]
	v_mfma_f32_16x16x32_bf16 v[80:83], v[172:175], v[212:215], v[80:83]
	v_mfma_f32_16x16x32_bf16 v[72:75], v[152:155], v[220:223], v[72:75]
	v_mfma_f32_16x16x32_bf16 v[64:67], v[172:175], v[220:223], v[64:67]
	v_mfma_f32_16x16x32_bf16 v[120:123], v[156:159], v[200:203], v[120:123]
	v_mfma_f32_16x16x32_bf16 v[112:115], v[176:179], v[200:203], v[112:115]
	v_mfma_f32_16x16x32_bf16 v[104:107], v[156:159], v[208:211], v[104:107]
	v_mfma_f32_16x16x32_bf16 v[96:99], v[176:179], v[208:211], v[96:99]
	v_mfma_f32_16x16x32_bf16 v[88:91], v[156:159], v[216:219], v[88:91]
	v_mfma_f32_16x16x32_bf16 v[80:83], v[176:179], v[216:219], v[80:83]
	v_mfma_f32_16x16x32_bf16 v[72:75], v[156:159], v[224:227], v[72:75]
	v_mfma_f32_16x16x32_bf16 v[64:67], v[176:179], v[224:227], v[64:67]
	s_setprio 0
	s_setprio 1
	v_mfma_f32_16x16x32_bf16 v[124:127], v[180:183], v[196:199], v[124:127]
	v_mfma_f32_16x16x32_bf16 v[116:119], v[188:191], v[196:199], v[116:119]
	v_mfma_f32_16x16x32_bf16 v[108:111], v[180:183], v[204:207], v[108:111]
	v_mfma_f32_16x16x32_bf16 v[100:103], v[188:191], v[204:207], v[100:103]
	v_mfma_f32_16x16x32_bf16 v[92:95], v[180:183], v[212:215], v[92:95]
	v_mfma_f32_16x16x32_bf16 v[84:87], v[188:191], v[212:215], v[84:87]
	v_mfma_f32_16x16x32_bf16 v[76:79], v[180:183], v[220:223], v[76:79]
	v_mfma_f32_16x16x32_bf16 v[68:71], v[188:191], v[220:223], v[68:71]
	v_mfma_f32_16x16x32_bf16 v[124:127], v[184:187], v[200:203], v[124:127]
	v_mfma_f32_16x16x32_bf16 v[116:119], v[192:195], v[200:203], v[116:119]
	v_mfma_f32_16x16x32_bf16 v[108:111], v[184:187], v[208:211], v[108:111]
	v_mfma_f32_16x16x32_bf16 v[100:103], v[192:195], v[208:211], v[100:103]
	v_mfma_f32_16x16x32_bf16 v[92:95], v[184:187], v[216:219], v[92:95]
	v_mfma_f32_16x16x32_bf16 v[84:87], v[192:195], v[216:219], v[84:87]
	v_mfma_f32_16x16x32_bf16 v[76:79], v[184:187], v[224:227], v[76:79]
	v_mfma_f32_16x16x32_bf16 v[68:71], v[192:195], v[224:227], v[68:71]
	s_barrier
	s_setprio 0
	s_add_i32 s71, s62, s49
	v_lshl_add_u64 v[160:161], s[40:41], 0, v[130:131]
	s_mov_b32 m0, s71
	ds_read_b128 v[196:199], v169 offset:16384
	ds_read_b128 v[200:203], v169 offset:17408
	ds_read_b128 v[204:207], v169 offset:18432
	ds_read_b128 v[208:211], v169 offset:19456
	ds_read_b128 v[212:215], v169 offset:20480
	ds_read_b128 v[216:219], v169 offset:21504
	ds_read_b128 v[220:223], v169 offset:22528
	ds_read_b128 v[224:227], v169 offset:23552
	global_load_lds_dwordx4 v[160:161], off
	s_add_i32 m0, s71, 0x2000
	s_add_u32 s78, s40, 0x80000
	v_lshl_add_u64 v[228:229], s[40:41], 0, v[134:135]
	s_addc_u32 s79, s41, 0
	s_add_i32 s71, s63, s49
	global_load_lds_dwordx4 v[228:229], off
	v_lshl_add_u64 v[230:231], s[78:79], 0, v[130:131]
	s_mov_b32 m0, s71
	v_lshl_add_u64 v[232:233], s[42:43], 0, v[132:133]
	global_load_lds_dwordx4 v[230:231], off
	v_lshl_add_u64 v[230:231], s[78:79], 0, v[134:135]
	s_add_i32 m0, s71, 0x2000
	s_nop 0
	global_load_lds_dwordx4 v[230:231], off
	v_lshl_add_u64 v[230:231], s[42:43], 0, v[128:129]
	s_mov_b32 m0, s50
	s_nop 0
	global_load_lds_dwordx4 v[230:231], off
	s_mov_b32 m0, s51
	s_nop 0
	global_load_lds_dwordx4 v[232:233], off
	s_waitcnt vmcnt(8)
	s_waitcnt lgkmcnt(0)
	s_setprio 1
	s_barrier
; #define PG8_STAGE(bufoff, gbase, voff) do { _Pragma("unroll") for (int _i = 0; _i < 2; ++_i) \
;         __builtin_amdgcn_global_load_lds((const unsigned*)((const char*)(gbase) + (voff)[_i]), (LAS unsigned*)(lds + (bufoff) + ldsw + _i * 8192), 16, 0, 0); } while (0)
; #define PG8_LDA(dst, b, h) do { _Pragma("unroll") for (int m = 0; m < 4; ++m) _Pragma("unroll") for (int k = 0; k < 2; ++k) dst[m][k] = *(const LAS bf16x8*)(lds + PG8_SA(b, h) + aoff + m * 2048 + k * 1024); } while (0)
; #define PG8_LDB(dst, b, h) do { _Pragma("unroll") for (int n = 0; n < 2; ++n) _Pragma("unroll") for (int k = 0; k < 2; ++k) dst[n][k] = *(const LAS bf16x8*)(lds + PG8_SB(b, h) + boff + n * 2048 + k * 1024); } while (0)
; #define PG8_MMA(ai, bj, At, Bt) do { __builtin_amdgcn_s_setprio(1); _Pragma("unroll") for (int m = 0; m < 4; ++m) _Pragma("unroll") for (int n = 0; n < 2; ++n) _Pragma("unroll") for (int k = 0; k < 2; ++k) \
;         acc[ai][bj][m][n] = __builtin_amdgcn_mfma_f32_16x16x32_bf16(Bt[n][k], At[m][k], acc[ai][bj][m][n], 0, 0, 0); __builtin_amdgcn_s_setprio(0); } while (0)
; #define PG8_WAIT_V(n) asm volatile("s_waitcnt vmcnt(" #n ")" ::: "memory")
; #define PG8_WAIT_L(n) asm volatile("s_waitcnt lgkmcnt(" #n ")" ::: "memory")
; #define PG8_BAR __builtin_amdgcn_s_barrier()
; #define PG8_SCHED __builtin_amdgcn_sched_barrier(0)
; template <class Epi, bool ALIGN_EPI>
; __device__ __forceinline__ void gemm_phase(LAS unsigned char* lds, const Gemm g, const StaticOrder& S, const Epi& E) {
;     ...
;             PG8_WAIT_V(8); PG8_WAIT_L(0); PG8_BAR; PG8_MMA(1, 0, At, B0); PG8_MMA(1, 1, At, B1); PG8_BAR; PG8_SCHED;
;             PG8_LDB(B0, 1, 0); PG8_LDB(B1, 1, 1); PG8_SCHED; PG8_LDA(At, 1, 0); PG8_STAGE(PG8_SA(0, 1), a2 + hstepA, voffA);
;             PG8_WAIT_V(8); PG8_WAIT_L(0); PG8_BAR; PG8_MMA(0, 0, At, B0); PG8_MMA(0, 1, At, B1); PG8_BAR; PG8_SCHED;
	v_mfma_f32_16x16x32_bf16 v[56:59], v[152:155], v[196:199], v[56:59]
	v_mfma_f32_16x16x32_bf16 v[48:51], v[172:175], v[196:199], v[48:51]
	v_mfma_f32_16x16x32_bf16 v[40:43], v[152:155], v[204:207], v[40:43]
	v_mfma_f32_16x16x32_bf16 v[32:35], v[172:175], v[204:207], v[32:35]
	v_mfma_f32_16x16x32_bf16 v[24:27], v[152:155], v[212:215], v[24:27]
	v_mfma_f32_16x16x32_bf16 v[16:19], v[172:175], v[212:215], v[16:19]
	v_mfma_f32_16x16x32_bf16 v[8:11], v[152:155], v[220:223], v[8:11]
	v_mfma_f32_16x16x32_bf16 v[0:3], v[172:175], v[220:223], v[0:3]
	v_mfma_f32_16x16x32_bf16 v[56:59], v[156:159], v[200:203], v[56:59]
	v_mfma_f32_16x16x32_bf16 v[48:51], v[176:179], v[200:203], v[48:51]
	v_mfma_f32_16x16x32_bf16 v[40:43], v[156:159], v[208:211], v[40:43]
	v_mfma_f32_16x16x32_bf16 v[32:35], v[176:179], v[208:211], v[32:35]
	v_mfma_f32_16x16x32_bf16 v[24:27], v[156:159], v[216:219], v[24:27]
	v_mfma_f32_16x16x32_bf16 v[16:19], v[176:179], v[216:219], v[16:19]
	v_mfma_f32_16x16x32_bf16 v[8:11], v[156:159], v[224:227], v[8:11]
	v_mfma_f32_16x16x32_bf16 v[0:3], v[176:179], v[224:227], v[0:3]
	s_setprio 0
	s_setprio 1
	v_mfma_f32_16x16x32_bf16 v[60:63], v[180:183], v[196:199], v[60:63]
	v_mfma_f32_16x16x32_bf16 v[52:55], v[188:191], v[196:199], v[52:55]
	v_mfma_f32_16x16x32_bf16 v[44:47], v[180:183], v[204:207], v[44:47]
	v_mfma_f32_16x16x32_bf16 v[36:39], v[188:191], v[204:207], v[36:39]
	v_mfma_f32_16x16x32_bf16 v[28:31], v[180:183], v[212:215], v[28:31]
	v_mfma_f32_16x16x32_bf16 v[20:23], v[188:191], v[212:215], v[20:23]
	v_mfma_f32_16x16x32_bf16 v[12:15], v[180:183], v[220:223], v[12:15]
	v_mfma_f32_16x16x32_bf16 v[4:7], v[188:191], v[220:223], v[4:7]
	v_mfma_f32_16x16x32_bf16 v[60:63], v[184:187], v[200:203], v[60:63]
	v_mfma_f32_16x16x32_bf16 v[52:55], v[192:195], v[200:203], v[52:55]
	v_mfma_f32_16x16x32_bf16 v[44:47], v[184:187], v[208:211], v[44:47]
	v_mfma_f32_16x16x32_bf16 v[36:39], v[192:195], v[208:211], v[36:39]
	v_mfma_f32_16x16x32_bf16 v[28:31], v[184:187], v[216:219], v[28:31]
	v_mfma_f32_16x16x32_bf16 v[20:23], v[192:195], v[216:219], v[20:23]
	v_mfma_f32_16x16x32_bf16 v[12:15], v[184:187], v[224:227], v[12:15]
	v_mfma_f32_16x16x32_bf16 v[4:7], v[192:195], v[224:227], v[4:7]
	s_barrier
	s_setprio 0
	s_add_i32 s71, 0, 0x18000
	v_add_u32_e32 v136, s71, v162
	s_add_i32 s73, 0, 0x1c000
	ds_read_b128 v[152:155], v136
	ds_read_b128 v[156:159], v136 offset:1024
	ds_read_b128 v[172:175], v136 offset:2048
	ds_read_b128 v[176:179], v136 offset:3072
	v_add_u32_e32 v136, s73, v162
	ds_read_b128 v[180:183], v136
	ds_read_b128 v[184:187], v136 offset:1024
	ds_read_b128 v[188:191], v136 offset:2048
	ds_read_b128 v[192:195], v136 offset:3072
	s_add_u32 s42, s42, 0x80000
	s_addc_u32 s43, s43, 0
	s_mov_b32 m0, s52
	v_lshl_add_u64 v[234:235], s[42:43], 0, v[128:129]
	ds_read_b128 v[196:199], v169 offset:32768
	ds_read_b128 v[200:203], v169 offset:33792
	ds_read_b128 v[204:207], v169 offset:34816
	ds_read_b128 v[208:211], v169 offset:35840
	ds_read_b128 v[212:215], v169 offset:36864
	ds_read_b128 v[216:219], v169 offset:37888
	ds_read_b128 v[220:223], v169 offset:38912
	ds_read_b128 v[224:227], v169 offset:39936
	global_load_lds_dwordx4 v[234:235], off
	v_lshl_add_u64 v[234:235], s[42:43], 0, v[132:133]
	s_mov_b32 m0, s53
	s_nop 0
	global_load_lds_dwordx4 v[234:235], off
	s_waitcnt vmcnt(8)
	s_waitcnt lgkmcnt(0)
	s_setprio 1
	s_barrier
	v_mfma_f32_16x16x32_bf16 v[120:123], v[152:155], v[196:199], v[120:123]
	v_mfma_f32_16x16x32_bf16 v[112:115], v[172:175], v[196:199], v[112:115]
	v_mfma_f32_16x16x32_bf16 v[104:107], v[152:155], v[204:207], v[104:107]
	v_mfma_f32_16x16x32_bf16 v[96:99], v[172:175], v[204:207], v[96:99]
	v_mfma_f32_16x16x32_bf16 v[88:91], v[152:155], v[212:215], v[88:91]
	v_mfma_f32_16x16x32_bf16 v[80:83], v[172:175], v[212:215], v[80:83]
	v_mfma_f32_16x16x32_bf16 v[72:75], v[152:155], v[220:223], v[72:75]
	v_mfma_f32_16x16x32_bf16 v[64:67], v[172:175], v[220:223], v[64:67]
	v_mfma_f32_16x16x32_bf16 v[120:123], v[156:159], v[200:203], v[120:123]
	v_mfma_f32_16x16x32_bf16 v[112:115], v[176:179], v[200:203], v[112:115]
	v_mfma_f32_16x16x32_bf16 v[104:107], v[156:159], v[208:211], v[104:107]
	v_mfma_f32_16x16x32_bf16 v[96:99], v[176:179], v[208:211], v[96:99]
	v_mfma_f32_16x16x32_bf16 v[88:91], v[156:159], v[216:219], v[88:91]
	v_mfma_f32_16x16x32_bf16 v[80:83], v[176:179], v[216:219], v[80:83]
	v_mfma_f32_16x16x32_bf16 v[72:75], v[156:159], v[224:227], v[72:75]
	v_mfma_f32_16x16x32_bf16 v[64:67], v[176:179], v[224:227], v[64:67]
	s_setprio 0
	s_setprio 1
	v_mfma_f32_16x16x32_bf16 v[124:127], v[180:183], v[196:199], v[124:127]
	v_mfma_f32_16x16x32_bf16 v[116:119], v[188:191], v[196:199], v[116:119]
	v_mfma_f32_16x16x32_bf16 v[108:111], v[180:183], v[204:207], v[108:111]
	v_mfma_f32_16x16x32_bf16 v[100:103], v[188:191], v[204:207], v[100:103]
	v_mfma_f32_16x16x32_bf16 v[92:95], v[180:183], v[212:215], v[92:95]
	v_mfma_f32_16x16x32_bf16 v[84:87], v[188:191], v[212:215], v[84:87]
	v_mfma_f32_16x16x32_bf16 v[76:79], v[180:183], v[220:223], v[76:79]
	v_mfma_f32_16x16x32_bf16 v[68:71], v[188:191], v[220:223], v[68:71]
	v_mfma_f32_16x16x32_bf16 v[124:127], v[184:187], v[200:203], v[124:127]
	v_mfma_f32_16x16x32_bf16 v[116:119], v[192:195], v[200:203], v[116:119]
	v_mfma_f32_16x16x32_bf16 v[108:111], v[184:187], v[208:211], v[108:111]
	v_mfma_f32_16x16x32_bf16 v[100:103], v[192:195], v[208:211], v[100:103]
	v_mfma_f32_16x16x32_bf16 v[92:95], v[184:187], v[216:219], v[92:95]
	v_mfma_f32_16x16x32_bf16 v[84:87], v[192:195], v[216:219], v[84:87]
	v_mfma_f32_16x16x32_bf16 v[76:79], v[184:187], v[224:227], v[76:79]
	v_mfma_f32_16x16x32_bf16 v[68:71], v[192:195], v[224:227], v[68:71]
	s_barrier
; #define PG8_STAGE(bufoff, gbase, voff) do { _Pragma("unroll") for (int _i = 0; _i < 2; ++_i) \
;         __builtin_amdgcn_global_load_lds((const unsigned*)((const char*)(gbase) + (voff)[_i]), (LAS unsigned*)(lds + (bufoff) + ldsw + _i * 8192), 16, 0, 0); } while (0)
; #define PG8_LDA(dst, b, h) do { _Pragma("unroll") for (int m = 0; m < 4; ++m) _Pragma("unroll") for (int k = 0; k < 2; ++k) dst[m][k] = *(const LAS bf16x8*)(lds + PG8_SA(b, h) + aoff + m * 2048 + k * 1024); } while (0)
; #define PG8_MMA(ai, bj, At, Bt) do { __builtin_amdgcn_s_setprio(1); _Pragma("unroll") for (int m = 0; m < 4; ++m) _Pragma("unroll") for (int n = 0; n < 2; ++n) _Pragma("unroll") for (int k = 0; k < 2; ++k) \
;         acc[ai][bj][m][n] = __builtin_amdgcn_mfma_f32_16x16x32_bf16(Bt[n][k], At[m][k], acc[ai][bj][m][n], 0, 0, 0); __builtin_amdgcn_s_setprio(0); } while (0)
; #define PG8_WAIT_V(n) asm volatile("s_waitcnt vmcnt(" #n ")" ::: "memory")
; #define PG8_WAIT_L(n) asm volatile("s_waitcnt lgkmcnt(" #n ")" ::: "memory")
; #define PG8_BAR __builtin_amdgcn_s_barrier()
; #define PG8_SCHED __builtin_amdgcn_sched_barrier(0)
; template <class Epi, bool ALIGN_EPI>
; __device__ __forceinline__ void gemm_phase(LAS unsigned char* lds, const Gemm g, const StaticOrder& S, const Epi& E) {
;     ...
;             PG8_LDA(At, 1, 1); PG8_STAGE(PG8_SB(1, 0), b3, voffB); PG8_STAGE(PG8_SB(1, 1), b3 + hstepB, voffB); PG8_STAGE(PG8_SA(1, 0), a3, voffA);
;             PG8_WAIT_V(8); PG8_WAIT_L(0); PG8_BAR; PG8_MMA(1, 0, At, B0); PG8_MMA(1, 1, At, B1); PG8_BAR; PG8_SCHED;
;         }
	s_setprio 0
	s_add_i32 s42, s71, s49
	v_lshl_add_u64 v[160:161], v[160:161], 0, s[22:23]
	s_mov_b32 m0, s42
	ds_read_b128 v[196:199], v169 offset:49152
	ds_read_b128 v[200:203], v169 offset:50176
	ds_read_b128 v[204:207], v169 offset:51200
	ds_read_b128 v[208:211], v169 offset:52224
	ds_read_b128 v[212:215], v169 offset:53248
	ds_read_b128 v[216:219], v169 offset:54272
	ds_read_b128 v[220:223], v169 offset:55296
	ds_read_b128 v[224:227], v169 offset:56320
	global_load_lds_dwordx4 v[160:161], off
	s_add_i32 m0, s42, 0x2000
	s_add_u32 s40, s40, 0x80080
	v_lshl_add_u64 v[160:161], v[228:229], 0, s[22:23]
	s_addc_u32 s41, s41, 0
	s_add_i32 s42, s73, s49
	global_load_lds_dwordx4 v[160:161], off
	v_lshl_add_u64 v[160:161], s[40:41], 0, v[130:131]
	s_mov_b32 m0, s42
	s_nop 0
	global_load_lds_dwordx4 v[160:161], off
	v_lshl_add_u64 v[160:161], s[40:41], 0, v[134:135]
	s_add_i32 m0, s42, 0x2000
	s_nop 0
	global_load_lds_dwordx4 v[160:161], off
	v_lshl_add_u64 v[160:161], v[230:231], 0, s[22:23]
	s_mov_b32 m0, s56
	s_nop 0
	global_load_lds_dwordx4 v[160:161], off
	v_lshl_add_u64 v[160:161], v[232:233], 0, s[22:23]
	s_mov_b32 m0, s57
	s_nop 0
	global_load_lds_dwordx4 v[160:161], off
	s_waitcnt vmcnt(8)
	s_waitcnt lgkmcnt(0)
	s_setprio 1
	s_barrier
	v_mfma_f32_16x16x32_bf16 v[56:59], v[152:155], v[196:199], v[56:59]
	v_mfma_f32_16x16x32_bf16 v[48:51], v[172:175], v[196:199], v[48:51]
	v_mfma_f32_16x16x32_bf16 v[40:43], v[152:155], v[204:207], v[40:43]
	v_mfma_f32_16x16x32_bf16 v[32:35], v[172:175], v[204:207], v[32:35]
	v_mfma_f32_16x16x32_bf16 v[24:27], v[152:155], v[212:215], v[24:27]
	v_mfma_f32_16x16x32_bf16 v[16:19], v[172:175], v[212:215], v[16:19]
	v_mfma_f32_16x16x32_bf16 v[8:11], v[152:155], v[220:223], v[8:11]
	v_mfma_f32_16x16x32_bf16 v[0:3], v[172:175], v[220:223], v[0:3]
	v_mfma_f32_16x16x32_bf16 v[56:59], v[156:159], v[200:203], v[56:59]
	v_mfma_f32_16x16x32_bf16 v[48:51], v[176:179], v[200:203], v[48:51]
	v_mfma_f32_16x16x32_bf16 v[40:43], v[156:159], v[208:211], v[40:43]
	v_mfma_f32_16x16x32_bf16 v[32:35], v[176:179], v[208:211], v[32:35]
	v_mfma_f32_16x16x32_bf16 v[24:27], v[156:159], v[216:219], v[24:27]
	v_mfma_f32_16x16x32_bf16 v[16:19], v[176:179], v[216:219], v[16:19]
	v_mfma_f32_16x16x32_bf16 v[8:11], v[156:159], v[224:227], v[8:11]
	v_mfma_f32_16x16x32_bf16 v[0:3], v[176:179], v[224:227], v[0:3]
	s_setprio 0
	s_setprio 1
	v_mfma_f32_16x16x32_bf16 v[60:63], v[180:183], v[196:199], v[60:63]
	v_mfma_f32_16x16x32_bf16 v[52:55], v[188:191], v[196:199], v[52:55]
	v_mfma_f32_16x16x32_bf16 v[44:47], v[180:183], v[204:207], v[44:47]
	v_mfma_f32_16x16x32_bf16 v[36:39], v[188:191], v[204:207], v[36:39]
	v_mfma_f32_16x16x32_bf16 v[28:31], v[180:183], v[212:215], v[28:31]
	v_mfma_f32_16x16x32_bf16 v[20:23], v[188:191], v[212:215], v[20:23]
	v_mfma_f32_16x16x32_bf16 v[12:15], v[180:183], v[220:223], v[12:15]
	v_mfma_f32_16x16x32_bf16 v[4:7], v[188:191], v[220:223], v[4:7]
	v_mfma_f32_16x16x32_bf16 v[60:63], v[184:187], v[200:203], v[60:63]
	v_mfma_f32_16x16x32_bf16 v[52:55], v[192:195], v[200:203], v[52:55]
	v_mfma_f32_16x16x32_bf16 v[44:47], v[184:187], v[208:211], v[44:47]
	v_mfma_f32_16x16x32_bf16 v[36:39], v[192:195], v[208:211], v[36:39]
	v_mfma_f32_16x16x32_bf16 v[28:31], v[184:187], v[216:219], v[28:31]
	v_mfma_f32_16x16x32_bf16 v[20:23], v[192:195], v[216:219], v[20:23]
	v_mfma_f32_16x16x32_bf16 v[12:15], v[184:187], v[224:227], v[12:15]
	v_mfma_f32_16x16x32_bf16 v[4:7], v[192:195], v[224:227], v[4:7]
	s_barrier
	s_setprio 0
	s_add_i32 s45, s45, 2
	s_add_u32 s35, s35, 0x100
	s_addc_u32 s44, s44, 0
	s_add_u32 s8, s8, 0x100
	s_addc_u32 s9, s9, 0
	s_cmp_gt_u32 s45, 29
	s_cbranch_scc0 .LBB0_459
	s_and_b64 vcc, exec, s[24:25]
	s_cbranch_vccz .LBB0_462
	s_barrier

; #define PG8_STAGE(bufoff, gbase, voff) do { _Pragma("unroll") for (int _i = 0; _i < 2; ++_i) \
;         __builtin_amdgcn_global_load_lds((const unsigned*)((const char*)(gbase) + (voff)[_i]), (LAS unsigned*)(lds + (bufoff) + ldsw + _i * 8192), 16, 0, 0); } while (0)
; #define PG8_LDA(dst, b, h) do { _Pragma("unroll") for (int m = 0; m < 4; ++m) _Pragma("unroll") for (int k = 0; k < 2; ++k) dst[m][k] = *(const LAS bf16x8*)(lds + PG8_SA(b, h) + aoff + m * 2048 + k * 1024); } while (0)
; #define PG8_LDB(dst, b, h) do { _Pragma("unroll") for (int n = 0; n < 2; ++n) _Pragma("unroll") for (int k = 0; k < 2; ++k) dst[n][k] = *(const LAS bf16x8*)(lds + PG8_SB(b, h) + boff + n * 2048 + k * 1024); } while (0)
; #define PG8_MMA(ai, bj, At, Bt) do { __builtin_amdgcn_s_setprio(1); _Pragma("unroll") for (int m = 0; m < 4; ++m) _Pragma("unroll") for (int n = 0; n < 2; ++n) _Pragma("unroll") for (int k = 0; k < 2; ++k) \
;         acc[ai][bj][m][n] = __builtin_amdgcn_mfma_f32_16x16x32_bf16(Bt[n][k], At[m][k], acc[ai][bj][m][n], 0, 0, 0); __builtin_amdgcn_s_setprio(0); } while (0)
; #define PG8_WAIT_V(n) asm volatile("s_waitcnt vmcnt(" #n ")" ::: "memory")
; #define PG8_WAIT_L(n) asm volatile("s_waitcnt lgkmcnt(" #n ")" ::: "memory")
; #define PG8_BAR __builtin_amdgcn_s_barrier()
; #define PG8_SCHED __builtin_amdgcn_sched_barrier(0)
; template <class Epi, bool ALIGN_EPI>
; __device__ __forceinline__ void gemm_phase(LAS unsigned char* lds, const Gemm g, const StaticOrder& S, const Epi& E) {
;     ...
;             PG8_LDB(B0, 0, 0); PG8_LDB(B1, 0, 1); PG8_SCHED; PG8_LDA(At, 0, 0); PG8_STAGE(PG8_SA(1, 1), a1 + hstepA, voffA);
;             PG8_WAIT_V(8); PG8_WAIT_L(0); PG8_BAR; PG8_MMA(0, 0, At, B0); PG8_MMA(0, 1, At, B1); PG8_BAR; PG8_SCHED;
;             PG8_LDA(At, 0, 1); PG8_STAGE(PG8_SB(0, 0), b2, voffB); PG8_STAGE(PG8_SB(0, 1), b2 + hstepB, voffB); PG8_STAGE(PG8_SA(0, 0), a2, voffA);
;             PG8_WAIT_V(8); PG8_WAIT_L(0); PG8_BAR; PG8_MMA(1, 0, At, B0); PG8_MMA(1, 1, At, B1); PG8_BAR; PG8_SCHED;
.LBB0_817:
	ds_read_b128 v[152:155], v149
	ds_read_b128 v[156:159], v149 offset:1024
	ds_read_b128 v[160:163], v149 offset:2048
	ds_read_b128 v[168:171], v149 offset:3072
	ds_read_b128 v[172:175], v150
	ds_read_b128 v[176:179], v150 offset:1024
	ds_read_b128 v[180:183], v150 offset:2048
	ds_read_b128 v[184:187], v150 offset:3072
	s_add_u32 s24, s22, 0xfff80080
	s_addc_u32 s25, s23, -1
	s_cmp_eq_u32 s56, 12
	s_cselect_b32 s27, s15, s25
	s_cselect_b32 s26, s52, s24
	s_cselect_b32 s25, s13, s55
	s_cselect_b32 s24, s53, s54
	v_lshl_add_u64 v[144:145], s[22:23], 0, v[138:139]
	s_add_i32 m0, s21, 0xc000
	ds_read_b128 v[188:191], v151
	ds_read_b128 v[192:195], v151 offset:1024
	ds_read_b128 v[196:199], v151 offset:2048
	ds_read_b128 v[200:203], v151 offset:3072
	ds_read_b128 v[204:207], v151 offset:4096
	ds_read_b128 v[208:211], v151 offset:5120
	ds_read_b128 v[212:215], v151 offset:6144
	ds_read_b128 v[216:219], v151 offset:7168
	global_load_lds_dwordx4 v[144:145], off
	v_lshl_add_u64 v[144:145], s[22:23], 0, v[136:137]
	s_add_i32 m0, s21, 0xe000
	s_nop 0
	global_load_lds_dwordx4 v[144:145], off
	s_waitcnt vmcnt(8)
	s_waitcnt lgkmcnt(0)
	s_setprio 1
	s_barrier
	v_mfma_f32_16x16x32_bf16 v[124:127], v[152:155], v[188:191], v[124:127]
	v_mfma_f32_16x16x32_bf16 v[120:123], v[160:163], v[188:191], v[120:123]
	v_mfma_f32_16x16x32_bf16 v[108:111], v[152:155], v[196:199], v[108:111]
	v_mfma_f32_16x16x32_bf16 v[104:107], v[160:163], v[196:199], v[104:107]
	v_mfma_f32_16x16x32_bf16 v[92:95], v[152:155], v[204:207], v[92:95]
	v_mfma_f32_16x16x32_bf16 v[88:91], v[160:163], v[204:207], v[88:91]
	v_mfma_f32_16x16x32_bf16 v[76:79], v[152:155], v[212:215], v[76:79]
	v_mfma_f32_16x16x32_bf16 v[72:75], v[160:163], v[212:215], v[72:75]
	v_mfma_f32_16x16x32_bf16 v[124:127], v[156:159], v[192:195], v[124:127]
	v_mfma_f32_16x16x32_bf16 v[120:123], v[168:171], v[192:195], v[120:123]
	v_mfma_f32_16x16x32_bf16 v[108:111], v[156:159], v[200:203], v[108:111]
	v_mfma_f32_16x16x32_bf16 v[104:107], v[168:171], v[200:203], v[104:107]
	v_mfma_f32_16x16x32_bf16 v[92:95], v[156:159], v[208:211], v[92:95]
	v_mfma_f32_16x16x32_bf16 v[88:91], v[168:171], v[208:211], v[88:91]
	v_mfma_f32_16x16x32_bf16 v[76:79], v[156:159], v[216:219], v[76:79]
	v_mfma_f32_16x16x32_bf16 v[72:75], v[168:171], v[216:219], v[72:75]
	s_setprio 0
	s_setprio 1
	v_mfma_f32_16x16x32_bf16 v[116:119], v[172:175], v[188:191], v[116:119]
	v_mfma_f32_16x16x32_bf16 v[112:115], v[180:183], v[188:191], v[112:115]
	v_mfma_f32_16x16x32_bf16 v[100:103], v[172:175], v[196:199], v[100:103]
	v_mfma_f32_16x16x32_bf16 v[96:99], v[180:183], v[196:199], v[96:99]
	v_mfma_f32_16x16x32_bf16 v[84:87], v[172:175], v[204:207], v[84:87]
	v_mfma_f32_16x16x32_bf16 v[80:83], v[180:183], v[204:207], v[80:83]
	v_mfma_f32_16x16x32_bf16 v[68:71], v[172:175], v[212:215], v[68:71]
	v_mfma_f32_16x16x32_bf16 v[64:67], v[180:183], v[212:215], v[64:67]
	v_mfma_f32_16x16x32_bf16 v[116:119], v[176:179], v[192:195], v[116:119]
	v_mfma_f32_16x16x32_bf16 v[112:115], v[184:187], v[192:195], v[112:115]
	v_mfma_f32_16x16x32_bf16 v[100:103], v[176:179], v[200:203], v[100:103]
	v_mfma_f32_16x16x32_bf16 v[96:99], v[184:187], v[200:203], v[96:99]
	v_mfma_f32_16x16x32_bf16 v[84:87], v[176:179], v[208:211], v[84:87]
	v_mfma_f32_16x16x32_bf16 v[80:83], v[184:187], v[208:211], v[80:83]
	v_mfma_f32_16x16x32_bf16 v[68:71], v[176:179], v[216:219], v[68:71]
	v_mfma_f32_16x16x32_bf16 v[64:67], v[184:187], v[216:219], v[64:67]
	s_barrier
	s_setprio 0
	s_add_i32 s57, s45, s34
	v_lshl_add_u64 v[144:145], s[24:25], 0, v[132:133]
	s_mov_b32 m0, s57
	ds_read_b128 v[188:191], v151 offset:16384
	ds_read_b128 v[192:195], v151 offset:17408
	ds_read_b128 v[196:199], v151 offset:18432
	ds_read_b128 v[200:203], v151 offset:19456
	ds_read_b128 v[204:207], v151 offset:20480
	ds_read_b128 v[208:211], v151 offset:21504
	ds_read_b128 v[212:215], v151 offset:22528
	ds_read_b128 v[216:219], v151 offset:23552
	global_load_lds_dwordx4 v[144:145], off
	s_add_i32 m0, s57, 0x2000
	s_add_u32 s58, s24, 0x40000
	v_lshl_add_u64 v[164:165], s[24:25], 0, v[128:129]
	s_addc_u32 s59, s25, 0
	s_add_i32 s57, s46, s34
	global_load_lds_dwordx4 v[164:165], off
	v_lshl_add_u64 v[220:221], s[58:59], 0, v[132:133]
	s_mov_b32 m0, s57
	v_lshl_add_u64 v[222:223], s[26:27], 0, v[130:131]
	global_load_lds_dwordx4 v[220:221], off
	v_lshl_add_u64 v[220:221], s[58:59], 0, v[128:129]
	s_add_i32 m0, s57, 0x2000
	s_nop 0
	global_load_lds_dwordx4 v[220:221], off
	v_lshl_add_u64 v[220:221], s[26:27], 0, v[134:135]
	s_mov_b32 m0, s21
	s_nop 0
	global_load_lds_dwordx4 v[220:221], off
	s_mov_b32 m0, s37
	s_nop 0
	global_load_lds_dwordx4 v[222:223], off
	s_waitcnt vmcnt(8)
	s_waitcnt lgkmcnt(0)
	s_setprio 1
	s_barrier
; #define PG8_STAGE(bufoff, gbase, voff) do { _Pragma("unroll") for (int _i = 0; _i < 2; ++_i) \
;         __builtin_amdgcn_global_load_lds((const unsigned*)((const char*)(gbase) + (voff)[_i]), (LAS unsigned*)(lds + (bufoff) + ldsw + _i * 8192), 16, 0, 0); } while (0)
; #define PG8_LDA(dst, b, h) do { _Pragma("unroll") for (int m = 0; m < 4; ++m) _Pragma("unroll") for (int k = 0; k < 2; ++k) dst[m][k] = *(const LAS bf16x8*)(lds + PG8_SA(b, h) + aoff + m * 2048 + k * 1024); } while (0)
; #define PG8_LDB(dst, b, h) do { _Pragma("unroll") for (int n = 0; n < 2; ++n) _Pragma("unroll") for (int k = 0; k < 2; ++k) dst[n][k] = *(const LAS bf16x8*)(lds + PG8_SB(b, h) + boff + n * 2048 + k * 1024); } while (0)
; #define PG8_MMA(ai, bj, At, Bt) do { __builtin_amdgcn_s_setprio(1); _Pragma("unroll") for (int m = 0; m < 4; ++m) _Pragma("unroll") for (int n = 0; n < 2; ++n) _Pragma("unroll") for (int k = 0; k < 2; ++k) \
;         acc[ai][bj][m][n] = __builtin_amdgcn_mfma_f32_16x16x32_bf16(Bt[n][k], At[m][k], acc[ai][bj][m][n], 0, 0, 0); __builtin_amdgcn_s_setprio(0); } while (0)
; #define PG8_WAIT_V(n) asm volatile("s_waitcnt vmcnt(" #n ")" ::: "memory")
; #define PG8_WAIT_L(n) asm volatile("s_waitcnt lgkmcnt(" #n ")" ::: "memory")
; #define PG8_BAR __builtin_amdgcn_s_barrier()
; #define PG8_SCHED __builtin_amdgcn_sched_barrier(0)
; template <class Epi, bool ALIGN_EPI>
; __device__ __forceinline__ void gemm_phase(LAS unsigned char* lds, const Gemm g, const StaticOrder& S, const Epi& E) {
;     ...
;             PG8_WAIT_V(8); PG8_WAIT_L(0); PG8_BAR; PG8_MMA(1, 0, At, B0); PG8_MMA(1, 1, At, B1); PG8_BAR; PG8_SCHED;
;             PG8_LDB(B0, 1, 0); PG8_LDB(B1, 1, 1); PG8_SCHED; PG8_LDA(At, 1, 0); PG8_STAGE(PG8_SA(0, 1), a2 + hstepA, voffA);
;             PG8_WAIT_V(8); PG8_WAIT_L(0); PG8_BAR; PG8_MMA(0, 0, At, B0); PG8_MMA(0, 1, At, B1); PG8_BAR; PG8_SCHED;
	v_mfma_f32_16x16x32_bf16 v[60:63], v[152:155], v[188:191], v[60:63]
	v_mfma_f32_16x16x32_bf16 v[56:59], v[160:163], v[188:191], v[56:59]
	v_mfma_f32_16x16x32_bf16 v[44:47], v[152:155], v[196:199], v[44:47]
	v_mfma_f32_16x16x32_bf16 v[40:43], v[160:163], v[196:199], v[40:43]
	v_mfma_f32_16x16x32_bf16 v[28:31], v[152:155], v[204:207], v[28:31]
	v_mfma_f32_16x16x32_bf16 v[24:27], v[160:163], v[204:207], v[24:27]
	v_mfma_f32_16x16x32_bf16 v[12:15], v[152:155], v[212:215], v[12:15]
	v_mfma_f32_16x16x32_bf16 v[8:11], v[160:163], v[212:215], v[8:11]
	v_mfma_f32_16x16x32_bf16 v[60:63], v[156:159], v[192:195], v[60:63]
	v_mfma_f32_16x16x32_bf16 v[56:59], v[168:171], v[192:195], v[56:59]
	v_mfma_f32_16x16x32_bf16 v[44:47], v[156:159], v[200:203], v[44:47]
	v_mfma_f32_16x16x32_bf16 v[40:43], v[168:171], v[200:203], v[40:43]
	v_mfma_f32_16x16x32_bf16 v[28:31], v[156:159], v[208:211], v[28:31]
	v_mfma_f32_16x16x32_bf16 v[24:27], v[168:171], v[208:211], v[24:27]
	v_mfma_f32_16x16x32_bf16 v[12:15], v[156:159], v[216:219], v[12:15]
	v_mfma_f32_16x16x32_bf16 v[8:11], v[168:171], v[216:219], v[8:11]
	s_setprio 0
	s_setprio 1
	v_mfma_f32_16x16x32_bf16 v[52:55], v[172:175], v[188:191], v[52:55]
	v_mfma_f32_16x16x32_bf16 v[48:51], v[180:183], v[188:191], v[48:51]
	v_mfma_f32_16x16x32_bf16 v[36:39], v[172:175], v[196:199], v[36:39]
	v_mfma_f32_16x16x32_bf16 v[32:35], v[180:183], v[196:199], v[32:35]
	v_mfma_f32_16x16x32_bf16 v[20:23], v[172:175], v[204:207], v[20:23]
	v_mfma_f32_16x16x32_bf16 v[16:19], v[180:183], v[204:207], v[16:19]
	v_mfma_f32_16x16x32_bf16 v[4:7], v[172:175], v[212:215], v[4:7]
	v_mfma_f32_16x16x32_bf16 v[0:3], v[180:183], v[212:215], v[0:3]
	v_mfma_f32_16x16x32_bf16 v[52:55], v[176:179], v[192:195], v[52:55]
	v_mfma_f32_16x16x32_bf16 v[48:51], v[184:187], v[192:195], v[48:51]
	v_mfma_f32_16x16x32_bf16 v[36:39], v[176:179], v[200:203], v[36:39]
	v_mfma_f32_16x16x32_bf16 v[32:35], v[184:187], v[200:203], v[32:35]
	v_mfma_f32_16x16x32_bf16 v[20:23], v[176:179], v[208:211], v[20:23]
	v_mfma_f32_16x16x32_bf16 v[16:19], v[184:187], v[208:211], v[16:19]
	v_mfma_f32_16x16x32_bf16 v[4:7], v[176:179], v[216:219], v[4:7]
	v_mfma_f32_16x16x32_bf16 v[0:3], v[184:187], v[216:219], v[0:3]
	s_barrier
	s_setprio 0
	s_add_i32 s57, 0, 0x18000
	s_add_i32 s58, 0, 0x1c000
	v_add_u32_e32 v168, s57, v147
	v_add_u32_e32 v184, s58, v147
	ds_read_b128 v[152:155], v168
	ds_read_b128 v[156:159], v168 offset:1024
	ds_read_b128 v[160:163], v168 offset:2048
	ds_read_b128 v[168:171], v168 offset:3072
	ds_read_b128 v[172:175], v184
	ds_read_b128 v[176:179], v184 offset:1024
	ds_read_b128 v[180:183], v184 offset:2048
	ds_read_b128 v[184:187], v184 offset:3072
	s_add_u32 s26, s26, 0x80000
	s_addc_u32 s27, s27, 0
	s_mov_b32 m0, s38
	v_lshl_add_u64 v[224:225], s[26:27], 0, v[134:135]
	ds_read_b128 v[188:191], v151 offset:32768
	ds_read_b128 v[192:195], v151 offset:33792
	ds_read_b128 v[196:199], v151 offset:34816
	ds_read_b128 v[200:203], v151 offset:35840
	ds_read_b128 v[204:207], v151 offset:36864
	ds_read_b128 v[208:211], v151 offset:37888
	ds_read_b128 v[212:215], v151 offset:38912
	ds_read_b128 v[216:219], v151 offset:39936
	global_load_lds_dwordx4 v[224:225], off
	v_lshl_add_u64 v[224:225], s[26:27], 0, v[130:131]
	s_mov_b32 m0, s39
	s_nop 0
	global_load_lds_dwordx4 v[224:225], off
	s_waitcnt vmcnt(8)
	s_waitcnt lgkmcnt(0)
	s_setprio 1
	s_barrier
	v_mfma_f32_16x16x32_bf16 v[124:127], v[152:155], v[188:191], v[124:127]
	v_mfma_f32_16x16x32_bf16 v[120:123], v[160:163], v[188:191], v[120:123]
	v_mfma_f32_16x16x32_bf16 v[108:111], v[152:155], v[196:199], v[108:111]
	v_mfma_f32_16x16x32_bf16 v[104:107], v[160:163], v[196:199], v[104:107]
	v_mfma_f32_16x16x32_bf16 v[92:95], v[152:155], v[204:207], v[92:95]
	v_mfma_f32_16x16x32_bf16 v[88:91], v[160:163], v[204:207], v[88:91]
	v_mfma_f32_16x16x32_bf16 v[76:79], v[152:155], v[212:215], v[76:79]
	v_mfma_f32_16x16x32_bf16 v[72:75], v[160:163], v[212:215], v[72:75]
	v_mfma_f32_16x16x32_bf16 v[124:127], v[156:159], v[192:195], v[124:127]
	v_mfma_f32_16x16x32_bf16 v[120:123], v[168:171], v[192:195], v[120:123]
	v_mfma_f32_16x16x32_bf16 v[108:111], v[156:159], v[200:203], v[108:111]
	v_mfma_f32_16x16x32_bf16 v[104:107], v[168:171], v[200:203], v[104:107]
	v_mfma_f32_16x16x32_bf16 v[92:95], v[156:159], v[208:211], v[92:95]
	v_mfma_f32_16x16x32_bf16 v[88:91], v[168:171], v[208:211], v[88:91]
	v_mfma_f32_16x16x32_bf16 v[76:79], v[156:159], v[216:219], v[76:79]
	v_mfma_f32_16x16x32_bf16 v[72:75], v[168:171], v[216:219], v[72:75]
	s_setprio 0
	s_setprio 1
	v_mfma_f32_16x16x32_bf16 v[116:119], v[172:175], v[188:191], v[116:119]
	v_mfma_f32_16x16x32_bf16 v[112:115], v[180:183], v[188:191], v[112:115]
	v_mfma_f32_16x16x32_bf16 v[100:103], v[172:175], v[196:199], v[100:103]
	v_mfma_f32_16x16x32_bf16 v[96:99], v[180:183], v[196:199], v[96:99]
	v_mfma_f32_16x16x32_bf16 v[84:87], v[172:175], v[204:207], v[84:87]
	v_mfma_f32_16x16x32_bf16 v[80:83], v[180:183], v[204:207], v[80:83]
	v_mfma_f32_16x16x32_bf16 v[68:71], v[172:175], v[212:215], v[68:71]
	v_mfma_f32_16x16x32_bf16 v[64:67], v[180:183], v[212:215], v[64:67]
	v_mfma_f32_16x16x32_bf16 v[116:119], v[176:179], v[192:195], v[116:119]
	v_mfma_f32_16x16x32_bf16 v[112:115], v[184:187], v[192:195], v[112:115]
	v_mfma_f32_16x16x32_bf16 v[100:103], v[176:179], v[200:203], v[100:103]
	v_mfma_f32_16x16x32_bf16 v[96:99], v[184:187], v[200:203], v[96:99]
	v_mfma_f32_16x16x32_bf16 v[84:87], v[176:179], v[208:211], v[84:87]
	v_mfma_f32_16x16x32_bf16 v[80:83], v[184:187], v[208:211], v[80:83]
	v_mfma_f32_16x16x32_bf16 v[68:71], v[176:179], v[216:219], v[68:71]
	v_mfma_f32_16x16x32_bf16 v[64:67], v[184:187], v[216:219], v[64:67]
	s_barrier
; #define PG8_STAGE(bufoff, gbase, voff) do { _Pragma("unroll") for (int _i = 0; _i < 2; ++_i) \
;         __builtin_amdgcn_global_load_lds((const unsigned*)((const char*)(gbase) + (voff)[_i]), (LAS unsigned*)(lds + (bufoff) + ldsw + _i * 8192), 16, 0, 0); } while (0)
; #define PG8_LDA(dst, b, h) do { _Pragma("unroll") for (int m = 0; m < 4; ++m) _Pragma("unroll") for (int k = 0; k < 2; ++k) dst[m][k] = *(const LAS bf16x8*)(lds + PG8_SA(b, h) + aoff + m * 2048 + k * 1024); } while (0)
; #define PG8_MMA(ai, bj, At, Bt) do { __builtin_amdgcn_s_setprio(1); _Pragma("unroll") for (int m = 0; m < 4; ++m) _Pragma("unroll") for (int n = 0; n < 2; ++n) _Pragma("unroll") for (int k = 0; k < 2; ++k) \
;         acc[ai][bj][m][n] = __builtin_amdgcn_mfma_f32_16x16x32_bf16(Bt[n][k], At[m][k], acc[ai][bj][m][n], 0, 0, 0); __builtin_amdgcn_s_setprio(0); } while (0)
; #define PG8_WAIT_V(n) asm volatile("s_waitcnt vmcnt(" #n ")" ::: "memory")
; #define PG8_WAIT_L(n) asm volatile("s_waitcnt lgkmcnt(" #n ")" ::: "memory")
; #define PG8_BAR __builtin_amdgcn_s_barrier()
; #define PG8_SCHED __builtin_amdgcn_sched_barrier(0)
; template <class Epi, bool ALIGN_EPI>
; __device__ __forceinline__ void gemm_phase(LAS unsigned char* lds, const Gemm g, const StaticOrder& S, const Epi& E) {
;     ...
;             PG8_LDA(At, 1, 1); PG8_STAGE(PG8_SB(1, 0), b3, voffB); PG8_STAGE(PG8_SB(1, 1), b3 + hstepB, voffB); PG8_STAGE(PG8_SA(1, 0), a3, voffA);
;             PG8_WAIT_V(8); PG8_WAIT_L(0); PG8_BAR; PG8_MMA(1, 0, At, B0); PG8_MMA(1, 1, At, B1); PG8_BAR; PG8_SCHED;
;         }
	s_setprio 0
	s_add_i32 s26, s57, s34
	v_lshl_add_u64 v[144:145], v[144:145], 0, s[8:9]
	s_mov_b32 m0, s26
	ds_read_b128 v[188:191], v151 offset:49152
	ds_read_b128 v[192:195], v151 offset:50176
	ds_read_b128 v[196:199], v151 offset:51200
	ds_read_b128 v[200:203], v151 offset:52224
	ds_read_b128 v[204:207], v151 offset:53248
	ds_read_b128 v[208:211], v151 offset:54272
	ds_read_b128 v[212:215], v151 offset:55296
	ds_read_b128 v[216:219], v151 offset:56320
	global_load_lds_dwordx4 v[144:145], off
	s_add_i32 m0, s26, 0x2000
	s_add_u32 s24, s24, 0x40080
	v_lshl_add_u64 v[144:145], v[164:165], 0, s[8:9]
	s_addc_u32 s25, s25, 0
	s_add_i32 s26, s58, s34
	global_load_lds_dwordx4 v[144:145], off
	v_lshl_add_u64 v[144:145], s[24:25], 0, v[132:133]
	s_mov_b32 m0, s26
	s_nop 0
	global_load_lds_dwordx4 v[144:145], off
	v_lshl_add_u64 v[144:145], s[24:25], 0, v[128:129]
	s_add_i32 m0, s26, 0x2000
	s_nop 0
	global_load_lds_dwordx4 v[144:145], off
	v_lshl_add_u64 v[144:145], v[220:221], 0, s[8:9]
	s_mov_b32 m0, s40
	s_nop 0
	global_load_lds_dwordx4 v[144:145], off
	v_lshl_add_u64 v[144:145], v[222:223], 0, s[8:9]
	s_mov_b32 m0, s41
	s_nop 0
	global_load_lds_dwordx4 v[144:145], off
	s_waitcnt vmcnt(8)
	s_waitcnt lgkmcnt(0)
	s_setprio 1
	s_barrier
	v_mfma_f32_16x16x32_bf16 v[60:63], v[152:155], v[188:191], v[60:63]
	v_mfma_f32_16x16x32_bf16 v[56:59], v[160:163], v[188:191], v[56:59]
	v_mfma_f32_16x16x32_bf16 v[44:47], v[152:155], v[196:199], v[44:47]
	v_mfma_f32_16x16x32_bf16 v[40:43], v[160:163], v[196:199], v[40:43]
	v_mfma_f32_16x16x32_bf16 v[28:31], v[152:155], v[204:207], v[28:31]
	v_mfma_f32_16x16x32_bf16 v[24:27], v[160:163], v[204:207], v[24:27]
	v_mfma_f32_16x16x32_bf16 v[12:15], v[152:155], v[212:215], v[12:15]
	v_mfma_f32_16x16x32_bf16 v[8:11], v[160:163], v[212:215], v[8:11]
	v_mfma_f32_16x16x32_bf16 v[60:63], v[156:159], v[192:195], v[60:63]
	v_mfma_f32_16x16x32_bf16 v[56:59], v[168:171], v[192:195], v[56:59]
	v_mfma_f32_16x16x32_bf16 v[44:47], v[156:159], v[200:203], v[44:47]
	v_mfma_f32_16x16x32_bf16 v[40:43], v[168:171], v[200:203], v[40:43]
	v_mfma_f32_16x16x32_bf16 v[28:31], v[156:159], v[208:211], v[28:31]
	v_mfma_f32_16x16x32_bf16 v[24:27], v[168:171], v[208:211], v[24:27]
	v_mfma_f32_16x16x32_bf16 v[12:15], v[156:159], v[216:219], v[12:15]
	v_mfma_f32_16x16x32_bf16 v[8:11], v[168:171], v[216:219], v[8:11]
	s_setprio 0
	s_setprio 1
	v_mfma_f32_16x16x32_bf16 v[52:55], v[172:175], v[188:191], v[52:55]
	v_mfma_f32_16x16x32_bf16 v[48:51], v[180:183], v[188:191], v[48:51]
	v_mfma_f32_16x16x32_bf16 v[36:39], v[172:175], v[196:199], v[36:39]
	v_mfma_f32_16x16x32_bf16 v[32:35], v[180:183], v[196:199], v[32:35]
	v_mfma_f32_16x16x32_bf16 v[20:23], v[172:175], v[204:207], v[20:23]
	v_mfma_f32_16x16x32_bf16 v[16:19], v[180:183], v[204:207], v[16:19]
	v_mfma_f32_16x16x32_bf16 v[4:7], v[172:175], v[212:215], v[4:7]
	v_mfma_f32_16x16x32_bf16 v[0:3], v[180:183], v[212:215], v[0:3]
	v_mfma_f32_16x16x32_bf16 v[52:55], v[176:179], v[192:195], v[52:55]
	v_mfma_f32_16x16x32_bf16 v[48:51], v[184:187], v[192:195], v[48:51]
	v_mfma_f32_16x16x32_bf16 v[36:39], v[176:179], v[200:203], v[36:39]
	v_mfma_f32_16x16x32_bf16 v[32:35], v[184:187], v[200:203], v[32:35]
	v_mfma_f32_16x16x32_bf16 v[20:23], v[176:179], v[208:211], v[20:23]
	v_mfma_f32_16x16x32_bf16 v[16:19], v[184:187], v[208:211], v[16:19]
	v_mfma_f32_16x16x32_bf16 v[4:7], v[176:179], v[216:219], v[4:7]
	v_mfma_f32_16x16x32_bf16 v[0:3], v[184:187], v[216:219], v[0:3]
	s_barrier
	s_setprio 0
	s_add_i32 s56, s56, 2
	s_add_u32 s54, s54, 0x100
	s_addc_u32 s55, s55, 0
	s_add_u32 s22, s22, 0x100
	s_addc_u32 s23, s23, 0
	s_cmp_gt_u32 s56, 13
	s_cbranch_scc0 .LBB0_817
	s_and_b64 vcc, exec, s[10:11]
	s_cbranch_vccz .LBB0_820
	s_barrier

; #define PG8_STAGE(bufoff, gbase, voff) do { _Pragma("unroll") for (int _i = 0; _i < 2; ++_i) \
;         __builtin_amdgcn_global_load_lds((const unsigned*)((const char*)(gbase) + (voff)[_i]), (LAS unsigned*)(lds + (bufoff) + ldsw + _i * 8192), 16, 0, 0); } while (0)
; #define PG8_LDA(dst, b, h) do { _Pragma("unroll") for (int m = 0; m < 4; ++m) _Pragma("unroll") for (int k = 0; k < 2; ++k) dst[m][k] = *(const LAS bf16x8*)(lds + PG8_SA(b, h) + aoff + m * 2048 + k * 1024); } while (0)
; #define PG8_LDB(dst, b, h) do { _Pragma("unroll") for (int n = 0; n < 2; ++n) _Pragma("unroll") for (int k = 0; k < 2; ++k) dst[n][k] = *(const LAS bf16x8*)(lds + PG8_SB(b, h) + boff + n * 2048 + k * 1024); } while (0)
; #define PG8_MMA(ai, bj, At, Bt) do { __builtin_amdgcn_s_setprio(1); _Pragma("unroll") for (int m = 0; m < 4; ++m) _Pragma("unroll") for (int n = 0; n < 2; ++n) _Pragma("unroll") for (int k = 0; k < 2; ++k) \
;         acc[ai][bj][m][n] = __builtin_amdgcn_mfma_f32_16x16x32_bf16(Bt[n][k], At[m][k], acc[ai][bj][m][n], 0, 0, 0); __builtin_amdgcn_s_setprio(0); } while (0)
; #define PG8_WAIT_V(n) asm volatile("s_waitcnt vmcnt(" #n ")" ::: "memory")
; #define PG8_WAIT_L(n) asm volatile("s_waitcnt lgkmcnt(" #n ")" ::: "memory")
; #define PG8_BAR __builtin_amdgcn_s_barrier()
; #define PG8_SCHED __builtin_amdgcn_sched_barrier(0)
; template <class Epi, bool ALIGN_EPI>
; __device__ __forceinline__ void gemm_phase(LAS unsigned char* lds, const Gemm g, const StaticOrder& S, const Epi& E) {
;     ...
;             PG8_LDB(B0, 0, 0); PG8_LDB(B1, 0, 1); PG8_SCHED; PG8_LDA(At, 0, 0); PG8_STAGE(PG8_SA(1, 1), a1 + hstepA, voffA);
;             PG8_WAIT_V(8); PG8_WAIT_L(0); PG8_BAR; PG8_MMA(0, 0, At, B0); PG8_MMA(0, 1, At, B1); PG8_BAR; PG8_SCHED;
;             PG8_LDA(At, 0, 1); PG8_STAGE(PG8_SB(0, 0), b2, voffB); PG8_STAGE(PG8_SB(0, 1), b2 + hstepB, voffB); PG8_STAGE(PG8_SA(0, 0), a2, voffA);
;             PG8_WAIT_V(8); PG8_WAIT_L(0); PG8_BAR; PG8_MMA(1, 0, At, B0); PG8_MMA(1, 1, At, B1); PG8_BAR; PG8_SCHED;
.LBB0_1082:
	ds_read_b128 v[64:67], v169
	ds_read_b128 v[72:75], v169 offset:1024
	ds_read_b128 v[76:79], v169 offset:2048
	ds_read_b128 v[84:87], v169 offset:3072
	ds_read_b128 v[156:159], v170
	ds_read_b128 v[160:163], v170 offset:1024
	ds_read_b128 v[174:177], v170 offset:2048
	ds_read_b128 v[178:181], v170 offset:3072
	s_add_u32 s38, s36, 0xfff80080
	s_addc_u32 s39, s37, -1
	s_cmp_eq_u32 s61, 28
	s_cselect_b32 s41, s5, s39
	s_cselect_b32 s40, s27, s38
	s_cselect_b32 s39, s25, s60
	s_cselect_b32 s38, s35, s59
	v_lshl_add_u64 v[214:215], s[36:37], 0, v[150:151]
	s_add_i32 m0, s45, 0xc000
	ds_read_b128 v[182:185], v171
	ds_read_b128 v[186:189], v171 offset:1024
	ds_read_b128 v[190:193], v171 offset:2048
	ds_read_b128 v[194:197], v171 offset:3072
	ds_read_b128 v[198:201], v171 offset:4096
	ds_read_b128 v[202:205], v171 offset:5120
	ds_read_b128 v[206:209], v171 offset:6144
	ds_read_b128 v[210:213], v171 offset:7168
	global_load_lds_dwordx4 v[214:215], off
	v_lshl_add_u64 v[214:215], s[36:37], 0, v[148:149]
	s_add_i32 m0, s45, 0xe000
	s_nop 0
	global_load_lds_dwordx4 v[214:215], off
	s_waitcnt vmcnt(8)
	s_waitcnt lgkmcnt(0)
	s_setprio 1
	s_barrier
	v_mfma_f32_16x16x32_bf16 v[140:143], v[64:67], v[182:185], v[140:143]
	v_mfma_f32_16x16x32_bf16 v[136:139], v[76:79], v[182:185], v[136:139]
	v_mfma_f32_16x16x32_bf16 v[124:127], v[64:67], v[190:193], v[124:127]
	v_mfma_f32_16x16x32_bf16 v[120:123], v[76:79], v[190:193], v[120:123]
	v_mfma_f32_16x16x32_bf16 v[108:111], v[64:67], v[198:201], v[108:111]
	v_mfma_f32_16x16x32_bf16 v[104:107], v[76:79], v[198:201], v[104:107]
	v_mfma_f32_16x16x32_bf16 v[92:95], v[64:67], v[206:209], v[92:95]
	v_mfma_f32_16x16x32_bf16 v[88:91], v[76:79], v[206:209], v[88:91]
	v_mfma_f32_16x16x32_bf16 v[140:143], v[72:75], v[186:189], v[140:143]
	v_mfma_f32_16x16x32_bf16 v[136:139], v[84:87], v[186:189], v[136:139]
	v_mfma_f32_16x16x32_bf16 v[124:127], v[72:75], v[194:197], v[124:127]
	v_mfma_f32_16x16x32_bf16 v[120:123], v[84:87], v[194:197], v[120:123]
	v_mfma_f32_16x16x32_bf16 v[108:111], v[72:75], v[202:205], v[108:111]
	v_mfma_f32_16x16x32_bf16 v[104:107], v[84:87], v[202:205], v[104:107]
	v_mfma_f32_16x16x32_bf16 v[92:95], v[72:75], v[210:213], v[92:95]
	v_mfma_f32_16x16x32_bf16 v[88:91], v[84:87], v[210:213], v[88:91]
	s_setprio 0
	s_setprio 1
	v_mfma_f32_16x16x32_bf16 v[132:135], v[156:159], v[182:185], v[132:135]
	v_mfma_f32_16x16x32_bf16 v[128:131], v[174:177], v[182:185], v[128:131]
	v_mfma_f32_16x16x32_bf16 v[116:119], v[156:159], v[190:193], v[116:119]
	v_mfma_f32_16x16x32_bf16 v[112:115], v[174:177], v[190:193], v[112:115]
	v_mfma_f32_16x16x32_bf16 v[100:103], v[156:159], v[198:201], v[100:103]
	v_mfma_f32_16x16x32_bf16 v[96:99], v[174:177], v[198:201], v[96:99]
	v_mfma_f32_16x16x32_bf16 v[80:83], v[156:159], v[206:209], v[80:83]
	v_mfma_f32_16x16x32_bf16 v[68:71], v[174:177], v[206:209], v[68:71]
	v_mfma_f32_16x16x32_bf16 v[132:135], v[160:163], v[186:189], v[132:135]
	v_mfma_f32_16x16x32_bf16 v[128:131], v[178:181], v[186:189], v[128:131]
	v_mfma_f32_16x16x32_bf16 v[116:119], v[160:163], v[194:197], v[116:119]
	v_mfma_f32_16x16x32_bf16 v[112:115], v[178:181], v[194:197], v[112:115]
	v_mfma_f32_16x16x32_bf16 v[100:103], v[160:163], v[202:205], v[100:103]
	v_mfma_f32_16x16x32_bf16 v[96:99], v[178:181], v[202:205], v[96:99]
	v_mfma_f32_16x16x32_bf16 v[80:83], v[160:163], v[210:213], v[80:83]
	v_mfma_f32_16x16x32_bf16 v[68:71], v[178:181], v[210:213], v[68:71]
	s_barrier
	s_setprio 0
	s_add_i32 s62, s56, s44
	v_lshl_add_u64 v[214:215], s[38:39], 0, v[144:145]
	s_mov_b32 m0, s62
	ds_read_b128 v[182:185], v171 offset:16384
	ds_read_b128 v[186:189], v171 offset:17408
	ds_read_b128 v[190:193], v171 offset:18432
	ds_read_b128 v[194:197], v171 offset:19456
	ds_read_b128 v[198:201], v171 offset:20480
	ds_read_b128 v[202:205], v171 offset:21504
	ds_read_b128 v[206:209], v171 offset:22528
	ds_read_b128 v[210:213], v171 offset:23552
	global_load_lds_dwordx4 v[214:215], off
	s_add_i32 m0, s62, 0x2000
	s_add_u32 s62, s38, 0x80000
	v_lshl_add_u64 v[216:217], s[38:39], 0, v[146:147]
	s_addc_u32 s63, s39, 0
	s_add_i32 s64, s57, s44
	global_load_lds_dwordx4 v[216:217], off
	v_lshl_add_u64 v[218:219], s[62:63], 0, v[144:145]
	s_mov_b32 m0, s64
	v_lshl_add_u64 v[220:221], s[40:41], 0, v[146:147]
	global_load_lds_dwordx4 v[218:219], off
	v_lshl_add_u64 v[218:219], s[62:63], 0, v[146:147]
	s_add_i32 m0, s64, 0x2000
	s_nop 0
	global_load_lds_dwordx4 v[218:219], off
	v_lshl_add_u64 v[218:219], s[40:41], 0, v[144:145]
	s_mov_b32 m0, s45
	s_nop 0
	global_load_lds_dwordx4 v[218:219], off
	s_mov_b32 m0, s46
	s_nop 0
	global_load_lds_dwordx4 v[220:221], off
	s_waitcnt vmcnt(8)
	s_waitcnt lgkmcnt(0)
	s_setprio 1
	s_barrier
; #define PG8_STAGE(bufoff, gbase, voff) do { _Pragma("unroll") for (int _i = 0; _i < 2; ++_i) \
;         __builtin_amdgcn_global_load_lds((const unsigned*)((const char*)(gbase) + (voff)[_i]), (LAS unsigned*)(lds + (bufoff) + ldsw + _i * 8192), 16, 0, 0); } while (0)
; #define PG8_LDA(dst, b, h) do { _Pragma("unroll") for (int m = 0; m < 4; ++m) _Pragma("unroll") for (int k = 0; k < 2; ++k) dst[m][k] = *(const LAS bf16x8*)(lds + PG8_SA(b, h) + aoff + m * 2048 + k * 1024); } while (0)
; #define PG8_LDB(dst, b, h) do { _Pragma("unroll") for (int n = 0; n < 2; ++n) _Pragma("unroll") for (int k = 0; k < 2; ++k) dst[n][k] = *(const LAS bf16x8*)(lds + PG8_SB(b, h) + boff + n * 2048 + k * 1024); } while (0)
; #define PG8_MMA(ai, bj, At, Bt) do { __builtin_amdgcn_s_setprio(1); _Pragma("unroll") for (int m = 0; m < 4; ++m) _Pragma("unroll") for (int n = 0; n < 2; ++n) _Pragma("unroll") for (int k = 0; k < 2; ++k) \
;         acc[ai][bj][m][n] = __builtin_amdgcn_mfma_f32_16x16x32_bf16(Bt[n][k], At[m][k], acc[ai][bj][m][n], 0, 0, 0); __builtin_amdgcn_s_setprio(0); } while (0)
; #define PG8_WAIT_V(n) asm volatile("s_waitcnt vmcnt(" #n ")" ::: "memory")
; #define PG8_WAIT_L(n) asm volatile("s_waitcnt lgkmcnt(" #n ")" ::: "memory")
; #define PG8_BAR __builtin_amdgcn_s_barrier()
; #define PG8_SCHED __builtin_amdgcn_sched_barrier(0)
; template <class Epi, bool ALIGN_EPI>
; __device__ __forceinline__ void gemm_phase(LAS unsigned char* lds, const Gemm g, const StaticOrder& S, const Epi& E) {
;     ...
;             PG8_WAIT_V(8); PG8_WAIT_L(0); PG8_BAR; PG8_MMA(1, 0, At, B0); PG8_MMA(1, 1, At, B1); PG8_BAR; PG8_SCHED;
;             PG8_LDB(B0, 1, 0); PG8_LDB(B1, 1, 1); PG8_SCHED; PG8_LDA(At, 1, 0); PG8_STAGE(PG8_SA(0, 1), a2 + hstepA, voffA);
;             PG8_WAIT_V(8); PG8_WAIT_L(0); PG8_BAR; PG8_MMA(0, 0, At, B0); PG8_MMA(0, 1, At, B1); PG8_BAR; PG8_SCHED;
	v_mfma_f32_16x16x32_bf16 v[60:63], v[64:67], v[182:185], v[60:63]
	v_mfma_f32_16x16x32_bf16 v[56:59], v[76:79], v[182:185], v[56:59]
	v_mfma_f32_16x16x32_bf16 v[44:47], v[64:67], v[190:193], v[44:47]
	v_mfma_f32_16x16x32_bf16 v[40:43], v[76:79], v[190:193], v[40:43]
	v_mfma_f32_16x16x32_bf16 v[28:31], v[64:67], v[198:201], v[28:31]
	v_mfma_f32_16x16x32_bf16 v[24:27], v[76:79], v[198:201], v[24:27]
	v_mfma_f32_16x16x32_bf16 v[12:15], v[64:67], v[206:209], v[12:15]
	v_mfma_f32_16x16x32_bf16 v[8:11], v[76:79], v[206:209], v[8:11]
	v_mfma_f32_16x16x32_bf16 v[60:63], v[72:75], v[186:189], v[60:63]
	v_mfma_f32_16x16x32_bf16 v[56:59], v[84:87], v[186:189], v[56:59]
	v_mfma_f32_16x16x32_bf16 v[44:47], v[72:75], v[194:197], v[44:47]
	v_mfma_f32_16x16x32_bf16 v[40:43], v[84:87], v[194:197], v[40:43]
	v_mfma_f32_16x16x32_bf16 v[28:31], v[72:75], v[202:205], v[28:31]
	v_mfma_f32_16x16x32_bf16 v[24:27], v[84:87], v[202:205], v[24:27]
	v_mfma_f32_16x16x32_bf16 v[12:15], v[72:75], v[210:213], v[12:15]
	v_mfma_f32_16x16x32_bf16 v[8:11], v[84:87], v[210:213], v[8:11]
	s_setprio 0
	s_setprio 1
	v_mfma_f32_16x16x32_bf16 v[52:55], v[156:159], v[182:185], v[52:55]
	v_mfma_f32_16x16x32_bf16 v[48:51], v[174:177], v[182:185], v[48:51]
	v_mfma_f32_16x16x32_bf16 v[36:39], v[156:159], v[190:193], v[36:39]
	v_mfma_f32_16x16x32_bf16 v[32:35], v[174:177], v[190:193], v[32:35]
	v_mfma_f32_16x16x32_bf16 v[20:23], v[156:159], v[198:201], v[20:23]
	v_mfma_f32_16x16x32_bf16 v[16:19], v[174:177], v[198:201], v[16:19]
	v_mfma_f32_16x16x32_bf16 v[4:7], v[156:159], v[206:209], v[4:7]
	v_mfma_f32_16x16x32_bf16 v[0:3], v[174:177], v[206:209], v[0:3]
	v_mfma_f32_16x16x32_bf16 v[52:55], v[160:163], v[186:189], v[52:55]
	v_mfma_f32_16x16x32_bf16 v[48:51], v[178:181], v[186:189], v[48:51]
	v_mfma_f32_16x16x32_bf16 v[36:39], v[160:163], v[194:197], v[36:39]
	v_mfma_f32_16x16x32_bf16 v[32:35], v[178:181], v[194:197], v[32:35]
	v_mfma_f32_16x16x32_bf16 v[20:23], v[160:163], v[202:205], v[20:23]
	v_mfma_f32_16x16x32_bf16 v[16:19], v[178:181], v[202:205], v[16:19]
	v_mfma_f32_16x16x32_bf16 v[4:7], v[160:163], v[210:213], v[4:7]
	v_mfma_f32_16x16x32_bf16 v[0:3], v[178:181], v[210:213], v[0:3]
	s_barrier
	s_setprio 0
	s_add_i32 s62, 0, 0x18000
	s_add_i32 s63, 0, 0x1c000
	v_add_u32_e32 v84, s62, v165
	v_add_u32_e32 v173, s63, v165
	ds_read_b128 v[64:67], v84
	ds_read_b128 v[72:75], v84 offset:1024
	ds_read_b128 v[76:79], v84 offset:2048
	ds_read_b128 v[84:87], v84 offset:3072
	ds_read_b128 v[156:159], v173
	ds_read_b128 v[160:163], v173 offset:1024
	ds_read_b128 v[174:177], v173 offset:2048
	ds_read_b128 v[178:181], v173 offset:3072
	s_add_u32 s40, s40, 0x80000
	s_addc_u32 s41, s41, 0
	s_mov_b32 m0, s47
	v_lshl_add_u64 v[222:223], s[40:41], 0, v[144:145]
	ds_read_b128 v[182:185], v171 offset:32768
	ds_read_b128 v[186:189], v171 offset:33792
	ds_read_b128 v[190:193], v171 offset:34816
	ds_read_b128 v[194:197], v171 offset:35840
	ds_read_b128 v[198:201], v171 offset:36864
	ds_read_b128 v[202:205], v171 offset:37888
	ds_read_b128 v[206:209], v171 offset:38912
	ds_read_b128 v[210:213], v171 offset:39936
	global_load_lds_dwordx4 v[222:223], off
	v_lshl_add_u64 v[222:223], s[40:41], 0, v[146:147]
	s_mov_b32 m0, s48
	s_nop 0
	global_load_lds_dwordx4 v[222:223], off
	s_waitcnt vmcnt(8)
	s_waitcnt lgkmcnt(0)
	s_setprio 1
	s_barrier
	v_mfma_f32_16x16x32_bf16 v[140:143], v[64:67], v[182:185], v[140:143]
	v_mfma_f32_16x16x32_bf16 v[136:139], v[76:79], v[182:185], v[136:139]
	v_mfma_f32_16x16x32_bf16 v[124:127], v[64:67], v[190:193], v[124:127]
	v_mfma_f32_16x16x32_bf16 v[120:123], v[76:79], v[190:193], v[120:123]
	v_mfma_f32_16x16x32_bf16 v[108:111], v[64:67], v[198:201], v[108:111]
	v_mfma_f32_16x16x32_bf16 v[104:107], v[76:79], v[198:201], v[104:107]
	v_mfma_f32_16x16x32_bf16 v[92:95], v[64:67], v[206:209], v[92:95]
	v_mfma_f32_16x16x32_bf16 v[88:91], v[76:79], v[206:209], v[88:91]
	v_mfma_f32_16x16x32_bf16 v[140:143], v[72:75], v[186:189], v[140:143]
	v_mfma_f32_16x16x32_bf16 v[136:139], v[84:87], v[186:189], v[136:139]
	v_mfma_f32_16x16x32_bf16 v[124:127], v[72:75], v[194:197], v[124:127]
	v_mfma_f32_16x16x32_bf16 v[120:123], v[84:87], v[194:197], v[120:123]
	v_mfma_f32_16x16x32_bf16 v[108:111], v[72:75], v[202:205], v[108:111]
	v_mfma_f32_16x16x32_bf16 v[104:107], v[84:87], v[202:205], v[104:107]
	v_mfma_f32_16x16x32_bf16 v[92:95], v[72:75], v[210:213], v[92:95]
	v_mfma_f32_16x16x32_bf16 v[88:91], v[84:87], v[210:213], v[88:91]
	s_setprio 0
	s_setprio 1
	v_mfma_f32_16x16x32_bf16 v[132:135], v[156:159], v[182:185], v[132:135]
	v_mfma_f32_16x16x32_bf16 v[128:131], v[174:177], v[182:185], v[128:131]
	v_mfma_f32_16x16x32_bf16 v[116:119], v[156:159], v[190:193], v[116:119]
	v_mfma_f32_16x16x32_bf16 v[112:115], v[174:177], v[190:193], v[112:115]
	v_mfma_f32_16x16x32_bf16 v[100:103], v[156:159], v[198:201], v[100:103]
	v_mfma_f32_16x16x32_bf16 v[96:99], v[174:177], v[198:201], v[96:99]
	v_mfma_f32_16x16x32_bf16 v[80:83], v[156:159], v[206:209], v[80:83]
	v_mfma_f32_16x16x32_bf16 v[68:71], v[174:177], v[206:209], v[68:71]
	v_mfma_f32_16x16x32_bf16 v[132:135], v[160:163], v[186:189], v[132:135]
	v_mfma_f32_16x16x32_bf16 v[128:131], v[178:181], v[186:189], v[128:131]
	v_mfma_f32_16x16x32_bf16 v[116:119], v[160:163], v[194:197], v[116:119]
	v_mfma_f32_16x16x32_bf16 v[112:115], v[178:181], v[194:197], v[112:115]
	v_mfma_f32_16x16x32_bf16 v[100:103], v[160:163], v[202:205], v[100:103]
	v_mfma_f32_16x16x32_bf16 v[96:99], v[178:181], v[202:205], v[96:99]
	v_mfma_f32_16x16x32_bf16 v[80:83], v[160:163], v[210:213], v[80:83]
	v_mfma_f32_16x16x32_bf16 v[68:71], v[178:181], v[210:213], v[68:71]
	s_barrier
; #define PG8_STAGE(bufoff, gbase, voff) do { _Pragma("unroll") for (int _i = 0; _i < 2; ++_i) \
;         __builtin_amdgcn_global_load_lds((const unsigned*)((const char*)(gbase) + (voff)[_i]), (LAS unsigned*)(lds + (bufoff) + ldsw + _i * 8192), 16, 0, 0); } while (0)
; #define PG8_LDA(dst, b, h) do { _Pragma("unroll") for (int m = 0; m < 4; ++m) _Pragma("unroll") for (int k = 0; k < 2; ++k) dst[m][k] = *(const LAS bf16x8*)(lds + PG8_SA(b, h) + aoff + m * 2048 + k * 1024); } while (0)
; #define PG8_MMA(ai, bj, At, Bt) do { __builtin_amdgcn_s_setprio(1); _Pragma("unroll") for (int m = 0; m < 4; ++m) _Pragma("unroll") for (int n = 0; n < 2; ++n) _Pragma("unroll") for (int k = 0; k < 2; ++k) \
;         acc[ai][bj][m][n] = __builtin_amdgcn_mfma_f32_16x16x32_bf16(Bt[n][k], At[m][k], acc[ai][bj][m][n], 0, 0, 0); __builtin_amdgcn_s_setprio(0); } while (0)
; #define PG8_WAIT_V(n) asm volatile("s_waitcnt vmcnt(" #n ")" ::: "memory")
; #define PG8_WAIT_L(n) asm volatile("s_waitcnt lgkmcnt(" #n ")" ::: "memory")
; #define PG8_BAR __builtin_amdgcn_s_barrier()
; #define PG8_SCHED __builtin_amdgcn_sched_barrier(0)
; template <class Epi, bool ALIGN_EPI>
; __device__ __forceinline__ void gemm_phase(LAS unsigned char* lds, const Gemm g, const StaticOrder& S, const Epi& E) {
;     ...
;             PG8_LDA(At, 1, 1); PG8_STAGE(PG8_SB(1, 0), b3, voffB); PG8_STAGE(PG8_SB(1, 1), b3 + hstepB, voffB); PG8_STAGE(PG8_SA(1, 0), a3, voffA);
;             PG8_WAIT_V(8); PG8_WAIT_L(0); PG8_BAR; PG8_MMA(1, 0, At, B0); PG8_MMA(1, 1, At, B1); PG8_BAR; PG8_SCHED;
;         }
	s_setprio 0
	s_add_i32 s40, s62, s44
	v_lshl_add_u64 v[214:215], v[214:215], 0, s[18:19]
	s_mov_b32 m0, s40
	ds_read_b128 v[182:185], v171 offset:49152
	ds_read_b128 v[186:189], v171 offset:50176
	ds_read_b128 v[190:193], v171 offset:51200
	ds_read_b128 v[194:197], v171 offset:52224
	ds_read_b128 v[198:201], v171 offset:53248
	ds_read_b128 v[202:205], v171 offset:54272
	ds_read_b128 v[206:209], v171 offset:55296
	ds_read_b128 v[210:213], v171 offset:56320
	global_load_lds_dwordx4 v[214:215], off
	s_add_i32 m0, s40, 0x2000
	s_add_u32 s38, s38, 0x80080
	v_lshl_add_u64 v[214:215], v[216:217], 0, s[18:19]
	s_addc_u32 s39, s39, 0
	s_add_i32 s40, s63, s44
	global_load_lds_dwordx4 v[214:215], off
	v_lshl_add_u64 v[214:215], s[38:39], 0, v[144:145]
	s_mov_b32 m0, s40
	s_nop 0
	global_load_lds_dwordx4 v[214:215], off
	v_lshl_add_u64 v[214:215], s[38:39], 0, v[146:147]
	s_add_i32 m0, s40, 0x2000
	s_nop 0
	global_load_lds_dwordx4 v[214:215], off
	v_lshl_add_u64 v[214:215], v[218:219], 0, s[18:19]
	s_mov_b32 m0, s50
	s_nop 0
	global_load_lds_dwordx4 v[214:215], off
	v_lshl_add_u64 v[214:215], v[220:221], 0, s[18:19]
	s_mov_b32 m0, s51
	s_nop 0
	global_load_lds_dwordx4 v[214:215], off
	s_waitcnt vmcnt(8)
	s_waitcnt lgkmcnt(0)
	s_setprio 1
	s_barrier
	v_mfma_f32_16x16x32_bf16 v[60:63], v[64:67], v[182:185], v[60:63]
	v_mfma_f32_16x16x32_bf16 v[56:59], v[76:79], v[182:185], v[56:59]
	v_mfma_f32_16x16x32_bf16 v[44:47], v[64:67], v[190:193], v[44:47]
	v_mfma_f32_16x16x32_bf16 v[40:43], v[76:79], v[190:193], v[40:43]
	v_mfma_f32_16x16x32_bf16 v[28:31], v[64:67], v[198:201], v[28:31]
	v_mfma_f32_16x16x32_bf16 v[24:27], v[76:79], v[198:201], v[24:27]
	v_mfma_f32_16x16x32_bf16 v[12:15], v[64:67], v[206:209], v[12:15]
	v_mfma_f32_16x16x32_bf16 v[8:11], v[76:79], v[206:209], v[8:11]
	v_mfma_f32_16x16x32_bf16 v[60:63], v[72:75], v[186:189], v[60:63]
	v_mfma_f32_16x16x32_bf16 v[56:59], v[84:87], v[186:189], v[56:59]
	v_mfma_f32_16x16x32_bf16 v[44:47], v[72:75], v[194:197], v[44:47]
	v_mfma_f32_16x16x32_bf16 v[40:43], v[84:87], v[194:197], v[40:43]
	v_mfma_f32_16x16x32_bf16 v[28:31], v[72:75], v[202:205], v[28:31]
	v_mfma_f32_16x16x32_bf16 v[24:27], v[84:87], v[202:205], v[24:27]
	v_mfma_f32_16x16x32_bf16 v[12:15], v[72:75], v[210:213], v[12:15]
	v_mfma_f32_16x16x32_bf16 v[8:11], v[84:87], v[210:213], v[8:11]
	s_setprio 0
	s_setprio 1
	v_mfma_f32_16x16x32_bf16 v[52:55], v[156:159], v[182:185], v[52:55]
	v_mfma_f32_16x16x32_bf16 v[48:51], v[174:177], v[182:185], v[48:51]
	v_mfma_f32_16x16x32_bf16 v[36:39], v[156:159], v[190:193], v[36:39]
	v_mfma_f32_16x16x32_bf16 v[32:35], v[174:177], v[190:193], v[32:35]
	v_mfma_f32_16x16x32_bf16 v[20:23], v[156:159], v[198:201], v[20:23]
	v_mfma_f32_16x16x32_bf16 v[16:19], v[174:177], v[198:201], v[16:19]
	v_mfma_f32_16x16x32_bf16 v[4:7], v[156:159], v[206:209], v[4:7]
	v_mfma_f32_16x16x32_bf16 v[0:3], v[174:177], v[206:209], v[0:3]
	v_mfma_f32_16x16x32_bf16 v[52:55], v[160:163], v[186:189], v[52:55]
	v_mfma_f32_16x16x32_bf16 v[48:51], v[178:181], v[186:189], v[48:51]
	v_mfma_f32_16x16x32_bf16 v[36:39], v[160:163], v[194:197], v[36:39]
	v_mfma_f32_16x16x32_bf16 v[32:35], v[178:181], v[194:197], v[32:35]
	v_mfma_f32_16x16x32_bf16 v[20:23], v[160:163], v[202:205], v[20:23]
	v_mfma_f32_16x16x32_bf16 v[16:19], v[178:181], v[202:205], v[16:19]
	v_mfma_f32_16x16x32_bf16 v[4:7], v[160:163], v[210:213], v[4:7]
	v_mfma_f32_16x16x32_bf16 v[0:3], v[178:181], v[210:213], v[0:3]
	s_barrier
	s_setprio 0
	s_add_i32 s61, s61, 2
	s_add_u32 s59, s59, 0x100
	s_addc_u32 s60, s60, 0
	s_add_u32 s36, s36, 0x100
	s_addc_u32 s37, s37, 0
	s_cmp_gt_u32 s61, 29
	s_cbranch_scc0 .LBB0_1082
	s_and_b64 vcc, exec, s[20:21]
	s_cbranch_vccz .LBB0_1085
	s_barrier

; #define PG8_STAGE(bufoff, gbase, voff) do { _Pragma("unroll") for (int _i = 0; _i < 2; ++_i) \
;         __builtin_amdgcn_global_load_lds((const unsigned*)((const char*)(gbase) + (voff)[_i]), (LAS unsigned*)(lds + (bufoff) + ldsw + _i * 8192), 16, 0, 0); } while (0)
; #define PG8_LDA(dst, b, h) do { _Pragma("unroll") for (int m = 0; m < 4; ++m) _Pragma("unroll") for (int k = 0; k < 2; ++k) dst[m][k] = *(const LAS bf16x8*)(lds + PG8_SA(b, h) + aoff + m * 2048 + k * 1024); } while (0)
; #define PG8_LDB(dst, b, h) do { _Pragma("unroll") for (int n = 0; n < 2; ++n) _Pragma("unroll") for (int k = 0; k < 2; ++k) dst[n][k] = *(const LAS bf16x8*)(lds + PG8_SB(b, h) + boff + n * 2048 + k * 1024); } while (0)
; #define PG8_MMA(ai, bj, At, Bt) do { __builtin_amdgcn_s_setprio(1); _Pragma("unroll") for (int m = 0; m < 4; ++m) _Pragma("unroll") for (int n = 0; n < 2; ++n) _Pragma("unroll") for (int k = 0; k < 2; ++k) \
;         acc[ai][bj][m][n] = __builtin_amdgcn_mfma_f32_16x16x32_bf16(Bt[n][k], At[m][k], acc[ai][bj][m][n], 0, 0, 0); __builtin_amdgcn_s_setprio(0); } while (0)
; #define PG8_WAIT_V(n) asm volatile("s_waitcnt vmcnt(" #n ")" ::: "memory")
; #define PG8_WAIT_L(n) asm volatile("s_waitcnt lgkmcnt(" #n ")" ::: "memory")
; #define PG8_BAR __builtin_amdgcn_s_barrier()
; #define PG8_SCHED __builtin_amdgcn_sched_barrier(0)
; template <class Epi, bool ALIGN_EPI>
; __device__ __forceinline__ void gemm_phase(LAS unsigned char* lds, const Gemm g, const StaticOrder& S, const Epi& E) {
;     ...
;             PG8_LDB(B0, 0, 0); PG8_LDB(B1, 0, 1); PG8_SCHED; PG8_LDA(At, 0, 0); PG8_STAGE(PG8_SA(1, 1), a1 + hstepA, voffA);
;             PG8_WAIT_V(8); PG8_WAIT_L(0); PG8_BAR; PG8_MMA(0, 0, At, B0); PG8_MMA(0, 1, At, B1); PG8_BAR; PG8_SCHED;
;             PG8_LDA(At, 0, 1); PG8_STAGE(PG8_SB(0, 0), b2, voffB); PG8_STAGE(PG8_SB(0, 1), b2 + hstepB, voffB); PG8_STAGE(PG8_SA(0, 0), a2, voffA);
;             PG8_WAIT_V(8); PG8_WAIT_L(0); PG8_BAR; PG8_MMA(1, 0, At, B0); PG8_MMA(1, 1, At, B1); PG8_BAR; PG8_SCHED;
.LBB0_1293:
	ds_read_b128 v[144:147], v156
	ds_read_b128 v[148:151], v156 offset:1024
	ds_read_b128 v[160:163], v156 offset:2048
	ds_read_b128 v[168:171], v156 offset:3072
	ds_read_b128 v[172:175], v157
	ds_read_b128 v[176:179], v157 offset:1024
	ds_read_b128 v[180:183], v157 offset:2048
	ds_read_b128 v[184:187], v157 offset:3072
	s_add_u32 s26, s24, 0xfff80080
	s_addc_u32 s27, s25, -1
	s_cmp_eq_u32 s56, 28
	s_cselect_b32 s29, s19, s27
	s_cselect_b32 s28, s52, s26
	s_cselect_b32 s27, s17, s55
	s_cselect_b32 s26, s53, s54
	v_lshl_add_u64 v[164:165], s[24:25], 0, v[138:139]
	s_add_i32 m0, s38, 0xc000
	ds_read_b128 v[188:191], v158
	ds_read_b128 v[192:195], v158 offset:1024
	ds_read_b128 v[196:199], v158 offset:2048
	ds_read_b128 v[200:203], v158 offset:3072
	ds_read_b128 v[204:207], v158 offset:4096
	ds_read_b128 v[208:211], v158 offset:5120
	ds_read_b128 v[212:215], v158 offset:6144
	ds_read_b128 v[216:219], v158 offset:7168
	global_load_lds_dwordx4 v[164:165], off
	v_lshl_add_u64 v[164:165], s[24:25], 0, v[136:137]
	s_add_i32 m0, s38, 0xe000
	s_nop 0
	global_load_lds_dwordx4 v[164:165], off
	s_waitcnt vmcnt(8)
	s_waitcnt lgkmcnt(0)
	s_setprio 1
	s_barrier
	v_mfma_f32_16x16x32_bf16 v[124:127], v[144:147], v[188:191], v[124:127]
	v_mfma_f32_16x16x32_bf16 v[120:123], v[160:163], v[188:191], v[120:123]
	v_mfma_f32_16x16x32_bf16 v[108:111], v[144:147], v[196:199], v[108:111]
	v_mfma_f32_16x16x32_bf16 v[104:107], v[160:163], v[196:199], v[104:107]
	v_mfma_f32_16x16x32_bf16 v[92:95], v[144:147], v[204:207], v[92:95]
	v_mfma_f32_16x16x32_bf16 v[88:91], v[160:163], v[204:207], v[88:91]
	v_mfma_f32_16x16x32_bf16 v[76:79], v[144:147], v[212:215], v[76:79]
	v_mfma_f32_16x16x32_bf16 v[72:75], v[160:163], v[212:215], v[72:75]
	v_mfma_f32_16x16x32_bf16 v[124:127], v[148:151], v[192:195], v[124:127]
	v_mfma_f32_16x16x32_bf16 v[120:123], v[168:171], v[192:195], v[120:123]
	v_mfma_f32_16x16x32_bf16 v[108:111], v[148:151], v[200:203], v[108:111]
	v_mfma_f32_16x16x32_bf16 v[104:107], v[168:171], v[200:203], v[104:107]
	v_mfma_f32_16x16x32_bf16 v[92:95], v[148:151], v[208:211], v[92:95]
	v_mfma_f32_16x16x32_bf16 v[88:91], v[168:171], v[208:211], v[88:91]
	v_mfma_f32_16x16x32_bf16 v[76:79], v[148:151], v[216:219], v[76:79]
	v_mfma_f32_16x16x32_bf16 v[72:75], v[168:171], v[216:219], v[72:75]
	s_setprio 0
	s_setprio 1
	v_mfma_f32_16x16x32_bf16 v[116:119], v[172:175], v[188:191], v[116:119]
	v_mfma_f32_16x16x32_bf16 v[112:115], v[180:183], v[188:191], v[112:115]
	v_mfma_f32_16x16x32_bf16 v[100:103], v[172:175], v[196:199], v[100:103]
	v_mfma_f32_16x16x32_bf16 v[96:99], v[180:183], v[196:199], v[96:99]
	v_mfma_f32_16x16x32_bf16 v[84:87], v[172:175], v[204:207], v[84:87]
	v_mfma_f32_16x16x32_bf16 v[80:83], v[180:183], v[204:207], v[80:83]
	v_mfma_f32_16x16x32_bf16 v[68:71], v[172:175], v[212:215], v[68:71]
	v_mfma_f32_16x16x32_bf16 v[64:67], v[180:183], v[212:215], v[64:67]
	v_mfma_f32_16x16x32_bf16 v[116:119], v[176:179], v[192:195], v[116:119]
	v_mfma_f32_16x16x32_bf16 v[112:115], v[184:187], v[192:195], v[112:115]
	v_mfma_f32_16x16x32_bf16 v[100:103], v[176:179], v[200:203], v[100:103]
	v_mfma_f32_16x16x32_bf16 v[96:99], v[184:187], v[200:203], v[96:99]
	v_mfma_f32_16x16x32_bf16 v[84:87], v[176:179], v[208:211], v[84:87]
	v_mfma_f32_16x16x32_bf16 v[80:83], v[184:187], v[208:211], v[80:83]
	v_mfma_f32_16x16x32_bf16 v[68:71], v[176:179], v[216:219], v[68:71]
	v_mfma_f32_16x16x32_bf16 v[64:67], v[184:187], v[216:219], v[64:67]
	s_barrier
	s_setprio 0
	s_add_i32 s57, s47, s35
	v_lshl_add_u64 v[164:165], s[26:27], 0, v[132:133]
	s_mov_b32 m0, s57
	ds_read_b128 v[188:191], v158 offset:16384
	ds_read_b128 v[192:195], v158 offset:17408
	ds_read_b128 v[196:199], v158 offset:18432
	ds_read_b128 v[200:203], v158 offset:19456
	ds_read_b128 v[204:207], v158 offset:20480
	ds_read_b128 v[208:211], v158 offset:21504
	ds_read_b128 v[212:215], v158 offset:22528
	ds_read_b128 v[216:219], v158 offset:23552
	global_load_lds_dwordx4 v[164:165], off
	s_add_i32 m0, s57, 0x2000
	s_add_u32 s58, s26, 0x80000
	v_lshl_add_u64 v[220:221], s[26:27], 0, v[128:129]
	s_addc_u32 s59, s27, 0
	s_add_i32 s57, s48, s35
	global_load_lds_dwordx4 v[220:221], off
	v_lshl_add_u64 v[222:223], s[58:59], 0, v[132:133]
	s_mov_b32 m0, s57
	v_lshl_add_u64 v[224:225], s[28:29], 0, v[130:131]
	global_load_lds_dwordx4 v[222:223], off
	v_lshl_add_u64 v[222:223], s[58:59], 0, v[128:129]
	s_add_i32 m0, s57, 0x2000
	s_nop 0
	global_load_lds_dwordx4 v[222:223], off
	v_lshl_add_u64 v[222:223], s[28:29], 0, v[134:135]
	s_mov_b32 m0, s38
	s_nop 0
	global_load_lds_dwordx4 v[222:223], off
	s_mov_b32 m0, s39
	s_nop 0
	global_load_lds_dwordx4 v[224:225], off
	s_waitcnt vmcnt(8)
	s_waitcnt lgkmcnt(0)
	s_setprio 1
	s_barrier
; #define PG8_STAGE(bufoff, gbase, voff) do { _Pragma("unroll") for (int _i = 0; _i < 2; ++_i) \
;         __builtin_amdgcn_global_load_lds((const unsigned*)((const char*)(gbase) + (voff)[_i]), (LAS unsigned*)(lds + (bufoff) + ldsw + _i * 8192), 16, 0, 0); } while (0)
; #define PG8_LDA(dst, b, h) do { _Pragma("unroll") for (int m = 0; m < 4; ++m) _Pragma("unroll") for (int k = 0; k < 2; ++k) dst[m][k] = *(const LAS bf16x8*)(lds + PG8_SA(b, h) + aoff + m * 2048 + k * 1024); } while (0)
; #define PG8_LDB(dst, b, h) do { _Pragma("unroll") for (int n = 0; n < 2; ++n) _Pragma("unroll") for (int k = 0; k < 2; ++k) dst[n][k] = *(const LAS bf16x8*)(lds + PG8_SB(b, h) + boff + n * 2048 + k * 1024); } while (0)
; #define PG8_MMA(ai, bj, At, Bt) do { __builtin_amdgcn_s_setprio(1); _Pragma("unroll") for (int m = 0; m < 4; ++m) _Pragma("unroll") for (int n = 0; n < 2; ++n) _Pragma("unroll") for (int k = 0; k < 2; ++k) \
;         acc[ai][bj][m][n] = __builtin_amdgcn_mfma_f32_16x16x32_bf16(Bt[n][k], At[m][k], acc[ai][bj][m][n], 0, 0, 0); __builtin_amdgcn_s_setprio(0); } while (0)
; #define PG8_WAIT_V(n) asm volatile("s_waitcnt vmcnt(" #n ")" ::: "memory")
; #define PG8_WAIT_L(n) asm volatile("s_waitcnt lgkmcnt(" #n ")" ::: "memory")
; #define PG8_BAR __builtin_amdgcn_s_barrier()
; #define PG8_SCHED __builtin_amdgcn_sched_barrier(0)
; template <class Epi, bool ALIGN_EPI>
; __device__ __forceinline__ void gemm_phase(LAS unsigned char* lds, const Gemm g, const StaticOrder& S, const Epi& E) {
;     ...
;             PG8_WAIT_V(8); PG8_WAIT_L(0); PG8_BAR; PG8_MMA(1, 0, At, B0); PG8_MMA(1, 1, At, B1); PG8_BAR; PG8_SCHED;
;             PG8_LDB(B0, 1, 0); PG8_LDB(B1, 1, 1); PG8_SCHED; PG8_LDA(At, 1, 0); PG8_STAGE(PG8_SA(0, 1), a2 + hstepA, voffA);
;             PG8_WAIT_V(8); PG8_WAIT_L(0); PG8_BAR; PG8_MMA(0, 0, At, B0); PG8_MMA(0, 1, At, B1); PG8_BAR; PG8_SCHED;
	v_mfma_f32_16x16x32_bf16 v[60:63], v[144:147], v[188:191], v[60:63]
	v_mfma_f32_16x16x32_bf16 v[56:59], v[160:163], v[188:191], v[56:59]
	v_mfma_f32_16x16x32_bf16 v[44:47], v[144:147], v[196:199], v[44:47]
	v_mfma_f32_16x16x32_bf16 v[40:43], v[160:163], v[196:199], v[40:43]
	v_mfma_f32_16x16x32_bf16 v[28:31], v[144:147], v[204:207], v[28:31]
	v_mfma_f32_16x16x32_bf16 v[24:27], v[160:163], v[204:207], v[24:27]
	v_mfma_f32_16x16x32_bf16 v[12:15], v[144:147], v[212:215], v[12:15]
	v_mfma_f32_16x16x32_bf16 v[8:11], v[160:163], v[212:215], v[8:11]
	v_mfma_f32_16x16x32_bf16 v[60:63], v[148:151], v[192:195], v[60:63]
	v_mfma_f32_16x16x32_bf16 v[56:59], v[168:171], v[192:195], v[56:59]
	v_mfma_f32_16x16x32_bf16 v[44:47], v[148:151], v[200:203], v[44:47]
	v_mfma_f32_16x16x32_bf16 v[40:43], v[168:171], v[200:203], v[40:43]
	v_mfma_f32_16x16x32_bf16 v[28:31], v[148:151], v[208:211], v[28:31]
	v_mfma_f32_16x16x32_bf16 v[24:27], v[168:171], v[208:211], v[24:27]
	v_mfma_f32_16x16x32_bf16 v[12:15], v[148:151], v[216:219], v[12:15]
	v_mfma_f32_16x16x32_bf16 v[8:11], v[168:171], v[216:219], v[8:11]
	s_setprio 0
	s_setprio 1
	v_mfma_f32_16x16x32_bf16 v[52:55], v[172:175], v[188:191], v[52:55]
	v_mfma_f32_16x16x32_bf16 v[48:51], v[180:183], v[188:191], v[48:51]
	v_mfma_f32_16x16x32_bf16 v[36:39], v[172:175], v[196:199], v[36:39]
	v_mfma_f32_16x16x32_bf16 v[32:35], v[180:183], v[196:199], v[32:35]
	v_mfma_f32_16x16x32_bf16 v[20:23], v[172:175], v[204:207], v[20:23]
	v_mfma_f32_16x16x32_bf16 v[16:19], v[180:183], v[204:207], v[16:19]
	v_mfma_f32_16x16x32_bf16 v[4:7], v[172:175], v[212:215], v[4:7]
	v_mfma_f32_16x16x32_bf16 v[0:3], v[180:183], v[212:215], v[0:3]
	v_mfma_f32_16x16x32_bf16 v[52:55], v[176:179], v[192:195], v[52:55]
	v_mfma_f32_16x16x32_bf16 v[48:51], v[184:187], v[192:195], v[48:51]
	v_mfma_f32_16x16x32_bf16 v[36:39], v[176:179], v[200:203], v[36:39]
	v_mfma_f32_16x16x32_bf16 v[32:35], v[184:187], v[200:203], v[32:35]
	v_mfma_f32_16x16x32_bf16 v[20:23], v[176:179], v[208:211], v[20:23]
	v_mfma_f32_16x16x32_bf16 v[16:19], v[184:187], v[208:211], v[16:19]
	v_mfma_f32_16x16x32_bf16 v[4:7], v[176:179], v[216:219], v[4:7]
	v_mfma_f32_16x16x32_bf16 v[0:3], v[184:187], v[216:219], v[0:3]
	s_barrier
	s_setprio 0
	s_add_i32 s57, 0, 0x18000
	s_add_i32 s58, 0, 0x1c000
	v_add_u32_e32 v168, s57, v154
	v_add_u32_e32 v184, s58, v154
	ds_read_b128 v[144:147], v168
	ds_read_b128 v[148:151], v168 offset:1024
	ds_read_b128 v[160:163], v168 offset:2048
	ds_read_b128 v[168:171], v168 offset:3072
	ds_read_b128 v[172:175], v184
	ds_read_b128 v[176:179], v184 offset:1024
	ds_read_b128 v[180:183], v184 offset:2048
	ds_read_b128 v[184:187], v184 offset:3072
	s_add_u32 s28, s28, 0x80000
	s_addc_u32 s29, s29, 0
	s_mov_b32 m0, s40
	v_lshl_add_u64 v[226:227], s[28:29], 0, v[134:135]
	ds_read_b128 v[188:191], v158 offset:32768
	ds_read_b128 v[192:195], v158 offset:33792
	ds_read_b128 v[196:199], v158 offset:34816
	ds_read_b128 v[200:203], v158 offset:35840
	ds_read_b128 v[204:207], v158 offset:36864
	ds_read_b128 v[208:211], v158 offset:37888
	ds_read_b128 v[212:215], v158 offset:38912
	ds_read_b128 v[216:219], v158 offset:39936
	global_load_lds_dwordx4 v[226:227], off
	v_lshl_add_u64 v[226:227], s[28:29], 0, v[130:131]
	s_mov_b32 m0, s41
	s_nop 0
	global_load_lds_dwordx4 v[226:227], off
	s_waitcnt vmcnt(8)
	s_waitcnt lgkmcnt(0)
	s_setprio 1
	s_barrier
	v_mfma_f32_16x16x32_bf16 v[124:127], v[144:147], v[188:191], v[124:127]
	v_mfma_f32_16x16x32_bf16 v[120:123], v[160:163], v[188:191], v[120:123]
	v_mfma_f32_16x16x32_bf16 v[108:111], v[144:147], v[196:199], v[108:111]
	v_mfma_f32_16x16x32_bf16 v[104:107], v[160:163], v[196:199], v[104:107]
	v_mfma_f32_16x16x32_bf16 v[92:95], v[144:147], v[204:207], v[92:95]
	v_mfma_f32_16x16x32_bf16 v[88:91], v[160:163], v[204:207], v[88:91]
	v_mfma_f32_16x16x32_bf16 v[76:79], v[144:147], v[212:215], v[76:79]
	v_mfma_f32_16x16x32_bf16 v[72:75], v[160:163], v[212:215], v[72:75]
	v_mfma_f32_16x16x32_bf16 v[124:127], v[148:151], v[192:195], v[124:127]
	v_mfma_f32_16x16x32_bf16 v[120:123], v[168:171], v[192:195], v[120:123]
	v_mfma_f32_16x16x32_bf16 v[108:111], v[148:151], v[200:203], v[108:111]
	v_mfma_f32_16x16x32_bf16 v[104:107], v[168:171], v[200:203], v[104:107]
	v_mfma_f32_16x16x32_bf16 v[92:95], v[148:151], v[208:211], v[92:95]
	v_mfma_f32_16x16x32_bf16 v[88:91], v[168:171], v[208:211], v[88:91]
	v_mfma_f32_16x16x32_bf16 v[76:79], v[148:151], v[216:219], v[76:79]
	v_mfma_f32_16x16x32_bf16 v[72:75], v[168:171], v[216:219], v[72:75]
	s_setprio 0
	s_setprio 1
	v_mfma_f32_16x16x32_bf16 v[116:119], v[172:175], v[188:191], v[116:119]
	v_mfma_f32_16x16x32_bf16 v[112:115], v[180:183], v[188:191], v[112:115]
	v_mfma_f32_16x16x32_bf16 v[100:103], v[172:175], v[196:199], v[100:103]
	v_mfma_f32_16x16x32_bf16 v[96:99], v[180:183], v[196:199], v[96:99]
	v_mfma_f32_16x16x32_bf16 v[84:87], v[172:175], v[204:207], v[84:87]
	v_mfma_f32_16x16x32_bf16 v[80:83], v[180:183], v[204:207], v[80:83]
	v_mfma_f32_16x16x32_bf16 v[68:71], v[172:175], v[212:215], v[68:71]
	v_mfma_f32_16x16x32_bf16 v[64:67], v[180:183], v[212:215], v[64:67]
	v_mfma_f32_16x16x32_bf16 v[116:119], v[176:179], v[192:195], v[116:119]
	v_mfma_f32_16x16x32_bf16 v[112:115], v[184:187], v[192:195], v[112:115]
	v_mfma_f32_16x16x32_bf16 v[100:103], v[176:179], v[200:203], v[100:103]
	v_mfma_f32_16x16x32_bf16 v[96:99], v[184:187], v[200:203], v[96:99]
	v_mfma_f32_16x16x32_bf16 v[84:87], v[176:179], v[208:211], v[84:87]
	v_mfma_f32_16x16x32_bf16 v[80:83], v[184:187], v[208:211], v[80:83]
	v_mfma_f32_16x16x32_bf16 v[68:71], v[176:179], v[216:219], v[68:71]
	v_mfma_f32_16x16x32_bf16 v[64:67], v[184:187], v[216:219], v[64:67]
	s_barrier
; #define PG8_STAGE(bufoff, gbase, voff) do { _Pragma("unroll") for (int _i = 0; _i < 2; ++_i) \
;         __builtin_amdgcn_global_load_lds((const unsigned*)((const char*)(gbase) + (voff)[_i]), (LAS unsigned*)(lds + (bufoff) + ldsw + _i * 8192), 16, 0, 0); } while (0)
; #define PG8_LDA(dst, b, h) do { _Pragma("unroll") for (int m = 0; m < 4; ++m) _Pragma("unroll") for (int k = 0; k < 2; ++k) dst[m][k] = *(const LAS bf16x8*)(lds + PG8_SA(b, h) + aoff + m * 2048 + k * 1024); } while (0)
; #define PG8_MMA(ai, bj, At, Bt) do { __builtin_amdgcn_s_setprio(1); _Pragma("unroll") for (int m = 0; m < 4; ++m) _Pragma("unroll") for (int n = 0; n < 2; ++n) _Pragma("unroll") for (int k = 0; k < 2; ++k) \
;         acc[ai][bj][m][n] = __builtin_amdgcn_mfma_f32_16x16x32_bf16(Bt[n][k], At[m][k], acc[ai][bj][m][n], 0, 0, 0); __builtin_amdgcn_s_setprio(0); } while (0)
; #define PG8_WAIT_V(n) asm volatile("s_waitcnt vmcnt(" #n ")" ::: "memory")
; #define PG8_WAIT_L(n) asm volatile("s_waitcnt lgkmcnt(" #n ")" ::: "memory")
; #define PG8_BAR __builtin_amdgcn_s_barrier()
; #define PG8_SCHED __builtin_amdgcn_sched_barrier(0)
; template <class Epi, bool ALIGN_EPI>
; __device__ __forceinline__ void gemm_phase(LAS unsigned char* lds, const Gemm g, const StaticOrder& S, const Epi& E) {
;     ...
;             PG8_LDA(At, 1, 1); PG8_STAGE(PG8_SB(1, 0), b3, voffB); PG8_STAGE(PG8_SB(1, 1), b3 + hstepB, voffB); PG8_STAGE(PG8_SA(1, 0), a3, voffA);
;             PG8_WAIT_V(8); PG8_WAIT_L(0); PG8_BAR; PG8_MMA(1, 0, At, B0); PG8_MMA(1, 1, At, B1); PG8_BAR; PG8_SCHED;
;         }
	s_setprio 0
	s_add_i32 s28, s57, s35
	v_lshl_add_u64 v[164:165], v[164:165], 0, s[12:13]
	s_mov_b32 m0, s28
	ds_read_b128 v[188:191], v158 offset:49152
	ds_read_b128 v[192:195], v158 offset:50176
	ds_read_b128 v[196:199], v158 offset:51200
	ds_read_b128 v[200:203], v158 offset:52224
	ds_read_b128 v[204:207], v158 offset:53248
	ds_read_b128 v[208:211], v158 offset:54272
	ds_read_b128 v[212:215], v158 offset:55296
	ds_read_b128 v[216:219], v158 offset:56320
	global_load_lds_dwordx4 v[164:165], off
	s_add_i32 m0, s28, 0x2000
	s_add_u32 s26, s26, 0x80080
	v_lshl_add_u64 v[164:165], v[220:221], 0, s[12:13]
	s_addc_u32 s27, s27, 0
	s_add_i32 s28, s58, s35
	global_load_lds_dwordx4 v[164:165], off
	v_lshl_add_u64 v[164:165], s[26:27], 0, v[132:133]
	s_mov_b32 m0, s28
	s_nop 0
	global_load_lds_dwordx4 v[164:165], off
	v_lshl_add_u64 v[164:165], s[26:27], 0, v[128:129]
	s_add_i32 m0, s28, 0x2000
	s_nop 0
	global_load_lds_dwordx4 v[164:165], off
	v_lshl_add_u64 v[164:165], v[222:223], 0, s[12:13]
	s_mov_b32 m0, s42
	s_nop 0
	global_load_lds_dwordx4 v[164:165], off
	v_lshl_add_u64 v[164:165], v[224:225], 0, s[12:13]
	s_mov_b32 m0, s43
	s_nop 0
	global_load_lds_dwordx4 v[164:165], off
	s_waitcnt vmcnt(8)
	s_waitcnt lgkmcnt(0)
	s_setprio 1
	s_barrier
	v_mfma_f32_16x16x32_bf16 v[60:63], v[144:147], v[188:191], v[60:63]
	v_mfma_f32_16x16x32_bf16 v[56:59], v[160:163], v[188:191], v[56:59]
	v_mfma_f32_16x16x32_bf16 v[44:47], v[144:147], v[196:199], v[44:47]
	v_mfma_f32_16x16x32_bf16 v[40:43], v[160:163], v[196:199], v[40:43]
	v_mfma_f32_16x16x32_bf16 v[28:31], v[144:147], v[204:207], v[28:31]
	v_mfma_f32_16x16x32_bf16 v[24:27], v[160:163], v[204:207], v[24:27]
	v_mfma_f32_16x16x32_bf16 v[12:15], v[144:147], v[212:215], v[12:15]
	v_mfma_f32_16x16x32_bf16 v[8:11], v[160:163], v[212:215], v[8:11]
	v_mfma_f32_16x16x32_bf16 v[60:63], v[148:151], v[192:195], v[60:63]
	v_mfma_f32_16x16x32_bf16 v[56:59], v[168:171], v[192:195], v[56:59]
	v_mfma_f32_16x16x32_bf16 v[44:47], v[148:151], v[200:203], v[44:47]
	v_mfma_f32_16x16x32_bf16 v[40:43], v[168:171], v[200:203], v[40:43]
	v_mfma_f32_16x16x32_bf16 v[28:31], v[148:151], v[208:211], v[28:31]
	v_mfma_f32_16x16x32_bf16 v[24:27], v[168:171], v[208:211], v[24:27]
	v_mfma_f32_16x16x32_bf16 v[12:15], v[148:151], v[216:219], v[12:15]
	v_mfma_f32_16x16x32_bf16 v[8:11], v[168:171], v[216:219], v[8:11]
	s_setprio 0
	s_setprio 1
	v_mfma_f32_16x16x32_bf16 v[52:55], v[172:175], v[188:191], v[52:55]
	v_mfma_f32_16x16x32_bf16 v[48:51], v[180:183], v[188:191], v[48:51]
	v_mfma_f32_16x16x32_bf16 v[36:39], v[172:175], v[196:199], v[36:39]
	v_mfma_f32_16x16x32_bf16 v[32:35], v[180:183], v[196:199], v[32:35]
	v_mfma_f32_16x16x32_bf16 v[20:23], v[172:175], v[204:207], v[20:23]
	v_mfma_f32_16x16x32_bf16 v[16:19], v[180:183], v[204:207], v[16:19]
	v_mfma_f32_16x16x32_bf16 v[4:7], v[172:175], v[212:215], v[4:7]
	v_mfma_f32_16x16x32_bf16 v[0:3], v[180:183], v[212:215], v[0:3]
	v_mfma_f32_16x16x32_bf16 v[52:55], v[176:179], v[192:195], v[52:55]
	v_mfma_f32_16x16x32_bf16 v[48:51], v[184:187], v[192:195], v[48:51]
	v_mfma_f32_16x16x32_bf16 v[36:39], v[176:179], v[200:203], v[36:39]
	v_mfma_f32_16x16x32_bf16 v[32:35], v[184:187], v[200:203], v[32:35]
	v_mfma_f32_16x16x32_bf16 v[20:23], v[176:179], v[208:211], v[20:23]
	v_mfma_f32_16x16x32_bf16 v[16:19], v[184:187], v[208:211], v[16:19]
	v_mfma_f32_16x16x32_bf16 v[4:7], v[176:179], v[216:219], v[4:7]
	v_mfma_f32_16x16x32_bf16 v[0:3], v[184:187], v[216:219], v[0:3]
	s_barrier
	s_setprio 0
	s_add_i32 s56, s56, 2
	s_add_u32 s54, s54, 0x100
	s_addc_u32 s55, s55, 0
	s_add_u32 s24, s24, 0x100
	s_addc_u32 s25, s25, 0
	s_cmp_gt_u32 s56, 29
	s_cbranch_scc0 .LBB0_1293
	s_and_b64 vcc, exec, s[14:15]
	s_cbranch_vccz .LBB0_1296
	s_barrier

; #define PG8_STAGE(bufoff, gbase, voff) do { _Pragma("unroll") for (int _i = 0; _i < 2; ++_i) \
;         __builtin_amdgcn_global_load_lds((const unsigned*)((const char*)(gbase) + (voff)[_i]), (LAS unsigned*)(lds + (bufoff) + ldsw + _i * 8192), 16, 0, 0); } while (0)
; #define PG8_LDA(dst, b, h) do { _Pragma("unroll") for (int m = 0; m < 4; ++m) _Pragma("unroll") for (int k = 0; k < 2; ++k) dst[m][k] = *(const LAS bf16x8*)(lds + PG8_SA(b, h) + aoff + m * 2048 + k * 1024); } while (0)
; #define PG8_LDB(dst, b, h) do { _Pragma("unroll") for (int n = 0; n < 2; ++n) _Pragma("unroll") for (int k = 0; k < 2; ++k) dst[n][k] = *(const LAS bf16x8*)(lds + PG8_SB(b, h) + boff + n * 2048 + k * 1024); } while (0)
; #define PG8_MMA(ai, bj, At, Bt) do { __builtin_amdgcn_s_setprio(1); _Pragma("unroll") for (int m = 0; m < 4; ++m) _Pragma("unroll") for (int n = 0; n < 2; ++n) _Pragma("unroll") for (int k = 0; k < 2; ++k) \
;         acc[ai][bj][m][n] = __builtin_amdgcn_mfma_f32_16x16x32_bf16(Bt[n][k], At[m][k], acc[ai][bj][m][n], 0, 0, 0); __builtin_amdgcn_s_setprio(0); } while (0)
; #define PG8_WAIT_V(n) asm volatile("s_waitcnt vmcnt(" #n ")" ::: "memory")
; #define PG8_WAIT_L(n) asm volatile("s_waitcnt lgkmcnt(" #n ")" ::: "memory")
; #define PG8_BAR __builtin_amdgcn_s_barrier()
; #define PG8_SCHED __builtin_amdgcn_sched_barrier(0)
; template <class Epi, bool ALIGN_EPI>
; __device__ __forceinline__ void gemm_phase(LAS unsigned char* lds, const Gemm g, const StaticOrder& S, const Epi& E) {
;     ...
;             PG8_LDB(B0, 0, 0); PG8_LDB(B1, 0, 1); PG8_SCHED; PG8_LDA(At, 0, 0); PG8_STAGE(PG8_SA(1, 1), a1 + hstepA, voffA);
;             PG8_WAIT_V(8); PG8_WAIT_L(0); PG8_BAR; PG8_MMA(0, 0, At, B0); PG8_MMA(0, 1, At, B1); PG8_BAR; PG8_SCHED;
;             PG8_LDA(At, 0, 1); PG8_STAGE(PG8_SB(0, 0), b2, voffB); PG8_STAGE(PG8_SB(0, 1), b2 + hstepB, voffB); PG8_STAGE(PG8_SA(0, 0), a2, voffA);
;             PG8_WAIT_V(8); PG8_WAIT_L(0); PG8_BAR; PG8_MMA(1, 0, At, B0); PG8_MMA(1, 1, At, B1); PG8_BAR; PG8_SCHED;
.LBB0_1379:
	ds_read_b128 v[72:75], v163
	ds_read_b128 v[84:87], v163 offset:1024
	ds_read_b128 v[88:91], v163 offset:2048
	ds_read_b128 v[96:99], v163 offset:3072
	ds_read_b128 v[156:159], v164
	ds_read_b128 v[168:171], v164 offset:1024
	ds_read_b128 v[172:175], v164 offset:2048
	ds_read_b128 v[176:179], v164 offset:3072
	s_add_u32 s26, s24, 0x100
	s_addc_u32 s27, s25, 0
	s_cmpk_eq_i32 s57, 0x54
	s_cselect_b32 s31, s5, s27
	s_cselect_b32 s30, s4, s26
	s_cselect_b32 s29, s23, s56
	s_cselect_b32 s28, s22, s55
	v_lshl_add_u64 v[212:213], s[24:25], 0, v[150:151]
	s_add_i32 m0, s37, 0xc000
	ds_read_b128 v[180:183], v165
	ds_read_b128 v[184:187], v165 offset:1024
	ds_read_b128 v[188:191], v165 offset:2048
	ds_read_b128 v[192:195], v165 offset:3072
	ds_read_b128 v[196:199], v165 offset:4096
	ds_read_b128 v[200:203], v165 offset:5120
	ds_read_b128 v[204:207], v165 offset:6144
	ds_read_b128 v[208:211], v165 offset:7168
	global_load_lds_dwordx4 v[212:213], off
	v_lshl_add_u64 v[212:213], s[24:25], 0, v[148:149]
	s_add_i32 m0, s37, 0xe000
	s_nop 0
	global_load_lds_dwordx4 v[212:213], off
	s_waitcnt vmcnt(8)
	s_waitcnt lgkmcnt(0)
	s_setprio 1
	s_barrier
	v_mfma_f32_16x16x32_bf16 v[140:143], v[72:75], v[180:183], v[140:143]
	v_mfma_f32_16x16x32_bf16 v[136:139], v[88:91], v[180:183], v[136:139]
	v_mfma_f32_16x16x32_bf16 v[124:127], v[72:75], v[188:191], v[124:127]
	v_mfma_f32_16x16x32_bf16 v[120:123], v[88:91], v[188:191], v[120:123]
	v_mfma_f32_16x16x32_bf16 v[108:111], v[72:75], v[196:199], v[108:111]
	v_mfma_f32_16x16x32_bf16 v[104:107], v[88:91], v[196:199], v[104:107]
	v_mfma_f32_16x16x32_bf16 v[80:83], v[72:75], v[204:207], v[80:83]
	v_mfma_f32_16x16x32_bf16 v[76:79], v[88:91], v[204:207], v[76:79]
	v_mfma_f32_16x16x32_bf16 v[140:143], v[84:87], v[184:187], v[140:143]
	v_mfma_f32_16x16x32_bf16 v[136:139], v[96:99], v[184:187], v[136:139]
	v_mfma_f32_16x16x32_bf16 v[124:127], v[84:87], v[192:195], v[124:127]
	v_mfma_f32_16x16x32_bf16 v[120:123], v[96:99], v[192:195], v[120:123]
	v_mfma_f32_16x16x32_bf16 v[108:111], v[84:87], v[200:203], v[108:111]
	v_mfma_f32_16x16x32_bf16 v[104:107], v[96:99], v[200:203], v[104:107]
	v_mfma_f32_16x16x32_bf16 v[80:83], v[84:87], v[208:211], v[80:83]
	v_mfma_f32_16x16x32_bf16 v[76:79], v[96:99], v[208:211], v[76:79]
	s_setprio 0
	s_setprio 1
	v_mfma_f32_16x16x32_bf16 v[132:135], v[156:159], v[180:183], v[132:135]
	v_mfma_f32_16x16x32_bf16 v[128:131], v[172:175], v[180:183], v[128:131]
	v_mfma_f32_16x16x32_bf16 v[116:119], v[156:159], v[188:191], v[116:119]
	v_mfma_f32_16x16x32_bf16 v[112:115], v[172:175], v[188:191], v[112:115]
	v_mfma_f32_16x16x32_bf16 v[100:103], v[156:159], v[196:199], v[100:103]
	v_mfma_f32_16x16x32_bf16 v[92:95], v[172:175], v[196:199], v[92:95]
	v_mfma_f32_16x16x32_bf16 v[68:71], v[156:159], v[204:207], v[68:71]
	v_mfma_f32_16x16x32_bf16 v[64:67], v[172:175], v[204:207], v[64:67]
	v_mfma_f32_16x16x32_bf16 v[132:135], v[168:171], v[184:187], v[132:135]
	v_mfma_f32_16x16x32_bf16 v[128:131], v[176:179], v[184:187], v[128:131]
	v_mfma_f32_16x16x32_bf16 v[116:119], v[168:171], v[192:195], v[116:119]
	v_mfma_f32_16x16x32_bf16 v[112:115], v[176:179], v[192:195], v[112:115]
	v_mfma_f32_16x16x32_bf16 v[100:103], v[168:171], v[200:203], v[100:103]
	v_mfma_f32_16x16x32_bf16 v[92:95], v[176:179], v[200:203], v[92:95]
	v_mfma_f32_16x16x32_bf16 v[68:71], v[168:171], v[208:211], v[68:71]
	v_mfma_f32_16x16x32_bf16 v[64:67], v[176:179], v[208:211], v[64:67]
	s_barrier
	s_setprio 0
	s_add_i32 s24, s48, s36
	v_lshl_add_u64 v[212:213], s[28:29], 0, v[144:145]
	s_mov_b32 m0, s24
	ds_read_b128 v[180:183], v165 offset:16384
	ds_read_b128 v[184:187], v165 offset:17408
	ds_read_b128 v[188:191], v165 offset:18432
	ds_read_b128 v[192:195], v165 offset:19456
	ds_read_b128 v[196:199], v165 offset:20480
	ds_read_b128 v[200:203], v165 offset:21504
	ds_read_b128 v[204:207], v165 offset:22528
	ds_read_b128 v[208:211], v165 offset:23552
	global_load_lds_dwordx4 v[212:213], off
	s_add_i32 m0, s24, 0x2000
	s_add_u32 s24, s28, 0x160000
	v_lshl_add_u64 v[214:215], s[28:29], 0, v[146:147]
	s_addc_u32 s25, s29, 0
	s_add_i32 s58, s49, s36
	global_load_lds_dwordx4 v[214:215], off
	v_lshl_add_u64 v[216:217], s[24:25], 0, v[144:145]
	s_mov_b32 m0, s58
	v_lshl_add_u64 v[218:219], s[30:31], 0, v[146:147]
	global_load_lds_dwordx4 v[216:217], off
	v_lshl_add_u64 v[216:217], s[24:25], 0, v[146:147]
	s_add_i32 m0, s58, 0x2000
	s_nop 0
	global_load_lds_dwordx4 v[216:217], off
	v_lshl_add_u64 v[216:217], s[30:31], 0, v[144:145]
	s_mov_b32 m0, s37
	s_nop 0
	global_load_lds_dwordx4 v[216:217], off
	s_mov_b32 m0, s38
	s_nop 0
	global_load_lds_dwordx4 v[218:219], off
	s_waitcnt vmcnt(8)
	s_waitcnt lgkmcnt(0)
	s_setprio 1
	s_barrier
; #define PG8_STAGE(bufoff, gbase, voff) do { _Pragma("unroll") for (int _i = 0; _i < 2; ++_i) \
;         __builtin_amdgcn_global_load_lds((const unsigned*)((const char*)(gbase) + (voff)[_i]), (LAS unsigned*)(lds + (bufoff) + ldsw + _i * 8192), 16, 0, 0); } while (0)
; #define PG8_LDA(dst, b, h) do { _Pragma("unroll") for (int m = 0; m < 4; ++m) _Pragma("unroll") for (int k = 0; k < 2; ++k) dst[m][k] = *(const LAS bf16x8*)(lds + PG8_SA(b, h) + aoff + m * 2048 + k * 1024); } while (0)
; #define PG8_LDB(dst, b, h) do { _Pragma("unroll") for (int n = 0; n < 2; ++n) _Pragma("unroll") for (int k = 0; k < 2; ++k) dst[n][k] = *(const LAS bf16x8*)(lds + PG8_SB(b, h) + boff + n * 2048 + k * 1024); } while (0)
; #define PG8_MMA(ai, bj, At, Bt) do { __builtin_amdgcn_s_setprio(1); _Pragma("unroll") for (int m = 0; m < 4; ++m) _Pragma("unroll") for (int n = 0; n < 2; ++n) _Pragma("unroll") for (int k = 0; k < 2; ++k) \
;         acc[ai][bj][m][n] = __builtin_amdgcn_mfma_f32_16x16x32_bf16(Bt[n][k], At[m][k], acc[ai][bj][m][n], 0, 0, 0); __builtin_amdgcn_s_setprio(0); } while (0)
; #define PG8_WAIT_V(n) asm volatile("s_waitcnt vmcnt(" #n ")" ::: "memory")
; #define PG8_WAIT_L(n) asm volatile("s_waitcnt lgkmcnt(" #n ")" ::: "memory")
; #define PG8_BAR __builtin_amdgcn_s_barrier()
; #define PG8_SCHED __builtin_amdgcn_sched_barrier(0)
; template <class Epi, bool ALIGN_EPI>
; __device__ __forceinline__ void gemm_phase(LAS unsigned char* lds, const Gemm g, const StaticOrder& S, const Epi& E) {
;     ...
;             PG8_WAIT_V(8); PG8_WAIT_L(0); PG8_BAR; PG8_MMA(1, 0, At, B0); PG8_MMA(1, 1, At, B1); PG8_BAR; PG8_SCHED;
;             PG8_LDB(B0, 1, 0); PG8_LDB(B1, 1, 1); PG8_SCHED; PG8_LDA(At, 1, 0); PG8_STAGE(PG8_SA(0, 1), a2 + hstepA, voffA);
;             PG8_WAIT_V(8); PG8_WAIT_L(0); PG8_BAR; PG8_MMA(0, 0, At, B0); PG8_MMA(0, 1, At, B1); PG8_BAR; PG8_SCHED;
	v_mfma_f32_16x16x32_bf16 v[60:63], v[72:75], v[180:183], v[60:63]
	v_mfma_f32_16x16x32_bf16 v[56:59], v[88:91], v[180:183], v[56:59]
	v_mfma_f32_16x16x32_bf16 v[44:47], v[72:75], v[188:191], v[44:47]
	v_mfma_f32_16x16x32_bf16 v[40:43], v[88:91], v[188:191], v[40:43]
	v_mfma_f32_16x16x32_bf16 v[28:31], v[72:75], v[196:199], v[28:31]
	v_mfma_f32_16x16x32_bf16 v[24:27], v[88:91], v[196:199], v[24:27]
	v_mfma_f32_16x16x32_bf16 v[12:15], v[72:75], v[204:207], v[12:15]
	v_mfma_f32_16x16x32_bf16 v[8:11], v[88:91], v[204:207], v[8:11]
	v_mfma_f32_16x16x32_bf16 v[60:63], v[84:87], v[184:187], v[60:63]
	v_mfma_f32_16x16x32_bf16 v[56:59], v[96:99], v[184:187], v[56:59]
	v_mfma_f32_16x16x32_bf16 v[44:47], v[84:87], v[192:195], v[44:47]
	v_mfma_f32_16x16x32_bf16 v[40:43], v[96:99], v[192:195], v[40:43]
	v_mfma_f32_16x16x32_bf16 v[28:31], v[84:87], v[200:203], v[28:31]
	v_mfma_f32_16x16x32_bf16 v[24:27], v[96:99], v[200:203], v[24:27]
	v_mfma_f32_16x16x32_bf16 v[12:15], v[84:87], v[208:211], v[12:15]
	v_mfma_f32_16x16x32_bf16 v[8:11], v[96:99], v[208:211], v[8:11]
	s_setprio 0
	s_setprio 1
	v_mfma_f32_16x16x32_bf16 v[52:55], v[156:159], v[180:183], v[52:55]
	v_mfma_f32_16x16x32_bf16 v[48:51], v[172:175], v[180:183], v[48:51]
	v_mfma_f32_16x16x32_bf16 v[36:39], v[156:159], v[188:191], v[36:39]
	v_mfma_f32_16x16x32_bf16 v[32:35], v[172:175], v[188:191], v[32:35]
	v_mfma_f32_16x16x32_bf16 v[20:23], v[156:159], v[196:199], v[20:23]
	v_mfma_f32_16x16x32_bf16 v[16:19], v[172:175], v[196:199], v[16:19]
	v_mfma_f32_16x16x32_bf16 v[4:7], v[156:159], v[204:207], v[4:7]
	v_mfma_f32_16x16x32_bf16 v[0:3], v[172:175], v[204:207], v[0:3]
	v_mfma_f32_16x16x32_bf16 v[52:55], v[168:171], v[184:187], v[52:55]
	v_mfma_f32_16x16x32_bf16 v[48:51], v[176:179], v[184:187], v[48:51]
	v_mfma_f32_16x16x32_bf16 v[36:39], v[168:171], v[192:195], v[36:39]
	v_mfma_f32_16x16x32_bf16 v[32:35], v[176:179], v[192:195], v[32:35]
	v_mfma_f32_16x16x32_bf16 v[20:23], v[168:171], v[200:203], v[20:23]
	v_mfma_f32_16x16x32_bf16 v[16:19], v[176:179], v[200:203], v[16:19]
	v_mfma_f32_16x16x32_bf16 v[4:7], v[168:171], v[208:211], v[4:7]
	v_mfma_f32_16x16x32_bf16 v[0:3], v[176:179], v[208:211], v[0:3]
	s_barrier
	s_setprio 0
	s_add_i32 s58, 0, 0x18000
	s_add_i32 s59, 0, 0x1c000
	v_add_u32_e32 v96, s58, v161
	v_add_u32_e32 v176, s59, v161
	ds_read_b128 v[72:75], v96
	ds_read_b128 v[84:87], v96 offset:1024
	ds_read_b128 v[88:91], v96 offset:2048
	ds_read_b128 v[96:99], v96 offset:3072
	ds_read_b128 v[156:159], v176
	ds_read_b128 v[168:171], v176 offset:1024
	ds_read_b128 v[172:175], v176 offset:2048
	ds_read_b128 v[176:179], v176 offset:3072
	s_add_u32 s24, s30, 0x160000
	s_addc_u32 s25, s31, 0
	s_mov_b32 m0, s39
	v_lshl_add_u64 v[220:221], s[24:25], 0, v[144:145]
	ds_read_b128 v[180:183], v165 offset:32768
	ds_read_b128 v[184:187], v165 offset:33792
	ds_read_b128 v[188:191], v165 offset:34816
	ds_read_b128 v[192:195], v165 offset:35840
	ds_read_b128 v[196:199], v165 offset:36864
	ds_read_b128 v[200:203], v165 offset:37888
	ds_read_b128 v[204:207], v165 offset:38912
	ds_read_b128 v[208:211], v165 offset:39936
	global_load_lds_dwordx4 v[220:221], off
	v_lshl_add_u64 v[220:221], s[24:25], 0, v[146:147]
	s_mov_b32 m0, s40
	s_nop 0
	global_load_lds_dwordx4 v[220:221], off
	s_waitcnt vmcnt(8)
	s_waitcnt lgkmcnt(0)
	s_setprio 1
	s_barrier
	v_mfma_f32_16x16x32_bf16 v[140:143], v[72:75], v[180:183], v[140:143]
	v_mfma_f32_16x16x32_bf16 v[136:139], v[88:91], v[180:183], v[136:139]
	v_mfma_f32_16x16x32_bf16 v[124:127], v[72:75], v[188:191], v[124:127]
	v_mfma_f32_16x16x32_bf16 v[120:123], v[88:91], v[188:191], v[120:123]
	v_mfma_f32_16x16x32_bf16 v[108:111], v[72:75], v[196:199], v[108:111]
	v_mfma_f32_16x16x32_bf16 v[104:107], v[88:91], v[196:199], v[104:107]
	v_mfma_f32_16x16x32_bf16 v[80:83], v[72:75], v[204:207], v[80:83]
	v_mfma_f32_16x16x32_bf16 v[76:79], v[88:91], v[204:207], v[76:79]
	v_mfma_f32_16x16x32_bf16 v[140:143], v[84:87], v[184:187], v[140:143]
	v_mfma_f32_16x16x32_bf16 v[136:139], v[96:99], v[184:187], v[136:139]
	v_mfma_f32_16x16x32_bf16 v[124:127], v[84:87], v[192:195], v[124:127]
	v_mfma_f32_16x16x32_bf16 v[120:123], v[96:99], v[192:195], v[120:123]
	v_mfma_f32_16x16x32_bf16 v[108:111], v[84:87], v[200:203], v[108:111]
	v_mfma_f32_16x16x32_bf16 v[104:107], v[96:99], v[200:203], v[104:107]
	v_mfma_f32_16x16x32_bf16 v[80:83], v[84:87], v[208:211], v[80:83]
	v_mfma_f32_16x16x32_bf16 v[76:79], v[96:99], v[208:211], v[76:79]
	s_setprio 0
	s_setprio 1
	v_mfma_f32_16x16x32_bf16 v[132:135], v[156:159], v[180:183], v[132:135]
	v_mfma_f32_16x16x32_bf16 v[128:131], v[172:175], v[180:183], v[128:131]
	v_mfma_f32_16x16x32_bf16 v[116:119], v[156:159], v[188:191], v[116:119]
	v_mfma_f32_16x16x32_bf16 v[112:115], v[172:175], v[188:191], v[112:115]
	v_mfma_f32_16x16x32_bf16 v[100:103], v[156:159], v[196:199], v[100:103]
	v_mfma_f32_16x16x32_bf16 v[92:95], v[172:175], v[196:199], v[92:95]
	v_mfma_f32_16x16x32_bf16 v[68:71], v[156:159], v[204:207], v[68:71]
	v_mfma_f32_16x16x32_bf16 v[64:67], v[172:175], v[204:207], v[64:67]
	v_mfma_f32_16x16x32_bf16 v[132:135], v[168:171], v[184:187], v[132:135]
	v_mfma_f32_16x16x32_bf16 v[128:131], v[176:179], v[184:187], v[128:131]
	v_mfma_f32_16x16x32_bf16 v[116:119], v[168:171], v[192:195], v[116:119]
	v_mfma_f32_16x16x32_bf16 v[112:115], v[176:179], v[192:195], v[112:115]
	v_mfma_f32_16x16x32_bf16 v[100:103], v[168:171], v[200:203], v[100:103]
	v_mfma_f32_16x16x32_bf16 v[92:95], v[176:179], v[200:203], v[92:95]
	v_mfma_f32_16x16x32_bf16 v[68:71], v[168:171], v[208:211], v[68:71]
	v_mfma_f32_16x16x32_bf16 v[64:67], v[176:179], v[208:211], v[64:67]
	s_barrier
; #define PG8_STAGE(bufoff, gbase, voff) do { _Pragma("unroll") for (int _i = 0; _i < 2; ++_i) \
;         __builtin_amdgcn_global_load_lds((const unsigned*)((const char*)(gbase) + (voff)[_i]), (LAS unsigned*)(lds + (bufoff) + ldsw + _i * 8192), 16, 0, 0); } while (0)
; #define PG8_LDA(dst, b, h) do { _Pragma("unroll") for (int m = 0; m < 4; ++m) _Pragma("unroll") for (int k = 0; k < 2; ++k) dst[m][k] = *(const LAS bf16x8*)(lds + PG8_SA(b, h) + aoff + m * 2048 + k * 1024); } while (0)
; #define PG8_MMA(ai, bj, At, Bt) do { __builtin_amdgcn_s_setprio(1); _Pragma("unroll") for (int m = 0; m < 4; ++m) _Pragma("unroll") for (int n = 0; n < 2; ++n) _Pragma("unroll") for (int k = 0; k < 2; ++k) \
;         acc[ai][bj][m][n] = __builtin_amdgcn_mfma_f32_16x16x32_bf16(Bt[n][k], At[m][k], acc[ai][bj][m][n], 0, 0, 0); __builtin_amdgcn_s_setprio(0); } while (0)
; #define PG8_WAIT_V(n) asm volatile("s_waitcnt vmcnt(" #n ")" ::: "memory")
; #define PG8_WAIT_L(n) asm volatile("s_waitcnt lgkmcnt(" #n ")" ::: "memory")
; #define PG8_BAR __builtin_amdgcn_s_barrier()
; #define PG8_SCHED __builtin_amdgcn_sched_barrier(0)
; template <class Epi, bool ALIGN_EPI>
; __device__ __forceinline__ void gemm_phase(LAS unsigned char* lds, const Gemm g, const StaticOrder& S, const Epi& E) {
;     ...
;             PG8_LDA(At, 1, 1); PG8_STAGE(PG8_SB(1, 0), b3, voffB); PG8_STAGE(PG8_SB(1, 1), b3 + hstepB, voffB); PG8_STAGE(PG8_SA(1, 0), a3, voffA);
;             PG8_WAIT_V(8); PG8_WAIT_L(0); PG8_BAR; PG8_MMA(1, 0, At, B0); PG8_MMA(1, 1, At, B1); PG8_BAR; PG8_SCHED;
;         }
	s_setprio 0
	s_add_i32 s24, s58, s36
	v_lshl_add_u64 v[212:213], v[212:213], 0, s[18:19]
	s_mov_b32 m0, s24
	ds_read_b128 v[180:183], v165 offset:49152
	ds_read_b128 v[184:187], v165 offset:50176
	ds_read_b128 v[188:191], v165 offset:51200
	ds_read_b128 v[192:195], v165 offset:52224
	ds_read_b128 v[196:199], v165 offset:53248
	ds_read_b128 v[200:203], v165 offset:54272
	ds_read_b128 v[204:207], v165 offset:55296
	ds_read_b128 v[208:211], v165 offset:56320
	global_load_lds_dwordx4 v[212:213], off
	s_add_i32 m0, s24, 0x2000
	s_add_u32 s24, s28, 0x160080
	v_lshl_add_u64 v[212:213], v[214:215], 0, s[18:19]
	s_addc_u32 s25, s29, 0
	s_add_i32 s28, s59, s36
	global_load_lds_dwordx4 v[212:213], off
	v_lshl_add_u64 v[212:213], s[24:25], 0, v[144:145]
	s_mov_b32 m0, s28
	s_nop 0
	global_load_lds_dwordx4 v[212:213], off
	v_lshl_add_u64 v[212:213], s[24:25], 0, v[146:147]
	s_add_i32 m0, s28, 0x2000
	s_nop 0
	global_load_lds_dwordx4 v[212:213], off
	v_lshl_add_u64 v[212:213], v[216:217], 0, s[18:19]
	s_mov_b32 m0, s42
	s_nop 0
	global_load_lds_dwordx4 v[212:213], off
	v_lshl_add_u64 v[212:213], v[218:219], 0, s[18:19]
	s_mov_b32 m0, s43
	s_nop 0
	global_load_lds_dwordx4 v[212:213], off
	s_waitcnt vmcnt(8)
	s_waitcnt lgkmcnt(0)
	s_setprio 1
	s_barrier
	v_mfma_f32_16x16x32_bf16 v[60:63], v[72:75], v[180:183], v[60:63]
	v_mfma_f32_16x16x32_bf16 v[56:59], v[88:91], v[180:183], v[56:59]
	v_mfma_f32_16x16x32_bf16 v[44:47], v[72:75], v[188:191], v[44:47]
	v_mfma_f32_16x16x32_bf16 v[40:43], v[88:91], v[188:191], v[40:43]
	v_mfma_f32_16x16x32_bf16 v[28:31], v[72:75], v[196:199], v[28:31]
	v_mfma_f32_16x16x32_bf16 v[24:27], v[88:91], v[196:199], v[24:27]
	v_mfma_f32_16x16x32_bf16 v[12:15], v[72:75], v[204:207], v[12:15]
	v_mfma_f32_16x16x32_bf16 v[8:11], v[88:91], v[204:207], v[8:11]
	v_mfma_f32_16x16x32_bf16 v[60:63], v[84:87], v[184:187], v[60:63]
	v_mfma_f32_16x16x32_bf16 v[56:59], v[96:99], v[184:187], v[56:59]
	v_mfma_f32_16x16x32_bf16 v[44:47], v[84:87], v[192:195], v[44:47]
	v_mfma_f32_16x16x32_bf16 v[40:43], v[96:99], v[192:195], v[40:43]
	v_mfma_f32_16x16x32_bf16 v[28:31], v[84:87], v[200:203], v[28:31]
	v_mfma_f32_16x16x32_bf16 v[24:27], v[96:99], v[200:203], v[24:27]
	v_mfma_f32_16x16x32_bf16 v[12:15], v[84:87], v[208:211], v[12:15]
	v_mfma_f32_16x16x32_bf16 v[8:11], v[96:99], v[208:211], v[8:11]
	s_setprio 0
	s_setprio 1
	v_mfma_f32_16x16x32_bf16 v[52:55], v[156:159], v[180:183], v[52:55]
	v_mfma_f32_16x16x32_bf16 v[48:51], v[172:175], v[180:183], v[48:51]
	v_mfma_f32_16x16x32_bf16 v[36:39], v[156:159], v[188:191], v[36:39]
	v_mfma_f32_16x16x32_bf16 v[32:35], v[172:175], v[188:191], v[32:35]
	v_mfma_f32_16x16x32_bf16 v[20:23], v[156:159], v[196:199], v[20:23]
	v_mfma_f32_16x16x32_bf16 v[16:19], v[172:175], v[196:199], v[16:19]
	v_mfma_f32_16x16x32_bf16 v[4:7], v[156:159], v[204:207], v[4:7]
	v_mfma_f32_16x16x32_bf16 v[0:3], v[172:175], v[204:207], v[0:3]
	v_mfma_f32_16x16x32_bf16 v[52:55], v[168:171], v[184:187], v[52:55]
	v_mfma_f32_16x16x32_bf16 v[48:51], v[176:179], v[184:187], v[48:51]
	v_mfma_f32_16x16x32_bf16 v[36:39], v[168:171], v[192:195], v[36:39]
	v_mfma_f32_16x16x32_bf16 v[32:35], v[176:179], v[192:195], v[32:35]
	v_mfma_f32_16x16x32_bf16 v[20:23], v[168:171], v[200:203], v[20:23]
	v_mfma_f32_16x16x32_bf16 v[16:19], v[176:179], v[200:203], v[16:19]
	v_mfma_f32_16x16x32_bf16 v[4:7], v[168:171], v[208:211], v[4:7]
	v_mfma_f32_16x16x32_bf16 v[0:3], v[176:179], v[208:211], v[0:3]
	s_barrier
	s_setprio 0
	s_add_i32 s57, s57, 2
	s_add_u32 s55, s55, 0x100
	s_addc_u32 s56, s56, 0
	s_cmpk_gt_u32 s57, 0x55
	s_mov_b64 s[24:25], s[26:27]
	s_cbranch_scc0 .LBB0_1379
	s_and_b64 vcc, exec, s[20:21]
	s_cbranch_vccz .LBB0_1382
	s_barrier
